# GEMM phases: every s_setprio flip and every duplicate post-barrier lgkmcnt wait removed (union of the removal edits)
# speedup vs baseline: 1.0036x; 1.0000x over previous
; #define PG8_STAGE(bufoff, gbase, voff) do { _Pragma("unroll") for (int _i = 0; _i < 2; ++_i) \
;         __builtin_amdgcn_global_load_lds((const unsigned*)((const char*)(gbase) + (voff)[_i]), (PG8_LAS unsigned*)(lds + (bufoff) + ldsw + _i * 8192), 16, 0, 0); } while (0)
; #define PG8_LDA(dst, b, h) do { _Pragma("unroll") for (int m = 0; m < 4; ++m) _Pragma("unroll") for (int k = 0; k < 2; ++k) dst[m][k] = *(const PG8_LAS bf16x8*)(lds + PG8_SA(b, h) + aoff + m * 2048 + k * 1024); } while (0)
; #define PG8_LDB(dst, b, h) do { _Pragma("unroll") for (int n = 0; n < 2; ++n) _Pragma("unroll") for (int k = 0; k < 2; ++k) dst[n][k] = *(const PG8_LAS bf16x8*)(lds + PG8_SB(b, h) + boff + n * 2048 + k * 1024); } while (0)
; #define PG8_MMA(ai, bj, At, Bt) do { __builtin_amdgcn_s_setprio(1); _Pragma("unroll") for (int m = 0; m < 4; ++m) _Pragma("unroll") for (int n = 0; n < 2; ++n) _Pragma("unroll") for (int k = 0; k < 2; ++k) \
;         acc[ai][bj][m][n] = __builtin_amdgcn_mfma_f32_16x16x32_bf16(Bt[n][k], At[m][k], acc[ai][bj][m][n], 0, 0, 0); __builtin_amdgcn_s_setprio(0); } while (0)
; #define PG8_WAIT_V(n) asm volatile("s_waitcnt vmcnt(" #n ")" ::: "memory")
; #define PG8_WAIT_L(n) asm volatile("s_waitcnt lgkmcnt(" #n ")" ::: "memory")
; #define PG8_BAR __builtin_amdgcn_s_barrier()
; #define PG8_SCHED __builtin_amdgcn_sched_barrier(0)
; template <class Epi, class Sched, bool ALIGN_EPI = false, bool SP2 = false>
; __device__ __forceinline__ void gemm_phase(PG8_LAS unsigned char* lds, const Gemm g, const Sched& S, const Epi& E) {
;     ...
;             PG8_LDB(B0, 0, 0); PG8_LDB(B1, 0, 1); PG8_SCHED; PG8_LDA(At, 0, 0); PG8_STAGE(PG8_SA(1, 1), a1 + hstepA, voffA);
;             PG8_WAIT_V(8); PG8_WAIT_L(0); PG8_BAR; PG8_MMA(0, 0, At, B0); PG8_MMA(0, 1, At, B1); PG8_BAR; PG8_SCHED;
;             PG8_LDA(At, 0, 1); PG8_STAGE(PG8_SB(0, 0), b2, voffB); PG8_STAGE(PG8_SB(0, 1), b2 + hstepB, voffB); PG8_STAGE(PG8_SA(0, 0), a2, voffA);
;             PG8_WAIT_V(8); PG8_WAIT_L(0); PG8_BAR; PG8_MMA(1, 0, At, B0); PG8_MMA(1, 1, At, B1); PG8_BAR; PG8_SCHED;
.LBB0_832:
	s_add_u32 s36, s24, s28
	s_addc_u32 s37, s25, s29
	s_add_u32 s34, s36, 0x100
	s_addc_u32 s35, s37, 0
	s_and_b64 s[30:31], s[26:27], exec
	s_cselect_b32 s31, s19, s35
	s_cselect_b32 s30, s18, s34
	s_add_u32 s28, s22, s28
	s_addc_u32 s29, s23, s29
	s_add_u32 s28, s28, 0x100
	s_addc_u32 s29, s29, 0
	s_and_b64 s[26:27], s[26:27], exec
	s_cselect_b32 s35, s5, s29
	s_cselect_b32 s34, s17, s28
	s_add_u32 s38, s36, 0x2a080
	ds_read_b128 v[162:165], v151
	ds_read_b128 v[166:169], v151 offset:1024
	ds_read_b128 v[170:173], v151 offset:2048
	ds_read_b128 v[174:177], v151 offset:3072
	ds_read_b128 v[178:181], v152
	ds_read_b128 v[182:185], v152 offset:1024
	ds_read_b128 v[186:189], v152 offset:2048
	ds_read_b128 v[190:193], v152 offset:3072
	s_addc_u32 s39, s37, 0
	s_add_i32 s73, s55, s45
	s_add_i32 m0, s46, 0xc000
	s_add_i32 s76, s46, 0xe000
	s_add_i32 s70, s73, 0x2000
	s_add_u32 s36, s34, 0x10000
	s_addc_u32 s37, s35, 0
	s_add_i32 s72, s56, s45
	s_add_i32 s71, s72, 0x2000
	s_add_i32 s69, 0, 0x18000
	s_add_i32 s68, 0, 0x1c000
	s_add_u32 s28, s30, 0x2a000
	s_addc_u32 s29, s31, 0
	s_add_i32 s67, s69, s45
	s_add_i32 s66, s67, 0x2000
	s_add_u32 s26, s34, 0x10080
	s_addc_u32 s27, s35, 0
	s_add_i32 s75, s68, s45
	s_add_i32 s74, s75, 0x2000
	v_lshl_add_u64 v[148:149], s[38:39], 0, v[130:131]
	ds_read_b128 v[194:197], v153
	ds_read_b128 v[198:201], v153 offset:1024
	ds_read_b128 v[202:205], v153 offset:2048
	ds_read_b128 v[206:209], v153 offset:3072
	ds_read_b128 v[210:213], v153 offset:4096
	ds_read_b128 v[214:217], v153 offset:5120
	ds_read_b128 v[218:221], v153 offset:6144
	ds_read_b128 v[222:225], v153 offset:7168
	global_load_lds_dwordx4 v[148:149], off
	v_lshl_add_u64 v[148:149], s[38:39], 0, v[134:135]
	s_mov_b32 m0, s76
	s_nop 0
	global_load_lds_dwordx4 v[148:149], off
	s_waitcnt vmcnt(8)
	s_waitcnt lgkmcnt(0)
	s_barrier
	v_mfma_f32_16x16x32_bf16 v[126:129], v[162:165], v[194:197], v[126:129]
	v_mfma_f32_16x16x32_bf16 v[122:125], v[170:173], v[194:197], v[122:125]
	v_mfma_f32_16x16x32_bf16 v[110:113], v[162:165], v[202:205], v[110:113]
	v_mfma_f32_16x16x32_bf16 v[106:109], v[170:173], v[202:205], v[106:109]
	v_mfma_f32_16x16x32_bf16 v[94:97], v[162:165], v[210:213], v[94:97]
	v_mfma_f32_16x16x32_bf16 v[90:93], v[170:173], v[210:213], v[90:93]
	v_mfma_f32_16x16x32_bf16 v[78:81], v[162:165], v[218:221], v[78:81]
	v_mfma_f32_16x16x32_bf16 v[74:77], v[170:173], v[218:221], v[74:77]
	v_mfma_f32_16x16x32_bf16 v[126:129], v[166:169], v[198:201], v[126:129]
	v_mfma_f32_16x16x32_bf16 v[122:125], v[174:177], v[198:201], v[122:125]
	v_mfma_f32_16x16x32_bf16 v[110:113], v[166:169], v[206:209], v[110:113]
	v_mfma_f32_16x16x32_bf16 v[106:109], v[174:177], v[206:209], v[106:109]
	v_mfma_f32_16x16x32_bf16 v[94:97], v[166:169], v[214:217], v[94:97]
	v_mfma_f32_16x16x32_bf16 v[90:93], v[174:177], v[214:217], v[90:93]
	v_mfma_f32_16x16x32_bf16 v[78:81], v[166:169], v[222:225], v[78:81]
	v_mfma_f32_16x16x32_bf16 v[74:77], v[174:177], v[222:225], v[74:77]
	v_mfma_f32_16x16x32_bf16 v[118:121], v[178:181], v[194:197], v[118:121]
	v_mfma_f32_16x16x32_bf16 v[114:117], v[186:189], v[194:197], v[114:117]
	v_mfma_f32_16x16x32_bf16 v[102:105], v[178:181], v[202:205], v[102:105]
	v_mfma_f32_16x16x32_bf16 v[98:101], v[186:189], v[202:205], v[98:101]
	v_mfma_f32_16x16x32_bf16 v[86:89], v[178:181], v[210:213], v[86:89]
	v_mfma_f32_16x16x32_bf16 v[82:85], v[186:189], v[210:213], v[82:85]
	v_mfma_f32_16x16x32_bf16 v[70:73], v[178:181], v[218:221], v[70:73]
	v_mfma_f32_16x16x32_bf16 v[66:69], v[186:189], v[218:221], v[66:69]
	v_mfma_f32_16x16x32_bf16 v[118:121], v[182:185], v[198:201], v[118:121]
	v_mfma_f32_16x16x32_bf16 v[114:117], v[190:193], v[198:201], v[114:117]
	v_mfma_f32_16x16x32_bf16 v[102:105], v[182:185], v[206:209], v[102:105]
	v_mfma_f32_16x16x32_bf16 v[98:101], v[190:193], v[206:209], v[98:101]
	v_mfma_f32_16x16x32_bf16 v[86:89], v[182:185], v[214:217], v[86:89]
	v_mfma_f32_16x16x32_bf16 v[82:85], v[190:193], v[214:217], v[82:85]
	v_mfma_f32_16x16x32_bf16 v[70:73], v[182:185], v[222:225], v[70:73]
	v_mfma_f32_16x16x32_bf16 v[66:69], v[190:193], v[222:225], v[66:69]
	s_barrier
	s_mov_b32 m0, s73
	v_lshl_add_u64 v[148:149], s[34:35], 0, v[132:133]
	ds_read_b128 v[194:197], v153 offset:16384
	ds_read_b128 v[198:201], v153 offset:17408
	ds_read_b128 v[202:205], v153 offset:18432
	ds_read_b128 v[206:209], v153 offset:19456
	ds_read_b128 v[210:213], v153 offset:20480
	ds_read_b128 v[214:217], v153 offset:21504
	ds_read_b128 v[218:221], v153 offset:22528
	ds_read_b128 v[222:225], v153 offset:23552
	global_load_lds_dwordx4 v[148:149], off
	v_lshl_add_u64 v[226:227], s[34:35], 0, v[136:137]
	s_mov_b32 m0, s70
	v_lshl_add_u64 v[228:229], s[36:37], 0, v[132:133]
	global_load_lds_dwordx4 v[226:227], off
	s_mov_b32 m0, s72
	v_lshl_add_u64 v[230:231], s[30:31], 0, v[134:135]
	global_load_lds_dwordx4 v[228:229], off
	v_lshl_add_u64 v[228:229], s[36:37], 0, v[136:137]
	s_mov_b32 m0, s71
	s_nop 0
	global_load_lds_dwordx4 v[228:229], off
	v_lshl_add_u64 v[228:229], s[30:31], 0, v[130:131]
	s_mov_b32 m0, s46
	s_nop 0
	global_load_lds_dwordx4 v[228:229], off
	s_mov_b32 m0, s47
	s_nop 0
	global_load_lds_dwordx4 v[230:231], off
	s_waitcnt vmcnt(8)
	s_waitcnt lgkmcnt(0)
	s_barrier
; #define PG8_STAGE(bufoff, gbase, voff) do { _Pragma("unroll") for (int _i = 0; _i < 2; ++_i) \
;         __builtin_amdgcn_global_load_lds((const unsigned*)((const char*)(gbase) + (voff)[_i]), (PG8_LAS unsigned*)(lds + (bufoff) + ldsw + _i * 8192), 16, 0, 0); } while (0)
; #define PG8_LDA(dst, b, h) do { _Pragma("unroll") for (int m = 0; m < 4; ++m) _Pragma("unroll") for (int k = 0; k < 2; ++k) dst[m][k] = *(const PG8_LAS bf16x8*)(lds + PG8_SA(b, h) + aoff + m * 2048 + k * 1024); } while (0)
; #define PG8_LDB(dst, b, h) do { _Pragma("unroll") for (int n = 0; n < 2; ++n) _Pragma("unroll") for (int k = 0; k < 2; ++k) dst[n][k] = *(const PG8_LAS bf16x8*)(lds + PG8_SB(b, h) + boff + n * 2048 + k * 1024); } while (0)
; #define PG8_MMA(ai, bj, At, Bt) do { __builtin_amdgcn_s_setprio(1); _Pragma("unroll") for (int m = 0; m < 4; ++m) _Pragma("unroll") for (int n = 0; n < 2; ++n) _Pragma("unroll") for (int k = 0; k < 2; ++k) \
;         acc[ai][bj][m][n] = __builtin_amdgcn_mfma_f32_16x16x32_bf16(Bt[n][k], At[m][k], acc[ai][bj][m][n], 0, 0, 0); __builtin_amdgcn_s_setprio(0); } while (0)
; #define PG8_WAIT_V(n) asm volatile("s_waitcnt vmcnt(" #n ")" ::: "memory")
; #define PG8_WAIT_L(n) asm volatile("s_waitcnt lgkmcnt(" #n ")" ::: "memory")
; #define PG8_BAR __builtin_amdgcn_s_barrier()
; #define PG8_SCHED __builtin_amdgcn_sched_barrier(0)
; template <class Epi, class Sched, bool ALIGN_EPI = false, bool SP2 = false>
; __device__ __forceinline__ void gemm_phase(PG8_LAS unsigned char* lds, const Gemm g, const Sched& S, const Epi& E) {
;     ...
;             PG8_WAIT_V(8); PG8_WAIT_L(0); PG8_BAR; PG8_MMA(1, 0, At, B0); PG8_MMA(1, 1, At, B1); PG8_BAR; PG8_SCHED;
;             PG8_LDB(B0, 1, 0); PG8_LDB(B1, 1, 1); PG8_SCHED; PG8_LDA(At, 1, 0); PG8_STAGE(PG8_SA(0, 1), a2 + hstepA, voffA);
;             PG8_WAIT_V(8); PG8_WAIT_L(0); PG8_BAR; PG8_MMA(0, 0, At, B0); PG8_MMA(0, 1, At, B1); PG8_BAR; PG8_SCHED;
;             PG8_LDA(At, 1, 1); PG8_STAGE(PG8_SB(1, 0), b3, voffB); PG8_STAGE(PG8_SB(1, 1), b3 + hstepB, voffB); PG8_STAGE(PG8_SA(1, 0), a3, voffA);
	v_mfma_f32_16x16x32_bf16 v[62:65], v[162:165], v[194:197], v[62:65]
	v_mfma_f32_16x16x32_bf16 v[58:61], v[170:173], v[194:197], v[58:61]
	v_mfma_f32_16x16x32_bf16 v[46:49], v[162:165], v[202:205], v[46:49]
	v_mfma_f32_16x16x32_bf16 v[42:45], v[170:173], v[202:205], v[42:45]
	v_mfma_f32_16x16x32_bf16 v[30:33], v[162:165], v[210:213], v[30:33]
	v_mfma_f32_16x16x32_bf16 v[26:29], v[170:173], v[210:213], v[26:29]
	v_mfma_f32_16x16x32_bf16 v[14:17], v[162:165], v[218:221], v[14:17]
	v_mfma_f32_16x16x32_bf16 v[10:13], v[170:173], v[218:221], v[10:13]
	v_mfma_f32_16x16x32_bf16 v[62:65], v[166:169], v[198:201], v[62:65]
	v_mfma_f32_16x16x32_bf16 v[58:61], v[174:177], v[198:201], v[58:61]
	v_mfma_f32_16x16x32_bf16 v[46:49], v[166:169], v[206:209], v[46:49]
	v_mfma_f32_16x16x32_bf16 v[42:45], v[174:177], v[206:209], v[42:45]
	v_mfma_f32_16x16x32_bf16 v[30:33], v[166:169], v[214:217], v[30:33]
	v_mfma_f32_16x16x32_bf16 v[26:29], v[174:177], v[214:217], v[26:29]
	v_mfma_f32_16x16x32_bf16 v[14:17], v[166:169], v[222:225], v[14:17]
	v_mfma_f32_16x16x32_bf16 v[10:13], v[174:177], v[222:225], v[10:13]
	v_mfma_f32_16x16x32_bf16 v[54:57], v[178:181], v[194:197], v[54:57]
	v_mfma_f32_16x16x32_bf16 v[50:53], v[186:189], v[194:197], v[50:53]
	v_mfma_f32_16x16x32_bf16 v[38:41], v[178:181], v[202:205], v[38:41]
	v_mfma_f32_16x16x32_bf16 v[34:37], v[186:189], v[202:205], v[34:37]
	v_mfma_f32_16x16x32_bf16 v[22:25], v[178:181], v[210:213], v[22:25]
	v_mfma_f32_16x16x32_bf16 v[18:21], v[186:189], v[210:213], v[18:21]
	v_mfma_f32_16x16x32_bf16 v[6:9], v[178:181], v[218:221], v[6:9]
	v_mfma_f32_16x16x32_bf16 v[2:5], v[186:189], v[218:221], v[2:5]
	v_mfma_f32_16x16x32_bf16 v[54:57], v[182:185], v[198:201], v[54:57]
	v_mfma_f32_16x16x32_bf16 v[50:53], v[190:193], v[198:201], v[50:53]
	v_mfma_f32_16x16x32_bf16 v[38:41], v[182:185], v[206:209], v[38:41]
	v_mfma_f32_16x16x32_bf16 v[34:37], v[190:193], v[206:209], v[34:37]
	v_mfma_f32_16x16x32_bf16 v[22:25], v[182:185], v[214:217], v[22:25]
	v_mfma_f32_16x16x32_bf16 v[18:21], v[190:193], v[214:217], v[18:21]
	v_mfma_f32_16x16x32_bf16 v[6:9], v[182:185], v[222:225], v[6:9]
	v_mfma_f32_16x16x32_bf16 v[2:5], v[190:193], v[222:225], v[2:5]
	s_barrier
	v_add_u32_e32 v138, s69, v150
	ds_read_b128 v[162:165], v138
	ds_read_b128 v[166:169], v138 offset:1024
	ds_read_b128 v[170:173], v138 offset:2048
	ds_read_b128 v[174:177], v138 offset:3072
	v_add_u32_e32 v138, s68, v150
	ds_read_b128 v[178:181], v138
	ds_read_b128 v[182:185], v138 offset:1024
	ds_read_b128 v[186:189], v138 offset:2048
	ds_read_b128 v[190:193], v138 offset:3072
	s_mov_b32 m0, s48
	v_lshl_add_u64 v[232:233], s[28:29], 0, v[130:131]
	ds_read_b128 v[194:197], v153 offset:32768
	ds_read_b128 v[198:201], v153 offset:33792
	ds_read_b128 v[202:205], v153 offset:34816
	ds_read_b128 v[206:209], v153 offset:35840
	ds_read_b128 v[210:213], v153 offset:36864
	ds_read_b128 v[214:217], v153 offset:37888
	ds_read_b128 v[218:221], v153 offset:38912
	ds_read_b128 v[222:225], v153 offset:39936
	global_load_lds_dwordx4 v[232:233], off
	v_lshl_add_u64 v[232:233], s[28:29], 0, v[134:135]
	s_mov_b32 m0, s49
	s_nop 0
	global_load_lds_dwordx4 v[232:233], off
	s_waitcnt vmcnt(8)
	s_waitcnt lgkmcnt(0)
	s_barrier
	v_mfma_f32_16x16x32_bf16 v[126:129], v[162:165], v[194:197], v[126:129]
	v_mfma_f32_16x16x32_bf16 v[122:125], v[170:173], v[194:197], v[122:125]
	v_mfma_f32_16x16x32_bf16 v[110:113], v[162:165], v[202:205], v[110:113]
	v_mfma_f32_16x16x32_bf16 v[106:109], v[170:173], v[202:205], v[106:109]
	v_mfma_f32_16x16x32_bf16 v[94:97], v[162:165], v[210:213], v[94:97]
	v_mfma_f32_16x16x32_bf16 v[90:93], v[170:173], v[210:213], v[90:93]
	v_mfma_f32_16x16x32_bf16 v[78:81], v[162:165], v[218:221], v[78:81]
	v_mfma_f32_16x16x32_bf16 v[74:77], v[170:173], v[218:221], v[74:77]
	v_mfma_f32_16x16x32_bf16 v[126:129], v[166:169], v[198:201], v[126:129]
	v_mfma_f32_16x16x32_bf16 v[122:125], v[174:177], v[198:201], v[122:125]
	v_mfma_f32_16x16x32_bf16 v[110:113], v[166:169], v[206:209], v[110:113]
	v_mfma_f32_16x16x32_bf16 v[106:109], v[174:177], v[206:209], v[106:109]
	v_mfma_f32_16x16x32_bf16 v[94:97], v[166:169], v[214:217], v[94:97]
	v_mfma_f32_16x16x32_bf16 v[90:93], v[174:177], v[214:217], v[90:93]
	v_mfma_f32_16x16x32_bf16 v[78:81], v[166:169], v[222:225], v[78:81]
	v_mfma_f32_16x16x32_bf16 v[74:77], v[174:177], v[222:225], v[74:77]
	v_mfma_f32_16x16x32_bf16 v[118:121], v[178:181], v[194:197], v[118:121]
	v_mfma_f32_16x16x32_bf16 v[114:117], v[186:189], v[194:197], v[114:117]
	v_mfma_f32_16x16x32_bf16 v[102:105], v[178:181], v[202:205], v[102:105]
	v_mfma_f32_16x16x32_bf16 v[98:101], v[186:189], v[202:205], v[98:101]
	v_mfma_f32_16x16x32_bf16 v[86:89], v[178:181], v[210:213], v[86:89]
	v_mfma_f32_16x16x32_bf16 v[82:85], v[186:189], v[210:213], v[82:85]
	v_mfma_f32_16x16x32_bf16 v[70:73], v[178:181], v[218:221], v[70:73]
	v_mfma_f32_16x16x32_bf16 v[66:69], v[186:189], v[218:221], v[66:69]
	v_mfma_f32_16x16x32_bf16 v[118:121], v[182:185], v[198:201], v[118:121]
	v_mfma_f32_16x16x32_bf16 v[114:117], v[190:193], v[198:201], v[114:117]
	v_mfma_f32_16x16x32_bf16 v[102:105], v[182:185], v[206:209], v[102:105]
	v_mfma_f32_16x16x32_bf16 v[98:101], v[190:193], v[206:209], v[98:101]
	v_mfma_f32_16x16x32_bf16 v[86:89], v[182:185], v[214:217], v[86:89]
	v_mfma_f32_16x16x32_bf16 v[82:85], v[190:193], v[214:217], v[82:85]
	v_mfma_f32_16x16x32_bf16 v[70:73], v[182:185], v[222:225], v[70:73]
	v_mfma_f32_16x16x32_bf16 v[66:69], v[190:193], v[222:225], v[66:69]
	s_barrier
; #define PG8_STAGE(bufoff, gbase, voff) do { _Pragma("unroll") for (int _i = 0; _i < 2; ++_i) \
;         __builtin_amdgcn_global_load_lds((const unsigned*)((const char*)(gbase) + (voff)[_i]), (PG8_LAS unsigned*)(lds + (bufoff) + ldsw + _i * 8192), 16, 0, 0); } while (0)
; #define PG8_LDA(dst, b, h) do { _Pragma("unroll") for (int m = 0; m < 4; ++m) _Pragma("unroll") for (int k = 0; k < 2; ++k) dst[m][k] = *(const PG8_LAS bf16x8*)(lds + PG8_SA(b, h) + aoff + m * 2048 + k * 1024); } while (0)
; #define PG8_MMA(ai, bj, At, Bt) do { __builtin_amdgcn_s_setprio(1); _Pragma("unroll") for (int m = 0; m < 4; ++m) _Pragma("unroll") for (int n = 0; n < 2; ++n) _Pragma("unroll") for (int k = 0; k < 2; ++k) \
;         acc[ai][bj][m][n] = __builtin_amdgcn_mfma_f32_16x16x32_bf16(Bt[n][k], At[m][k], acc[ai][bj][m][n], 0, 0, 0); __builtin_amdgcn_s_setprio(0); } while (0)
; #define PG8_WAIT_V(n) asm volatile("s_waitcnt vmcnt(" #n ")" ::: "memory")
; #define PG8_WAIT_L(n) asm volatile("s_waitcnt lgkmcnt(" #n ")" ::: "memory")
; #define PG8_BAR __builtin_amdgcn_s_barrier()
; #define PG8_SCHED __builtin_amdgcn_sched_barrier(0)
; template <class Epi, class Sched, bool ALIGN_EPI = false, bool SP2 = false>
; __device__ __forceinline__ void gemm_phase(PG8_LAS unsigned char* lds, const Gemm g, const Sched& S, const Epi& E) {
;     ...
;             PG8_LDA(At, 1, 1); PG8_STAGE(PG8_SB(1, 0), b3, voffB); PG8_STAGE(PG8_SB(1, 1), b3 + hstepB, voffB); PG8_STAGE(PG8_SA(1, 0), a3, voffA);
;             PG8_WAIT_V(8); PG8_WAIT_L(0); PG8_BAR; PG8_MMA(1, 0, At, B0); PG8_MMA(1, 1, At, B1); PG8_BAR; PG8_SCHED;
;     ...
;         if constexpr (ALIGN_EPI) { if (wr == 0) PG8_BAR; }
	s_mov_b32 m0, s67
	v_lshl_add_u64 v[148:149], v[148:149], 0, s[8:9]
	ds_read_b128 v[194:197], v153 offset:49152
	ds_read_b128 v[198:201], v153 offset:50176
	ds_read_b128 v[202:205], v153 offset:51200
	ds_read_b128 v[206:209], v153 offset:52224
	ds_read_b128 v[210:213], v153 offset:53248
	ds_read_b128 v[214:217], v153 offset:54272
	ds_read_b128 v[218:221], v153 offset:55296
	ds_read_b128 v[222:225], v153 offset:56320
	global_load_lds_dwordx4 v[148:149], off
	v_lshl_add_u64 v[148:149], v[226:227], 0, s[8:9]
	s_mov_b32 m0, s66
	s_nop 0
	global_load_lds_dwordx4 v[148:149], off
	v_lshl_add_u64 v[148:149], s[26:27], 0, v[132:133]
	s_mov_b32 m0, s75
	s_nop 0
	global_load_lds_dwordx4 v[148:149], off
	v_lshl_add_u64 v[148:149], s[26:27], 0, v[136:137]
	s_mov_b32 m0, s74
	s_nop 0
	global_load_lds_dwordx4 v[148:149], off
	v_lshl_add_u64 v[148:149], v[228:229], 0, s[8:9]
	s_mov_b32 m0, s53
	s_nop 0
	global_load_lds_dwordx4 v[148:149], off
	v_lshl_add_u64 v[148:149], v[230:231], 0, s[8:9]
	s_mov_b32 m0, s54
	s_nop 0
	global_load_lds_dwordx4 v[148:149], off
	s_waitcnt vmcnt(8)
	s_waitcnt lgkmcnt(0)
	s_barrier
	v_mfma_f32_16x16x32_bf16 v[62:65], v[162:165], v[194:197], v[62:65]
	v_mfma_f32_16x16x32_bf16 v[58:61], v[170:173], v[194:197], v[58:61]
	v_mfma_f32_16x16x32_bf16 v[46:49], v[162:165], v[202:205], v[46:49]
	v_mfma_f32_16x16x32_bf16 v[42:45], v[170:173], v[202:205], v[42:45]
	v_mfma_f32_16x16x32_bf16 v[30:33], v[162:165], v[210:213], v[30:33]
	v_mfma_f32_16x16x32_bf16 v[26:29], v[170:173], v[210:213], v[26:29]
	v_mfma_f32_16x16x32_bf16 v[14:17], v[162:165], v[218:221], v[14:17]
	v_mfma_f32_16x16x32_bf16 v[10:13], v[170:173], v[218:221], v[10:13]
	v_mfma_f32_16x16x32_bf16 v[62:65], v[166:169], v[198:201], v[62:65]
	v_mfma_f32_16x16x32_bf16 v[58:61], v[174:177], v[198:201], v[58:61]
	v_mfma_f32_16x16x32_bf16 v[46:49], v[166:169], v[206:209], v[46:49]
	v_mfma_f32_16x16x32_bf16 v[42:45], v[174:177], v[206:209], v[42:45]
	v_mfma_f32_16x16x32_bf16 v[30:33], v[166:169], v[214:217], v[30:33]
	v_mfma_f32_16x16x32_bf16 v[26:29], v[174:177], v[214:217], v[26:29]
	v_mfma_f32_16x16x32_bf16 v[14:17], v[166:169], v[222:225], v[14:17]
	v_mfma_f32_16x16x32_bf16 v[10:13], v[174:177], v[222:225], v[10:13]
	v_mfma_f32_16x16x32_bf16 v[54:57], v[178:181], v[194:197], v[54:57]
	v_mfma_f32_16x16x32_bf16 v[50:53], v[186:189], v[194:197], v[50:53]
	v_mfma_f32_16x16x32_bf16 v[38:41], v[178:181], v[202:205], v[38:41]
	v_mfma_f32_16x16x32_bf16 v[34:37], v[186:189], v[202:205], v[34:37]
	v_mfma_f32_16x16x32_bf16 v[22:25], v[178:181], v[210:213], v[22:25]
	v_mfma_f32_16x16x32_bf16 v[18:21], v[186:189], v[210:213], v[18:21]
	v_mfma_f32_16x16x32_bf16 v[6:9], v[178:181], v[218:221], v[6:9]
	v_mfma_f32_16x16x32_bf16 v[2:5], v[186:189], v[218:221], v[2:5]
	v_mfma_f32_16x16x32_bf16 v[54:57], v[182:185], v[198:201], v[54:57]
	v_mfma_f32_16x16x32_bf16 v[50:53], v[190:193], v[198:201], v[50:53]
	v_mfma_f32_16x16x32_bf16 v[38:41], v[182:185], v[206:209], v[38:41]
	v_mfma_f32_16x16x32_bf16 v[34:37], v[190:193], v[206:209], v[34:37]
	v_mfma_f32_16x16x32_bf16 v[22:25], v[182:185], v[214:217], v[22:25]
	v_mfma_f32_16x16x32_bf16 v[18:21], v[190:193], v[214:217], v[18:21]
	v_mfma_f32_16x16x32_bf16 v[6:9], v[182:185], v[222:225], v[6:9]
	v_mfma_f32_16x16x32_bf16 v[2:5], v[190:193], v[222:225], v[2:5]
	s_barrier
	s_andn2_b64 vcc, exec, s[0:1]
	s_mov_b64 s[26:27], -1
	s_mov_b64 s[0:1], 0
	s_mov_b64 s[28:29], 0x100
	s_cbranch_vccz .LBB0_832
	s_and_b64 vcc, exec, s[12:13]
	s_cbranch_vccz .LBB0_835
	s_barrier

; #define PG8_STAGE(bufoff, gbase, voff) do { _Pragma("unroll") for (int _i = 0; _i < 2; ++_i) \
;         __builtin_amdgcn_global_load_lds((const unsigned*)((const char*)(gbase) + (voff)[_i]), (PG8_LAS unsigned*)(lds + (bufoff) + ldsw + _i * 8192), 16, 0, 0); } while (0)
; #define PG8_LDA(dst, b, h) do { _Pragma("unroll") for (int m = 0; m < 4; ++m) _Pragma("unroll") for (int k = 0; k < 2; ++k) dst[m][k] = *(const PG8_LAS bf16x8*)(lds + PG8_SA(b, h) + aoff + m * 2048 + k * 1024); } while (0)
; #define PG8_LDB(dst, b, h) do { _Pragma("unroll") for (int n = 0; n < 2; ++n) _Pragma("unroll") for (int k = 0; k < 2; ++k) dst[n][k] = *(const PG8_LAS bf16x8*)(lds + PG8_SB(b, h) + boff + n * 2048 + k * 1024); } while (0)
; #define PG8_MMA(ai, bj, At, Bt) do { __builtin_amdgcn_s_setprio(1); _Pragma("unroll") for (int m = 0; m < 4; ++m) _Pragma("unroll") for (int n = 0; n < 2; ++n) _Pragma("unroll") for (int k = 0; k < 2; ++k) \
;         acc[ai][bj][m][n] = __builtin_amdgcn_mfma_f32_16x16x32_bf16(Bt[n][k], At[m][k], acc[ai][bj][m][n], 0, 0, 0); __builtin_amdgcn_s_setprio(0); } while (0)
; #define PG8_WAIT_V(n) asm volatile("s_waitcnt vmcnt(" #n ")" ::: "memory")
; #define PG8_WAIT_L(n) asm volatile("s_waitcnt lgkmcnt(" #n ")" ::: "memory")
; template <class Epi, class Sched, bool ALIGN_EPI = false, bool SP2 = false>
; __device__ __forceinline__ void gemm_phase(PG8_LAS unsigned char* lds, const Gemm g, const Sched& S, const Epi& E) {
;     ...
;             const bool last = (t == nt - 2);
;             const char* a1 = cA + (size_t)(t + 1) * kstep;
;             const char* a2 = last ? nA : cA + (size_t)(t + 2) * kstep; const char* b2 = last ? nB : cB + (size_t)(t + 2) * kstep;
;             const char* a3 = a2 + kstep; const char* b3 = b2 + kstep;
;             if (last && has_next) S.a_ready(nxt);
;             if constexpr (SP2) {
;             PG8_LDB(B0, 0, 0); PG8_LDB(B1, 0, 1); PG8_SCHED; PG8_LDA(At, 0, 0); PG8_STAGE(PG8_SA(1, 1), a1 + hstepA, voffA);
;             PG8_WAIT_V(8); PG8_WAIT_L(0); PG8_BAR; PG8_MMA(0, 0, At, B0); PG8_MMA(0, 1, At, B1); PG8_BAR; PG8_SCHED;
;             PG8_LDA(At, 0, 1); PG8_STAGE(PG8_SB(0, 0), b2, voffB); PG8_STAGE(PG8_SB(0, 1), b2 + hstepB, voffB); PG8_STAGE(PG8_SA(0, 0), a2, voffA);
;             PG8_WAIT_V(8); PG8_WAIT_L(0); PG8_BAR; PG8_MMA(1, 0, At, B0); PG8_MMA(1, 1, At, B1); PG8_BAR; PG8_SCHED;
.LBB0_1324:
	s_add_u32 s37, s28, s36
	s_addc_u32 s42, s29, 0
	s_add_u32 s40, s37, 0x100
	s_addc_u32 s41, s42, 0
	s_and_b64 s[38:39], s[34:35], exec
	s_cselect_b32 s39, s17, s41
	s_cselect_b32 s38, s78, s40
	s_add_u32 s36, s26, s36
	s_addc_u32 s40, s27, 0
	s_add_u32 s36, s36, 0x100
	s_addc_u32 s40, s40, 0
	s_and_b64 s[34:35], s[34:35], exec
	s_cselect_b32 s41, s15, s40
	s_cselect_b32 s40, s79, s36
	s_add_u32 s44, s37, 0x40080
	ds_read_b128 v[130:133], v158
	ds_read_b128 v[134:137], v158 offset:1024
	ds_read_b128 v[138:141], v158 offset:2048
	ds_read_b128 v[142:145], v158 offset:3072
	ds_read_b128 v[152:155], v159
	ds_read_b128 v[162:165], v159 offset:1024
	ds_read_b128 v[166:169], v159 offset:2048
	ds_read_b128 v[170:173], v159 offset:3072
	s_addc_u32 s45, s42, 0
	s_add_i32 s87, s69, s56
	s_add_i32 m0, s25, 0xc000
	s_add_i32 s90, s25, 0xe000
	s_add_i32 s84, s87, 0x2000
	s_add_u32 s42, s40, 0x40000
	s_addc_u32 s43, s41, 0
	s_add_i32 s86, s70, s56
	s_add_i32 s85, s86, 0x2000
	s_add_i32 s83, 0, 0x18000
	s_add_i32 s82, 0, 0x1c000
	s_add_u32 s36, s38, 0x40000
	s_addc_u32 s37, s39, 0
	s_add_i32 s81, s83, s56
	s_add_i32 s80, s81, 0x2000
	s_add_u32 s34, s40, 0x40080
	s_addc_u32 s35, s41, 0
	s_add_i32 s89, s82, s56
	s_add_i32 s88, s89, 0x2000
	v_lshl_add_u64 v[206:207], s[44:45], 0, v[148:149]
	ds_read_b128 v[174:177], v160
	ds_read_b128 v[178:181], v160 offset:1024
	ds_read_b128 v[182:185], v160 offset:2048
	ds_read_b128 v[186:189], v160 offset:3072
	ds_read_b128 v[190:193], v160 offset:4096
	ds_read_b128 v[194:197], v160 offset:5120
	ds_read_b128 v[198:201], v160 offset:6144
	ds_read_b128 v[202:205], v160 offset:7168
	global_load_lds_dwordx4 v[206:207], off
	v_lshl_add_u64 v[206:207], s[44:45], 0, v[146:147]
	s_mov_b32 m0, s90
	s_nop 0
	global_load_lds_dwordx4 v[206:207], off
	s_waitcnt vmcnt(8)
	s_waitcnt lgkmcnt(0)
	s_barrier
	v_mfma_f32_16x16x32_bf16 v[126:129], v[130:133], v[174:177], v[126:129]
	v_mfma_f32_16x16x32_bf16 v[122:125], v[138:141], v[174:177], v[122:125]
	v_mfma_f32_16x16x32_bf16 v[118:121], v[130:133], v[182:185], v[118:121]
	v_mfma_f32_16x16x32_bf16 v[114:117], v[138:141], v[182:185], v[114:117]
	v_mfma_f32_16x16x32_bf16 v[102:105], v[130:133], v[190:193], v[102:105]
	v_mfma_f32_16x16x32_bf16 v[90:93], v[138:141], v[190:193], v[90:93]
	v_mfma_f32_16x16x32_bf16 v[82:85], v[130:133], v[198:201], v[82:85]
	v_mfma_f32_16x16x32_bf16 v[74:77], v[138:141], v[198:201], v[74:77]
	v_mfma_f32_16x16x32_bf16 v[126:129], v[134:137], v[178:181], v[126:129]
	v_mfma_f32_16x16x32_bf16 v[122:125], v[142:145], v[178:181], v[122:125]
	v_mfma_f32_16x16x32_bf16 v[118:121], v[134:137], v[186:189], v[118:121]
	v_mfma_f32_16x16x32_bf16 v[114:117], v[142:145], v[186:189], v[114:117]
	v_mfma_f32_16x16x32_bf16 v[102:105], v[134:137], v[194:197], v[102:105]
	v_mfma_f32_16x16x32_bf16 v[90:93], v[142:145], v[194:197], v[90:93]
	v_mfma_f32_16x16x32_bf16 v[82:85], v[134:137], v[202:205], v[82:85]
	v_mfma_f32_16x16x32_bf16 v[74:77], v[142:145], v[202:205], v[74:77]
	v_mfma_f32_16x16x32_bf16 v[110:113], v[152:155], v[174:177], v[110:113]
	v_mfma_f32_16x16x32_bf16 v[106:109], v[166:169], v[174:177], v[106:109]
	v_mfma_f32_16x16x32_bf16 v[98:101], v[152:155], v[182:185], v[98:101]
	v_mfma_f32_16x16x32_bf16 v[94:97], v[166:169], v[182:185], v[94:97]
	v_mfma_f32_16x16x32_bf16 v[86:89], v[152:155], v[190:193], v[86:89]
	v_mfma_f32_16x16x32_bf16 v[78:81], v[166:169], v[190:193], v[78:81]
	v_mfma_f32_16x16x32_bf16 v[70:73], v[152:155], v[198:201], v[70:73]
	v_mfma_f32_16x16x32_bf16 v[66:69], v[166:169], v[198:201], v[66:69]
	v_mfma_f32_16x16x32_bf16 v[110:113], v[162:165], v[178:181], v[110:113]
	v_mfma_f32_16x16x32_bf16 v[106:109], v[170:173], v[178:181], v[106:109]
	v_mfma_f32_16x16x32_bf16 v[98:101], v[162:165], v[186:189], v[98:101]
	v_mfma_f32_16x16x32_bf16 v[94:97], v[170:173], v[186:189], v[94:97]
	v_mfma_f32_16x16x32_bf16 v[86:89], v[162:165], v[194:197], v[86:89]
	v_mfma_f32_16x16x32_bf16 v[78:81], v[170:173], v[194:197], v[78:81]
	v_mfma_f32_16x16x32_bf16 v[70:73], v[162:165], v[202:205], v[70:73]
	v_mfma_f32_16x16x32_bf16 v[66:69], v[170:173], v[202:205], v[66:69]
	s_barrier
	s_mov_b32 m0, s87
	v_lshl_add_u64 v[206:207], s[40:41], 0, v[148:149]
	ds_read_b128 v[174:177], v160 offset:16384
	ds_read_b128 v[178:181], v160 offset:17408
	ds_read_b128 v[182:185], v160 offset:18432
	ds_read_b128 v[186:189], v160 offset:19456
	ds_read_b128 v[190:193], v160 offset:20480
	ds_read_b128 v[194:197], v160 offset:21504
	ds_read_b128 v[198:201], v160 offset:22528
	ds_read_b128 v[202:205], v160 offset:23552
	global_load_lds_dwordx4 v[206:207], off
	v_lshl_add_u64 v[208:209], s[40:41], 0, v[146:147]
	s_mov_b32 m0, s84
	v_lshl_add_u64 v[210:211], s[42:43], 0, v[148:149]
	global_load_lds_dwordx4 v[208:209], off
	s_mov_b32 m0, s86
	v_lshl_add_u64 v[212:213], s[38:39], 0, v[146:147]
	global_load_lds_dwordx4 v[210:211], off
	v_lshl_add_u64 v[210:211], s[42:43], 0, v[146:147]
	s_mov_b32 m0, s85
	s_nop 0
	global_load_lds_dwordx4 v[210:211], off
	v_lshl_add_u64 v[210:211], s[38:39], 0, v[148:149]
	s_mov_b32 m0, s25
	s_nop 0
	global_load_lds_dwordx4 v[210:211], off
	s_mov_b32 m0, s58
	s_nop 0
	global_load_lds_dwordx4 v[212:213], off
	s_waitcnt vmcnt(8)
	s_waitcnt lgkmcnt(0)
	s_barrier
; #define PG8_STAGE(bufoff, gbase, voff) do { _Pragma("unroll") for (int _i = 0; _i < 2; ++_i) \
;         __builtin_amdgcn_global_load_lds((const unsigned*)((const char*)(gbase) + (voff)[_i]), (PG8_LAS unsigned*)(lds + (bufoff) + ldsw + _i * 8192), 16, 0, 0); } while (0)
; #define PG8_LDA(dst, b, h) do { _Pragma("unroll") for (int m = 0; m < 4; ++m) _Pragma("unroll") for (int k = 0; k < 2; ++k) dst[m][k] = *(const PG8_LAS bf16x8*)(lds + PG8_SA(b, h) + aoff + m * 2048 + k * 1024); } while (0)
; #define PG8_LDB(dst, b, h) do { _Pragma("unroll") for (int n = 0; n < 2; ++n) _Pragma("unroll") for (int k = 0; k < 2; ++k) dst[n][k] = *(const PG8_LAS bf16x8*)(lds + PG8_SB(b, h) + boff + n * 2048 + k * 1024); } while (0)
; #define PG8_MMA(ai, bj, At, Bt) do { __builtin_amdgcn_s_setprio(1); _Pragma("unroll") for (int m = 0; m < 4; ++m) _Pragma("unroll") for (int n = 0; n < 2; ++n) _Pragma("unroll") for (int k = 0; k < 2; ++k) \
;         acc[ai][bj][m][n] = __builtin_amdgcn_mfma_f32_16x16x32_bf16(Bt[n][k], At[m][k], acc[ai][bj][m][n], 0, 0, 0); __builtin_amdgcn_s_setprio(0); } while (0)
; #define PG8_WAIT_V(n) asm volatile("s_waitcnt vmcnt(" #n ")" ::: "memory")
; #define PG8_WAIT_L(n) asm volatile("s_waitcnt lgkmcnt(" #n ")" ::: "memory")
; #define PG8_BAR __builtin_amdgcn_s_barrier()
; #define PG8_SCHED __builtin_amdgcn_sched_barrier(0)
; template <class Epi, class Sched, bool ALIGN_EPI = false, bool SP2 = false>
; __device__ __forceinline__ void gemm_phase(PG8_LAS unsigned char* lds, const Gemm g, const Sched& S, const Epi& E) {
;     ...
;             PG8_WAIT_V(8); PG8_WAIT_L(0); PG8_BAR; PG8_MMA(1, 0, At, B0); PG8_MMA(1, 1, At, B1); PG8_BAR; PG8_SCHED;
;             PG8_LDB(B0, 1, 0); PG8_LDB(B1, 1, 1); PG8_SCHED; PG8_LDA(At, 1, 0); PG8_STAGE(PG8_SA(0, 1), a2 + hstepA, voffA);
;             PG8_WAIT_V(8); PG8_WAIT_L(0); PG8_BAR; PG8_MMA(0, 0, At, B0); PG8_MMA(0, 1, At, B1); PG8_BAR; PG8_SCHED;
	v_mfma_f32_16x16x32_bf16 v[62:65], v[130:133], v[174:177], v[62:65]
	v_mfma_f32_16x16x32_bf16 v[58:61], v[138:141], v[174:177], v[58:61]
	v_mfma_f32_16x16x32_bf16 v[54:57], v[130:133], v[182:185], v[54:57]
	v_mfma_f32_16x16x32_bf16 v[50:53], v[138:141], v[182:185], v[50:53]
	v_mfma_f32_16x16x32_bf16 v[46:49], v[130:133], v[190:193], v[46:49]
	v_mfma_f32_16x16x32_bf16 v[38:41], v[138:141], v[190:193], v[38:41]
	v_mfma_f32_16x16x32_bf16 v[18:21], v[130:133], v[198:201], v[18:21]
	v_mfma_f32_16x16x32_bf16 v[10:13], v[138:141], v[198:201], v[10:13]
	v_mfma_f32_16x16x32_bf16 v[62:65], v[134:137], v[178:181], v[62:65]
	v_mfma_f32_16x16x32_bf16 v[58:61], v[142:145], v[178:181], v[58:61]
	v_mfma_f32_16x16x32_bf16 v[54:57], v[134:137], v[186:189], v[54:57]
	v_mfma_f32_16x16x32_bf16 v[50:53], v[142:145], v[186:189], v[50:53]
	v_mfma_f32_16x16x32_bf16 v[46:49], v[134:137], v[194:197], v[46:49]
	v_mfma_f32_16x16x32_bf16 v[38:41], v[142:145], v[194:197], v[38:41]
	v_mfma_f32_16x16x32_bf16 v[18:21], v[134:137], v[202:205], v[18:21]
	v_mfma_f32_16x16x32_bf16 v[10:13], v[142:145], v[202:205], v[10:13]
	v_mfma_f32_16x16x32_bf16 v[42:45], v[152:155], v[174:177], v[42:45]
	v_mfma_f32_16x16x32_bf16 v[34:37], v[166:169], v[174:177], v[34:37]
	v_mfma_f32_16x16x32_bf16 v[30:33], v[152:155], v[182:185], v[30:33]
	v_mfma_f32_16x16x32_bf16 v[26:29], v[166:169], v[182:185], v[26:29]
	v_mfma_f32_16x16x32_bf16 v[22:25], v[152:155], v[190:193], v[22:25]
	v_mfma_f32_16x16x32_bf16 v[14:17], v[166:169], v[190:193], v[14:17]
	v_mfma_f32_16x16x32_bf16 v[6:9], v[152:155], v[198:201], v[6:9]
	v_mfma_f32_16x16x32_bf16 v[2:5], v[166:169], v[198:201], v[2:5]
	v_mfma_f32_16x16x32_bf16 v[42:45], v[162:165], v[178:181], v[42:45]
	v_mfma_f32_16x16x32_bf16 v[34:37], v[170:173], v[178:181], v[34:37]
	v_mfma_f32_16x16x32_bf16 v[30:33], v[162:165], v[186:189], v[30:33]
	v_mfma_f32_16x16x32_bf16 v[26:29], v[170:173], v[186:189], v[26:29]
	v_mfma_f32_16x16x32_bf16 v[22:25], v[162:165], v[194:197], v[22:25]
	v_mfma_f32_16x16x32_bf16 v[14:17], v[170:173], v[194:197], v[14:17]
	v_mfma_f32_16x16x32_bf16 v[6:9], v[162:165], v[202:205], v[6:9]
	v_mfma_f32_16x16x32_bf16 v[2:5], v[170:173], v[202:205], v[2:5]
	s_barrier
	v_add_u32_e32 v142, s83, v1
	v_add_u32_e32 v170, s82, v1
	ds_read_b128 v[130:133], v142
	ds_read_b128 v[134:137], v142 offset:1024
	ds_read_b128 v[138:141], v142 offset:2048
	ds_read_b128 v[142:145], v142 offset:3072
	ds_read_b128 v[152:155], v170
	ds_read_b128 v[162:165], v170 offset:1024
	ds_read_b128 v[166:169], v170 offset:2048
	ds_read_b128 v[170:173], v170 offset:3072
	s_mov_b32 m0, s59
	v_lshl_add_u64 v[214:215], s[36:37], 0, v[148:149]
	ds_read_b128 v[174:177], v160 offset:32768
	ds_read_b128 v[178:181], v160 offset:33792
	ds_read_b128 v[182:185], v160 offset:34816
	ds_read_b128 v[186:189], v160 offset:35840
	ds_read_b128 v[190:193], v160 offset:36864
	ds_read_b128 v[194:197], v160 offset:37888
	ds_read_b128 v[198:201], v160 offset:38912
	ds_read_b128 v[202:205], v160 offset:39936
	global_load_lds_dwordx4 v[214:215], off
	v_lshl_add_u64 v[214:215], s[36:37], 0, v[146:147]
	s_mov_b32 m0, s60
	s_nop 0
	global_load_lds_dwordx4 v[214:215], off
	s_waitcnt vmcnt(8)
	s_waitcnt lgkmcnt(0)
	s_barrier
	v_mfma_f32_16x16x32_bf16 v[126:129], v[130:133], v[174:177], v[126:129]
	v_mfma_f32_16x16x32_bf16 v[122:125], v[138:141], v[174:177], v[122:125]
	v_mfma_f32_16x16x32_bf16 v[118:121], v[130:133], v[182:185], v[118:121]
	v_mfma_f32_16x16x32_bf16 v[114:117], v[138:141], v[182:185], v[114:117]
	v_mfma_f32_16x16x32_bf16 v[102:105], v[130:133], v[190:193], v[102:105]
	v_mfma_f32_16x16x32_bf16 v[90:93], v[138:141], v[190:193], v[90:93]
	v_mfma_f32_16x16x32_bf16 v[82:85], v[130:133], v[198:201], v[82:85]
	v_mfma_f32_16x16x32_bf16 v[74:77], v[138:141], v[198:201], v[74:77]
	v_mfma_f32_16x16x32_bf16 v[126:129], v[134:137], v[178:181], v[126:129]
	v_mfma_f32_16x16x32_bf16 v[122:125], v[142:145], v[178:181], v[122:125]
	v_mfma_f32_16x16x32_bf16 v[118:121], v[134:137], v[186:189], v[118:121]
	v_mfma_f32_16x16x32_bf16 v[114:117], v[142:145], v[186:189], v[114:117]
	v_mfma_f32_16x16x32_bf16 v[102:105], v[134:137], v[194:197], v[102:105]
	v_mfma_f32_16x16x32_bf16 v[90:93], v[142:145], v[194:197], v[90:93]
	v_mfma_f32_16x16x32_bf16 v[82:85], v[134:137], v[202:205], v[82:85]
	v_mfma_f32_16x16x32_bf16 v[74:77], v[142:145], v[202:205], v[74:77]
	v_mfma_f32_16x16x32_bf16 v[110:113], v[152:155], v[174:177], v[110:113]
	v_mfma_f32_16x16x32_bf16 v[106:109], v[166:169], v[174:177], v[106:109]
	v_mfma_f32_16x16x32_bf16 v[98:101], v[152:155], v[182:185], v[98:101]
	v_mfma_f32_16x16x32_bf16 v[94:97], v[166:169], v[182:185], v[94:97]
	v_mfma_f32_16x16x32_bf16 v[86:89], v[152:155], v[190:193], v[86:89]
	v_mfma_f32_16x16x32_bf16 v[78:81], v[166:169], v[190:193], v[78:81]
	v_mfma_f32_16x16x32_bf16 v[70:73], v[152:155], v[198:201], v[70:73]
	v_mfma_f32_16x16x32_bf16 v[66:69], v[166:169], v[198:201], v[66:69]
	v_mfma_f32_16x16x32_bf16 v[110:113], v[162:165], v[178:181], v[110:113]
	v_mfma_f32_16x16x32_bf16 v[106:109], v[170:173], v[178:181], v[106:109]
	v_mfma_f32_16x16x32_bf16 v[98:101], v[162:165], v[186:189], v[98:101]
	v_mfma_f32_16x16x32_bf16 v[94:97], v[170:173], v[186:189], v[94:97]
	v_mfma_f32_16x16x32_bf16 v[86:89], v[162:165], v[194:197], v[86:89]
	v_mfma_f32_16x16x32_bf16 v[78:81], v[170:173], v[194:197], v[78:81]
	v_mfma_f32_16x16x32_bf16 v[70:73], v[162:165], v[202:205], v[70:73]
	v_mfma_f32_16x16x32_bf16 v[66:69], v[170:173], v[202:205], v[66:69]
	s_barrier
; #define PG8_STAGE(bufoff, gbase, voff) do { _Pragma("unroll") for (int _i = 0; _i < 2; ++_i) \
;         __builtin_amdgcn_global_load_lds((const unsigned*)((const char*)(gbase) + (voff)[_i]), (PG8_LAS unsigned*)(lds + (bufoff) + ldsw + _i * 8192), 16, 0, 0); } while (0)
; #define PG8_LDA(dst, b, h) do { _Pragma("unroll") for (int m = 0; m < 4; ++m) _Pragma("unroll") for (int k = 0; k < 2; ++k) dst[m][k] = *(const PG8_LAS bf16x8*)(lds + PG8_SA(b, h) + aoff + m * 2048 + k * 1024); } while (0)
; #define PG8_MMA(ai, bj, At, Bt) do { __builtin_amdgcn_s_setprio(1); _Pragma("unroll") for (int m = 0; m < 4; ++m) _Pragma("unroll") for (int n = 0; n < 2; ++n) _Pragma("unroll") for (int k = 0; k < 2; ++k) \
;         acc[ai][bj][m][n] = __builtin_amdgcn_mfma_f32_16x16x32_bf16(Bt[n][k], At[m][k], acc[ai][bj][m][n], 0, 0, 0); __builtin_amdgcn_s_setprio(0); } while (0)
; #define PG8_WAIT_V(n) asm volatile("s_waitcnt vmcnt(" #n ")" ::: "memory")
; #define PG8_WAIT_L(n) asm volatile("s_waitcnt lgkmcnt(" #n ")" ::: "memory")
; #define PG8_BAR __builtin_amdgcn_s_barrier()
; #define PG8_SCHED __builtin_amdgcn_sched_barrier(0)
; template <class Epi, class Sched, bool ALIGN_EPI = false, bool SP2 = false>
; __device__ __forceinline__ void gemm_phase(PG8_LAS unsigned char* lds, const Gemm g, const Sched& S, const Epi& E) {
;     ...
;         for (int t = 0; t < nt; t += 2) {
;     ...
;             PG8_LDA(At, 1, 1); PG8_STAGE(PG8_SB(1, 0), b3, voffB); PG8_STAGE(PG8_SB(1, 1), b3 + hstepB, voffB); PG8_STAGE(PG8_SA(1, 0), a3, voffA);
;             PG8_WAIT_V(8); PG8_WAIT_L(0); PG8_BAR; PG8_MMA(1, 0, At, B0); PG8_MMA(1, 1, At, B1); PG8_BAR; PG8_SCHED;
	s_mov_b32 m0, s81
	v_lshl_add_u64 v[206:207], v[206:207], 0, s[4:5]
	ds_read_b128 v[174:177], v160 offset:49152
	ds_read_b128 v[178:181], v160 offset:50176
	ds_read_b128 v[182:185], v160 offset:51200
	ds_read_b128 v[186:189], v160 offset:52224
	ds_read_b128 v[190:193], v160 offset:53248
	ds_read_b128 v[194:197], v160 offset:54272
	ds_read_b128 v[198:201], v160 offset:55296
	ds_read_b128 v[202:205], v160 offset:56320
	global_load_lds_dwordx4 v[206:207], off
	v_lshl_add_u64 v[206:207], v[208:209], 0, s[4:5]
	s_mov_b32 m0, s80
	s_nop 0
	global_load_lds_dwordx4 v[206:207], off
	v_lshl_add_u64 v[206:207], s[34:35], 0, v[148:149]
	s_mov_b32 m0, s89
	s_nop 0
	global_load_lds_dwordx4 v[206:207], off
	v_lshl_add_u64 v[206:207], s[34:35], 0, v[146:147]
	s_mov_b32 m0, s88
	s_nop 0
	global_load_lds_dwordx4 v[206:207], off
	v_lshl_add_u64 v[206:207], v[210:211], 0, s[4:5]
	s_mov_b32 m0, s66
	s_nop 0
	global_load_lds_dwordx4 v[206:207], off
	v_lshl_add_u64 v[206:207], v[212:213], 0, s[4:5]
	s_mov_b32 m0, s67
	s_nop 0
	global_load_lds_dwordx4 v[206:207], off
	s_waitcnt vmcnt(8)
	s_waitcnt lgkmcnt(0)
	s_barrier
	v_mfma_f32_16x16x32_bf16 v[62:65], v[130:133], v[174:177], v[62:65]
	v_mfma_f32_16x16x32_bf16 v[58:61], v[138:141], v[174:177], v[58:61]
	v_mfma_f32_16x16x32_bf16 v[54:57], v[130:133], v[182:185], v[54:57]
	v_mfma_f32_16x16x32_bf16 v[50:53], v[138:141], v[182:185], v[50:53]
	v_mfma_f32_16x16x32_bf16 v[46:49], v[130:133], v[190:193], v[46:49]
	v_mfma_f32_16x16x32_bf16 v[38:41], v[138:141], v[190:193], v[38:41]
	v_mfma_f32_16x16x32_bf16 v[18:21], v[130:133], v[198:201], v[18:21]
	v_mfma_f32_16x16x32_bf16 v[10:13], v[138:141], v[198:201], v[10:13]
	v_mfma_f32_16x16x32_bf16 v[62:65], v[134:137], v[178:181], v[62:65]
	v_mfma_f32_16x16x32_bf16 v[58:61], v[142:145], v[178:181], v[58:61]
	v_mfma_f32_16x16x32_bf16 v[54:57], v[134:137], v[186:189], v[54:57]
	v_mfma_f32_16x16x32_bf16 v[50:53], v[142:145], v[186:189], v[50:53]
	v_mfma_f32_16x16x32_bf16 v[46:49], v[134:137], v[194:197], v[46:49]
	v_mfma_f32_16x16x32_bf16 v[38:41], v[142:145], v[194:197], v[38:41]
	v_mfma_f32_16x16x32_bf16 v[18:21], v[134:137], v[202:205], v[18:21]
	v_mfma_f32_16x16x32_bf16 v[10:13], v[142:145], v[202:205], v[10:13]
	v_mfma_f32_16x16x32_bf16 v[42:45], v[152:155], v[174:177], v[42:45]
	v_mfma_f32_16x16x32_bf16 v[34:37], v[166:169], v[174:177], v[34:37]
	v_mfma_f32_16x16x32_bf16 v[30:33], v[152:155], v[182:185], v[30:33]
	v_mfma_f32_16x16x32_bf16 v[26:29], v[166:169], v[182:185], v[26:29]
	v_mfma_f32_16x16x32_bf16 v[22:25], v[152:155], v[190:193], v[22:25]
	v_mfma_f32_16x16x32_bf16 v[14:17], v[166:169], v[190:193], v[14:17]
	v_mfma_f32_16x16x32_bf16 v[6:9], v[152:155], v[198:201], v[6:9]
	v_mfma_f32_16x16x32_bf16 v[2:5], v[166:169], v[198:201], v[2:5]
	v_mfma_f32_16x16x32_bf16 v[42:45], v[162:165], v[178:181], v[42:45]
	v_mfma_f32_16x16x32_bf16 v[34:37], v[170:173], v[178:181], v[34:37]
	v_mfma_f32_16x16x32_bf16 v[30:33], v[162:165], v[186:189], v[30:33]
	v_mfma_f32_16x16x32_bf16 v[26:29], v[170:173], v[186:189], v[26:29]
	v_mfma_f32_16x16x32_bf16 v[22:25], v[162:165], v[194:197], v[22:25]
	v_mfma_f32_16x16x32_bf16 v[14:17], v[170:173], v[194:197], v[14:17]
	v_mfma_f32_16x16x32_bf16 v[6:9], v[162:165], v[202:205], v[6:9]
	v_mfma_f32_16x16x32_bf16 v[2:5], v[170:173], v[202:205], v[2:5]
	s_barrier
	s_movk_i32 s36, 0x100
	s_andn2_b64 vcc, exec, s[30:31]
	s_mov_b64 s[34:35], -1
	s_mov_b64 s[30:31], 0
	s_cbranch_vccz .LBB0_1324
	s_and_b64 vcc, exec, s[8:9]
	s_cbranch_vccz .LBB0_1327
	s_barrier

; #define PG8_STAGE(bufoff, gbase, voff) do { _Pragma("unroll") for (int _i = 0; _i < 2; ++_i) \
;         __builtin_amdgcn_global_load_lds((const unsigned*)((const char*)(gbase) + (voff)[_i]), (PG8_LAS unsigned*)(lds + (bufoff) + ldsw + _i * 8192), 16, 0, 0); } while (0)
; #define PG8_LDA(dst, b, h) do { _Pragma("unroll") for (int m = 0; m < 4; ++m) _Pragma("unroll") for (int k = 0; k < 2; ++k) dst[m][k] = *(const PG8_LAS bf16x8*)(lds + PG8_SA(b, h) + aoff + m * 2048 + k * 1024); } while (0)
; #define PG8_LDB(dst, b, h) do { _Pragma("unroll") for (int n = 0; n < 2; ++n) _Pragma("unroll") for (int k = 0; k < 2; ++k) dst[n][k] = *(const PG8_LAS bf16x8*)(lds + PG8_SB(b, h) + boff + n * 2048 + k * 1024); } while (0)
; #define PG8_MMA(ai, bj, At, Bt) do { __builtin_amdgcn_s_setprio(1); _Pragma("unroll") for (int m = 0; m < 4; ++m) _Pragma("unroll") for (int n = 0; n < 2; ++n) _Pragma("unroll") for (int k = 0; k < 2; ++k) \
;         acc[ai][bj][m][n] = __builtin_amdgcn_mfma_f32_16x16x32_bf16(Bt[n][k], At[m][k], acc[ai][bj][m][n], 0, 0, 0); __builtin_amdgcn_s_setprio(0); } while (0)
; #define PG8_WAIT_V(n) asm volatile("s_waitcnt vmcnt(" #n ")" ::: "memory")
; #define PG8_WAIT_L(n) asm volatile("s_waitcnt lgkmcnt(" #n ")" ::: "memory")
; template <class Epi, class Sched, bool ALIGN_EPI = false, bool SP2 = false>
; __device__ __forceinline__ void gemm_phase(PG8_LAS unsigned char* lds, const Gemm g, const Sched& S, const Epi& E) {
;     ...
;             const bool last = (t == nt - 2);
;             const char* a1 = cA + (size_t)(t + 1) * kstep;
;             const char* a2 = last ? nA : cA + (size_t)(t + 2) * kstep; const char* b2 = last ? nB : cB + (size_t)(t + 2) * kstep;
;             const char* a3 = a2 + kstep; const char* b3 = b2 + kstep;
;             if (last && has_next) S.a_ready(nxt);
;             if constexpr (SP2) {
;             PG8_LDB(B0, 0, 0); PG8_LDB(B1, 0, 1); PG8_SCHED; PG8_LDA(At, 0, 0); PG8_STAGE(PG8_SA(1, 1), a1 + hstepA, voffA);
;             PG8_WAIT_V(8); PG8_WAIT_L(0); PG8_BAR; PG8_MMA(0, 0, At, B0); PG8_MMA(0, 1, At, B1); PG8_BAR; PG8_SCHED;
;             PG8_LDA(At, 0, 1); PG8_STAGE(PG8_SB(0, 0), b2, voffB); PG8_STAGE(PG8_SB(0, 1), b2 + hstepB, voffB); PG8_STAGE(PG8_SA(0, 0), a2, voffA);
;             PG8_WAIT_V(8); PG8_WAIT_L(0); PG8_BAR; PG8_MMA(1, 0, At, B0); PG8_MMA(1, 1, At, B1); PG8_BAR; PG8_SCHED;
.LBB0_1344:
	s_add_u32 s72, s28, s71
	ds_read_b128 v[130:133], v158
	ds_read_b128 v[134:137], v158 offset:1024
	ds_read_b128 v[138:141], v158 offset:2048
	ds_read_b128 v[142:145], v158 offset:3072
	ds_read_b128 v[152:155], v159
	ds_read_b128 v[162:165], v159 offset:1024
	ds_read_b128 v[166:169], v159 offset:2048
	ds_read_b128 v[170:173], v159 offset:3072
	s_addc_u32 s73, s29, 0
	s_add_u32 s74, s72, 0x100
	s_addc_u32 s75, s73, 0
	s_and_b64 s[36:37], s[34:35], exec
	s_cselect_b32 s37, s17, s75
	s_cselect_b32 s36, s69, s74
	s_add_u32 s71, s26, s71
	s_addc_u32 s74, s27, 0
	s_add_u32 s71, s71, 0x100
	s_addc_u32 s74, s74, 0
	s_and_b64 s[34:35], s[34:35], exec
	s_cselect_b32 s35, s15, s74
	s_cselect_b32 s34, s70, s71
	s_add_u32 s72, s72, 0x40080
	s_addc_u32 s73, s73, 0
	v_lshl_add_u64 v[206:207], s[72:73], 0, v[148:149]
	s_add_i32 m0, s49, 0xc000
	ds_read_b128 v[174:177], v160
	ds_read_b128 v[178:181], v160 offset:1024
	ds_read_b128 v[182:185], v160 offset:2048
	ds_read_b128 v[186:189], v160 offset:3072
	ds_read_b128 v[190:193], v160 offset:4096
	ds_read_b128 v[194:197], v160 offset:5120
	ds_read_b128 v[198:201], v160 offset:6144
	ds_read_b128 v[202:205], v160 offset:7168
	global_load_lds_dwordx4 v[206:207], off
	v_lshl_add_u64 v[206:207], s[72:73], 0, v[146:147]
	s_add_i32 m0, s49, 0xe000
	s_nop 0
	global_load_lds_dwordx4 v[206:207], off
	s_waitcnt vmcnt(8)
	s_waitcnt lgkmcnt(0)
	s_barrier
	v_mfma_f32_16x16x32_bf16 v[126:129], v[130:133], v[174:177], v[126:129]
	v_mfma_f32_16x16x32_bf16 v[122:125], v[138:141], v[174:177], v[122:125]
	v_mfma_f32_16x16x32_bf16 v[118:121], v[130:133], v[182:185], v[118:121]
	v_mfma_f32_16x16x32_bf16 v[114:117], v[138:141], v[182:185], v[114:117]
	v_mfma_f32_16x16x32_bf16 v[102:105], v[130:133], v[190:193], v[102:105]
	v_mfma_f32_16x16x32_bf16 v[90:93], v[138:141], v[190:193], v[90:93]
	v_mfma_f32_16x16x32_bf16 v[82:85], v[130:133], v[198:201], v[82:85]
	v_mfma_f32_16x16x32_bf16 v[74:77], v[138:141], v[198:201], v[74:77]
	v_mfma_f32_16x16x32_bf16 v[126:129], v[134:137], v[178:181], v[126:129]
	v_mfma_f32_16x16x32_bf16 v[122:125], v[142:145], v[178:181], v[122:125]
	v_mfma_f32_16x16x32_bf16 v[118:121], v[134:137], v[186:189], v[118:121]
	v_mfma_f32_16x16x32_bf16 v[114:117], v[142:145], v[186:189], v[114:117]
	v_mfma_f32_16x16x32_bf16 v[102:105], v[134:137], v[194:197], v[102:105]
	v_mfma_f32_16x16x32_bf16 v[90:93], v[142:145], v[194:197], v[90:93]
	v_mfma_f32_16x16x32_bf16 v[82:85], v[134:137], v[202:205], v[82:85]
	v_mfma_f32_16x16x32_bf16 v[74:77], v[142:145], v[202:205], v[74:77]
	v_mfma_f32_16x16x32_bf16 v[110:113], v[152:155], v[174:177], v[110:113]
	v_mfma_f32_16x16x32_bf16 v[106:109], v[166:169], v[174:177], v[106:109]
	v_mfma_f32_16x16x32_bf16 v[98:101], v[152:155], v[182:185], v[98:101]
	v_mfma_f32_16x16x32_bf16 v[94:97], v[166:169], v[182:185], v[94:97]
	v_mfma_f32_16x16x32_bf16 v[86:89], v[152:155], v[190:193], v[86:89]
	v_mfma_f32_16x16x32_bf16 v[78:81], v[166:169], v[190:193], v[78:81]
	v_mfma_f32_16x16x32_bf16 v[70:73], v[152:155], v[198:201], v[70:73]
	v_mfma_f32_16x16x32_bf16 v[66:69], v[166:169], v[198:201], v[66:69]
	v_mfma_f32_16x16x32_bf16 v[110:113], v[162:165], v[178:181], v[110:113]
	v_mfma_f32_16x16x32_bf16 v[106:109], v[170:173], v[178:181], v[106:109]
	v_mfma_f32_16x16x32_bf16 v[98:101], v[162:165], v[186:189], v[98:101]
	v_mfma_f32_16x16x32_bf16 v[94:97], v[170:173], v[186:189], v[94:97]
	v_mfma_f32_16x16x32_bf16 v[86:89], v[162:165], v[194:197], v[86:89]
	v_mfma_f32_16x16x32_bf16 v[78:81], v[170:173], v[194:197], v[78:81]
	v_mfma_f32_16x16x32_bf16 v[70:73], v[162:165], v[202:205], v[70:73]
	v_mfma_f32_16x16x32_bf16 v[66:69], v[170:173], v[202:205], v[66:69]
	s_barrier
	s_add_i32 s71, s61, s45
	v_lshl_add_u64 v[206:207], s[34:35], 0, v[148:149]
	s_mov_b32 m0, s71
	ds_read_b128 v[174:177], v160 offset:16384
	ds_read_b128 v[178:181], v160 offset:17408
	ds_read_b128 v[182:185], v160 offset:18432
	ds_read_b128 v[186:189], v160 offset:19456
	ds_read_b128 v[190:193], v160 offset:20480
	ds_read_b128 v[194:197], v160 offset:21504
	ds_read_b128 v[198:201], v160 offset:22528
	ds_read_b128 v[202:205], v160 offset:23552
	global_load_lds_dwordx4 v[206:207], off
	s_add_i32 m0, s71, 0x2000
	s_add_u32 s72, s34, 0x40000
	v_lshl_add_u64 v[208:209], s[34:35], 0, v[146:147]
	s_addc_u32 s73, s35, 0
	s_add_i32 s71, s62, s45
	global_load_lds_dwordx4 v[208:209], off
	v_lshl_add_u64 v[210:211], s[72:73], 0, v[148:149]
	s_mov_b32 m0, s71
	v_lshl_add_u64 v[212:213], s[36:37], 0, v[146:147]
	global_load_lds_dwordx4 v[210:211], off
	v_lshl_add_u64 v[210:211], s[72:73], 0, v[146:147]
	s_add_i32 m0, s71, 0x2000
	s_nop 0
	global_load_lds_dwordx4 v[210:211], off
	v_lshl_add_u64 v[210:211], s[36:37], 0, v[148:149]
	s_mov_b32 m0, s49
	s_nop 0
	global_load_lds_dwordx4 v[210:211], off
	s_mov_b32 m0, s50
	s_nop 0
	global_load_lds_dwordx4 v[212:213], off
	s_waitcnt vmcnt(8)
	s_waitcnt lgkmcnt(0)
	s_barrier
; #define PG8_STAGE(bufoff, gbase, voff) do { _Pragma("unroll") for (int _i = 0; _i < 2; ++_i) \
;         __builtin_amdgcn_global_load_lds((const unsigned*)((const char*)(gbase) + (voff)[_i]), (PG8_LAS unsigned*)(lds + (bufoff) + ldsw + _i * 8192), 16, 0, 0); } while (0)
; #define PG8_LDA(dst, b, h) do { _Pragma("unroll") for (int m = 0; m < 4; ++m) _Pragma("unroll") for (int k = 0; k < 2; ++k) dst[m][k] = *(const PG8_LAS bf16x8*)(lds + PG8_SA(b, h) + aoff + m * 2048 + k * 1024); } while (0)
; #define PG8_LDB(dst, b, h) do { _Pragma("unroll") for (int n = 0; n < 2; ++n) _Pragma("unroll") for (int k = 0; k < 2; ++k) dst[n][k] = *(const PG8_LAS bf16x8*)(lds + PG8_SB(b, h) + boff + n * 2048 + k * 1024); } while (0)
; #define PG8_MMA(ai, bj, At, Bt) do { __builtin_amdgcn_s_setprio(1); _Pragma("unroll") for (int m = 0; m < 4; ++m) _Pragma("unroll") for (int n = 0; n < 2; ++n) _Pragma("unroll") for (int k = 0; k < 2; ++k) \
;         acc[ai][bj][m][n] = __builtin_amdgcn_mfma_f32_16x16x32_bf16(Bt[n][k], At[m][k], acc[ai][bj][m][n], 0, 0, 0); __builtin_amdgcn_s_setprio(0); } while (0)
; #define PG8_WAIT_V(n) asm volatile("s_waitcnt vmcnt(" #n ")" ::: "memory")
; #define PG8_WAIT_L(n) asm volatile("s_waitcnt lgkmcnt(" #n ")" ::: "memory")
; #define PG8_BAR __builtin_amdgcn_s_barrier()
; #define PG8_SCHED __builtin_amdgcn_sched_barrier(0)
; template <class Epi, class Sched, bool ALIGN_EPI = false, bool SP2 = false>
; __device__ __forceinline__ void gemm_phase(PG8_LAS unsigned char* lds, const Gemm g, const Sched& S, const Epi& E) {
;     ...
;             PG8_WAIT_V(8); PG8_WAIT_L(0); PG8_BAR; PG8_MMA(1, 0, At, B0); PG8_MMA(1, 1, At, B1); PG8_BAR; PG8_SCHED;
;             PG8_LDB(B0, 1, 0); PG8_LDB(B1, 1, 1); PG8_SCHED; PG8_LDA(At, 1, 0); PG8_STAGE(PG8_SA(0, 1), a2 + hstepA, voffA);
;             PG8_WAIT_V(8); PG8_WAIT_L(0); PG8_BAR; PG8_MMA(0, 0, At, B0); PG8_MMA(0, 1, At, B1); PG8_BAR; PG8_SCHED;
	v_mfma_f32_16x16x32_bf16 v[62:65], v[130:133], v[174:177], v[62:65]
	v_mfma_f32_16x16x32_bf16 v[58:61], v[138:141], v[174:177], v[58:61]
	v_mfma_f32_16x16x32_bf16 v[54:57], v[130:133], v[182:185], v[54:57]
	v_mfma_f32_16x16x32_bf16 v[50:53], v[138:141], v[182:185], v[50:53]
	v_mfma_f32_16x16x32_bf16 v[46:49], v[130:133], v[190:193], v[46:49]
	v_mfma_f32_16x16x32_bf16 v[38:41], v[138:141], v[190:193], v[38:41]
	v_mfma_f32_16x16x32_bf16 v[18:21], v[130:133], v[198:201], v[18:21]
	v_mfma_f32_16x16x32_bf16 v[10:13], v[138:141], v[198:201], v[10:13]
	v_mfma_f32_16x16x32_bf16 v[62:65], v[134:137], v[178:181], v[62:65]
	v_mfma_f32_16x16x32_bf16 v[58:61], v[142:145], v[178:181], v[58:61]
	v_mfma_f32_16x16x32_bf16 v[54:57], v[134:137], v[186:189], v[54:57]
	v_mfma_f32_16x16x32_bf16 v[50:53], v[142:145], v[186:189], v[50:53]
	v_mfma_f32_16x16x32_bf16 v[46:49], v[134:137], v[194:197], v[46:49]
	v_mfma_f32_16x16x32_bf16 v[38:41], v[142:145], v[194:197], v[38:41]
	v_mfma_f32_16x16x32_bf16 v[18:21], v[134:137], v[202:205], v[18:21]
	v_mfma_f32_16x16x32_bf16 v[10:13], v[142:145], v[202:205], v[10:13]
	v_mfma_f32_16x16x32_bf16 v[42:45], v[152:155], v[174:177], v[42:45]
	v_mfma_f32_16x16x32_bf16 v[34:37], v[166:169], v[174:177], v[34:37]
	v_mfma_f32_16x16x32_bf16 v[30:33], v[152:155], v[182:185], v[30:33]
	v_mfma_f32_16x16x32_bf16 v[26:29], v[166:169], v[182:185], v[26:29]
	v_mfma_f32_16x16x32_bf16 v[22:25], v[152:155], v[190:193], v[22:25]
	v_mfma_f32_16x16x32_bf16 v[14:17], v[166:169], v[190:193], v[14:17]
	v_mfma_f32_16x16x32_bf16 v[6:9], v[152:155], v[198:201], v[6:9]
	v_mfma_f32_16x16x32_bf16 v[2:5], v[166:169], v[198:201], v[2:5]
	v_mfma_f32_16x16x32_bf16 v[42:45], v[162:165], v[178:181], v[42:45]
	v_mfma_f32_16x16x32_bf16 v[34:37], v[170:173], v[178:181], v[34:37]
	v_mfma_f32_16x16x32_bf16 v[30:33], v[162:165], v[186:189], v[30:33]
	v_mfma_f32_16x16x32_bf16 v[26:29], v[170:173], v[186:189], v[26:29]
	v_mfma_f32_16x16x32_bf16 v[22:25], v[162:165], v[194:197], v[22:25]
	v_mfma_f32_16x16x32_bf16 v[14:17], v[170:173], v[194:197], v[14:17]
	v_mfma_f32_16x16x32_bf16 v[6:9], v[162:165], v[202:205], v[6:9]
	v_mfma_f32_16x16x32_bf16 v[2:5], v[170:173], v[202:205], v[2:5]
	s_barrier
	s_add_i32 s71, 0, 0x18000
	s_add_i32 s72, 0, 0x1c000
	v_add_u32_e32 v142, s71, v1
	v_add_u32_e32 v170, s72, v1
	ds_read_b128 v[130:133], v142
	ds_read_b128 v[134:137], v142 offset:1024
	ds_read_b128 v[138:141], v142 offset:2048
	ds_read_b128 v[142:145], v142 offset:3072
	ds_read_b128 v[152:155], v170
	ds_read_b128 v[162:165], v170 offset:1024
	ds_read_b128 v[166:169], v170 offset:2048
	ds_read_b128 v[170:173], v170 offset:3072
	s_add_u32 s36, s36, 0x40000
	s_addc_u32 s37, s37, 0
	s_mov_b32 m0, s51
	v_lshl_add_u64 v[214:215], s[36:37], 0, v[148:149]
	ds_read_b128 v[174:177], v160 offset:32768
	ds_read_b128 v[178:181], v160 offset:33792
	ds_read_b128 v[182:185], v160 offset:34816
	ds_read_b128 v[186:189], v160 offset:35840
	ds_read_b128 v[190:193], v160 offset:36864
	ds_read_b128 v[194:197], v160 offset:37888
	ds_read_b128 v[198:201], v160 offset:38912
	ds_read_b128 v[202:205], v160 offset:39936
	global_load_lds_dwordx4 v[214:215], off
	v_lshl_add_u64 v[214:215], s[36:37], 0, v[146:147]
	s_mov_b32 m0, s52
	s_nop 0
	global_load_lds_dwordx4 v[214:215], off
	s_waitcnt vmcnt(8)
	s_waitcnt lgkmcnt(0)
	s_barrier
	v_mfma_f32_16x16x32_bf16 v[126:129], v[130:133], v[174:177], v[126:129]
	v_mfma_f32_16x16x32_bf16 v[122:125], v[138:141], v[174:177], v[122:125]
	v_mfma_f32_16x16x32_bf16 v[118:121], v[130:133], v[182:185], v[118:121]
	v_mfma_f32_16x16x32_bf16 v[114:117], v[138:141], v[182:185], v[114:117]
	v_mfma_f32_16x16x32_bf16 v[102:105], v[130:133], v[190:193], v[102:105]
	v_mfma_f32_16x16x32_bf16 v[90:93], v[138:141], v[190:193], v[90:93]
	v_mfma_f32_16x16x32_bf16 v[82:85], v[130:133], v[198:201], v[82:85]
	v_mfma_f32_16x16x32_bf16 v[74:77], v[138:141], v[198:201], v[74:77]
	v_mfma_f32_16x16x32_bf16 v[126:129], v[134:137], v[178:181], v[126:129]
	v_mfma_f32_16x16x32_bf16 v[122:125], v[142:145], v[178:181], v[122:125]
	v_mfma_f32_16x16x32_bf16 v[118:121], v[134:137], v[186:189], v[118:121]
	v_mfma_f32_16x16x32_bf16 v[114:117], v[142:145], v[186:189], v[114:117]
	v_mfma_f32_16x16x32_bf16 v[102:105], v[134:137], v[194:197], v[102:105]
	v_mfma_f32_16x16x32_bf16 v[90:93], v[142:145], v[194:197], v[90:93]
	v_mfma_f32_16x16x32_bf16 v[82:85], v[134:137], v[202:205], v[82:85]
	v_mfma_f32_16x16x32_bf16 v[74:77], v[142:145], v[202:205], v[74:77]
	v_mfma_f32_16x16x32_bf16 v[110:113], v[152:155], v[174:177], v[110:113]
	v_mfma_f32_16x16x32_bf16 v[106:109], v[166:169], v[174:177], v[106:109]
	v_mfma_f32_16x16x32_bf16 v[98:101], v[152:155], v[182:185], v[98:101]
	v_mfma_f32_16x16x32_bf16 v[94:97], v[166:169], v[182:185], v[94:97]
	v_mfma_f32_16x16x32_bf16 v[86:89], v[152:155], v[190:193], v[86:89]
	v_mfma_f32_16x16x32_bf16 v[78:81], v[166:169], v[190:193], v[78:81]
	v_mfma_f32_16x16x32_bf16 v[70:73], v[152:155], v[198:201], v[70:73]
	v_mfma_f32_16x16x32_bf16 v[66:69], v[166:169], v[198:201], v[66:69]
	v_mfma_f32_16x16x32_bf16 v[110:113], v[162:165], v[178:181], v[110:113]
	v_mfma_f32_16x16x32_bf16 v[106:109], v[170:173], v[178:181], v[106:109]
	v_mfma_f32_16x16x32_bf16 v[98:101], v[162:165], v[186:189], v[98:101]
	v_mfma_f32_16x16x32_bf16 v[94:97], v[170:173], v[186:189], v[94:97]
	v_mfma_f32_16x16x32_bf16 v[86:89], v[162:165], v[194:197], v[86:89]
	v_mfma_f32_16x16x32_bf16 v[78:81], v[170:173], v[194:197], v[78:81]
	v_mfma_f32_16x16x32_bf16 v[70:73], v[162:165], v[202:205], v[70:73]
	v_mfma_f32_16x16x32_bf16 v[66:69], v[170:173], v[202:205], v[66:69]
	s_barrier
; #define PG8_STAGE(bufoff, gbase, voff) do { _Pragma("unroll") for (int _i = 0; _i < 2; ++_i) \
;         __builtin_amdgcn_global_load_lds((const unsigned*)((const char*)(gbase) + (voff)[_i]), (PG8_LAS unsigned*)(lds + (bufoff) + ldsw + _i * 8192), 16, 0, 0); } while (0)
; #define PG8_LDA(dst, b, h) do { _Pragma("unroll") for (int m = 0; m < 4; ++m) _Pragma("unroll") for (int k = 0; k < 2; ++k) dst[m][k] = *(const PG8_LAS bf16x8*)(lds + PG8_SA(b, h) + aoff + m * 2048 + k * 1024); } while (0)
; #define PG8_MMA(ai, bj, At, Bt) do { __builtin_amdgcn_s_setprio(1); _Pragma("unroll") for (int m = 0; m < 4; ++m) _Pragma("unroll") for (int n = 0; n < 2; ++n) _Pragma("unroll") for (int k = 0; k < 2; ++k) \
;         acc[ai][bj][m][n] = __builtin_amdgcn_mfma_f32_16x16x32_bf16(Bt[n][k], At[m][k], acc[ai][bj][m][n], 0, 0, 0); __builtin_amdgcn_s_setprio(0); } while (0)
; #define PG8_WAIT_V(n) asm volatile("s_waitcnt vmcnt(" #n ")" ::: "memory")
; #define PG8_WAIT_L(n) asm volatile("s_waitcnt lgkmcnt(" #n ")" ::: "memory")
; #define PG8_BAR __builtin_amdgcn_s_barrier()
; #define PG8_SCHED __builtin_amdgcn_sched_barrier(0)
; template <class Epi, class Sched, bool ALIGN_EPI = false, bool SP2 = false>
; __device__ __forceinline__ void gemm_phase(PG8_LAS unsigned char* lds, const Gemm g, const Sched& S, const Epi& E) {
;     ...
;         for (int t = 0; t < nt; t += 2) {
;     ...
;             PG8_LDA(At, 1, 1); PG8_STAGE(PG8_SB(1, 0), b3, voffB); PG8_STAGE(PG8_SB(1, 1), b3 + hstepB, voffB); PG8_STAGE(PG8_SA(1, 0), a3, voffA);
;             PG8_WAIT_V(8); PG8_WAIT_L(0); PG8_BAR; PG8_MMA(1, 0, At, B0); PG8_MMA(1, 1, At, B1); PG8_BAR; PG8_SCHED;
	s_add_i32 s36, s71, s45
	v_lshl_add_u64 v[206:207], v[206:207], 0, s[4:5]
	s_mov_b32 m0, s36
	ds_read_b128 v[174:177], v160 offset:49152
	ds_read_b128 v[178:181], v160 offset:50176
	ds_read_b128 v[182:185], v160 offset:51200
	ds_read_b128 v[186:189], v160 offset:52224
	ds_read_b128 v[190:193], v160 offset:53248
	ds_read_b128 v[194:197], v160 offset:54272
	ds_read_b128 v[198:201], v160 offset:55296
	ds_read_b128 v[202:205], v160 offset:56320
	global_load_lds_dwordx4 v[206:207], off
	s_add_i32 m0, s36, 0x2000
	s_add_u32 s34, s34, 0x40080
	v_lshl_add_u64 v[206:207], v[208:209], 0, s[4:5]
	s_addc_u32 s35, s35, 0
	s_add_i32 s36, s72, s45
	global_load_lds_dwordx4 v[206:207], off
	v_lshl_add_u64 v[206:207], s[34:35], 0, v[148:149]
	s_mov_b32 m0, s36
	s_nop 0
	global_load_lds_dwordx4 v[206:207], off
	v_lshl_add_u64 v[206:207], s[34:35], 0, v[146:147]
	s_add_i32 m0, s36, 0x2000
	s_nop 0
	global_load_lds_dwordx4 v[206:207], off
	v_lshl_add_u64 v[206:207], v[210:211], 0, s[4:5]
	s_mov_b32 m0, s59
	s_nop 0
	global_load_lds_dwordx4 v[206:207], off
	v_lshl_add_u64 v[206:207], v[212:213], 0, s[4:5]
	s_mov_b32 m0, s60
	s_nop 0
	global_load_lds_dwordx4 v[206:207], off
	s_waitcnt vmcnt(8)
	s_waitcnt lgkmcnt(0)
	s_barrier
	v_mfma_f32_16x16x32_bf16 v[62:65], v[130:133], v[174:177], v[62:65]
	v_mfma_f32_16x16x32_bf16 v[58:61], v[138:141], v[174:177], v[58:61]
	v_mfma_f32_16x16x32_bf16 v[54:57], v[130:133], v[182:185], v[54:57]
	v_mfma_f32_16x16x32_bf16 v[50:53], v[138:141], v[182:185], v[50:53]
	v_mfma_f32_16x16x32_bf16 v[46:49], v[130:133], v[190:193], v[46:49]
	v_mfma_f32_16x16x32_bf16 v[38:41], v[138:141], v[190:193], v[38:41]
	v_mfma_f32_16x16x32_bf16 v[18:21], v[130:133], v[198:201], v[18:21]
	v_mfma_f32_16x16x32_bf16 v[10:13], v[138:141], v[198:201], v[10:13]
	v_mfma_f32_16x16x32_bf16 v[62:65], v[134:137], v[178:181], v[62:65]
	v_mfma_f32_16x16x32_bf16 v[58:61], v[142:145], v[178:181], v[58:61]
	v_mfma_f32_16x16x32_bf16 v[54:57], v[134:137], v[186:189], v[54:57]
	v_mfma_f32_16x16x32_bf16 v[50:53], v[142:145], v[186:189], v[50:53]
	v_mfma_f32_16x16x32_bf16 v[46:49], v[134:137], v[194:197], v[46:49]
	v_mfma_f32_16x16x32_bf16 v[38:41], v[142:145], v[194:197], v[38:41]
	v_mfma_f32_16x16x32_bf16 v[18:21], v[134:137], v[202:205], v[18:21]
	v_mfma_f32_16x16x32_bf16 v[10:13], v[142:145], v[202:205], v[10:13]
	v_mfma_f32_16x16x32_bf16 v[42:45], v[152:155], v[174:177], v[42:45]
	v_mfma_f32_16x16x32_bf16 v[34:37], v[166:169], v[174:177], v[34:37]
	v_mfma_f32_16x16x32_bf16 v[30:33], v[152:155], v[182:185], v[30:33]
	v_mfma_f32_16x16x32_bf16 v[26:29], v[166:169], v[182:185], v[26:29]
	v_mfma_f32_16x16x32_bf16 v[22:25], v[152:155], v[190:193], v[22:25]
	v_mfma_f32_16x16x32_bf16 v[14:17], v[166:169], v[190:193], v[14:17]
	v_mfma_f32_16x16x32_bf16 v[6:9], v[152:155], v[198:201], v[6:9]
	v_mfma_f32_16x16x32_bf16 v[2:5], v[166:169], v[198:201], v[2:5]
	v_mfma_f32_16x16x32_bf16 v[42:45], v[162:165], v[178:181], v[42:45]
	v_mfma_f32_16x16x32_bf16 v[34:37], v[170:173], v[178:181], v[34:37]
	v_mfma_f32_16x16x32_bf16 v[30:33], v[162:165], v[186:189], v[30:33]
	v_mfma_f32_16x16x32_bf16 v[26:29], v[170:173], v[186:189], v[26:29]
	v_mfma_f32_16x16x32_bf16 v[22:25], v[162:165], v[194:197], v[22:25]
	v_mfma_f32_16x16x32_bf16 v[14:17], v[170:173], v[194:197], v[14:17]
	v_mfma_f32_16x16x32_bf16 v[6:9], v[162:165], v[202:205], v[6:9]
	v_mfma_f32_16x16x32_bf16 v[2:5], v[170:173], v[202:205], v[2:5]
	s_barrier
	s_movk_i32 s71, 0x100
	s_and_b64 vcc, exec, s[30:31]
	s_mov_b64 s[34:35], -1
	s_mov_b64 s[30:31], 0
	s_cbranch_vccnz .LBB0_1344
	s_andn2_b64 vcc, exec, s[8:9]
	s_cbranch_vccnz .LBB0_1347
	s_barrier

; #define PG8_STAGE(bufoff, gbase, voff) do { _Pragma("unroll") for (int _i = 0; _i < 2; ++_i) \
;         __builtin_amdgcn_global_load_lds((const unsigned*)((const char*)(gbase) + (voff)[_i]), (PG8_LAS unsigned*)(lds + (bufoff) + ldsw + _i * 8192), 16, 0, 0); } while (0)
; #define PG8_LDA(dst, b, h) do { _Pragma("unroll") for (int m = 0; m < 4; ++m) _Pragma("unroll") for (int k = 0; k < 2; ++k) dst[m][k] = *(const PG8_LAS bf16x8*)(lds + PG8_SA(b, h) + aoff + m * 2048 + k * 1024); } while (0)
; #define PG8_LDB(dst, b, h) do { _Pragma("unroll") for (int n = 0; n < 2; ++n) _Pragma("unroll") for (int k = 0; k < 2; ++k) dst[n][k] = *(const PG8_LAS bf16x8*)(lds + PG8_SB(b, h) + boff + n * 2048 + k * 1024); } while (0)
; #define PG8_MMA(ai, bj, At, Bt) do { __builtin_amdgcn_s_setprio(1); _Pragma("unroll") for (int m = 0; m < 4; ++m) _Pragma("unroll") for (int n = 0; n < 2; ++n) _Pragma("unroll") for (int k = 0; k < 2; ++k) \
;         acc[ai][bj][m][n] = __builtin_amdgcn_mfma_f32_16x16x32_bf16(Bt[n][k], At[m][k], acc[ai][bj][m][n], 0, 0, 0); __builtin_amdgcn_s_setprio(0); } while (0)
; #define PG8_WAIT_V(n) asm volatile("s_waitcnt vmcnt(" #n ")" ::: "memory")
; #define PG8_WAIT_L(n) asm volatile("s_waitcnt lgkmcnt(" #n ")" ::: "memory")
; template <class Epi, class Sched, bool ALIGN_EPI = false, bool SP2 = false>
; __device__ __forceinline__ void gemm_phase(PG8_LAS unsigned char* lds, const Gemm g, const Sched& S, const Epi& E) {
;     ...
;             const bool last = (t == nt - 2);
;             const char* a1 = cA + (size_t)(t + 1) * kstep;
;             const char* a2 = last ? nA : cA + (size_t)(t + 2) * kstep; const char* b2 = last ? nB : cB + (size_t)(t + 2) * kstep;
;             const char* a3 = a2 + kstep; const char* b3 = b2 + kstep;
;             if (last && has_next) S.a_ready(nxt);
;             if constexpr (SP2) {
;             PG8_LDB(B0, 0, 0); PG8_LDB(B1, 0, 1); PG8_SCHED; PG8_LDA(At, 0, 0); PG8_STAGE(PG8_SA(1, 1), a1 + hstepA, voffA);
;             PG8_WAIT_V(8); PG8_WAIT_L(0); PG8_BAR; PG8_MMA(0, 0, At, B0); PG8_MMA(0, 1, At, B1); PG8_BAR; PG8_SCHED;
;             PG8_LDA(At, 0, 1); PG8_STAGE(PG8_SB(0, 0), b2, voffB); PG8_STAGE(PG8_SB(0, 1), b2 + hstepB, voffB); PG8_STAGE(PG8_SA(0, 0), a2, voffA);
;             PG8_WAIT_V(8); PG8_WAIT_L(0); PG8_BAR; PG8_MMA(1, 0, At, B0); PG8_MMA(1, 1, At, B1); PG8_BAR; PG8_SCHED;
.LBB0_1364:
	s_add_u32 s73, s28, s72
	ds_read_b128 v[130:133], v158
	ds_read_b128 v[134:137], v158 offset:1024
	ds_read_b128 v[138:141], v158 offset:2048
	ds_read_b128 v[142:145], v158 offset:3072
	ds_read_b128 v[152:155], v159
	ds_read_b128 v[162:165], v159 offset:1024
	ds_read_b128 v[166:169], v159 offset:2048
	ds_read_b128 v[170:173], v159 offset:3072
	s_addc_u32 s74, s29, 0
	s_add_u32 s75, s73, 0x100
	s_addc_u32 s76, s74, 0
	s_and_b64 s[36:37], s[34:35], exec
	s_cselect_b32 s37, s17, s76
	s_cselect_b32 s36, s70, s75
	s_add_u32 s72, s26, s72
	s_addc_u32 s75, s27, 0
	s_add_u32 s72, s72, 0x100
	s_addc_u32 s75, s75, 0
	s_and_b64 s[34:35], s[34:35], exec
	s_cselect_b32 s35, s15, s75
	s_cselect_b32 s34, s71, s72
	s_add_u32 s72, s73, 0x40080
	s_addc_u32 s73, s74, 0
	v_lshl_add_u64 v[206:207], s[72:73], 0, v[148:149]
	s_add_i32 m0, s50, 0xc000
	ds_read_b128 v[174:177], v160
	ds_read_b128 v[178:181], v160 offset:1024
	ds_read_b128 v[182:185], v160 offset:2048
	ds_read_b128 v[186:189], v160 offset:3072
	ds_read_b128 v[190:193], v160 offset:4096
	ds_read_b128 v[194:197], v160 offset:5120
	ds_read_b128 v[198:201], v160 offset:6144
	ds_read_b128 v[202:205], v160 offset:7168
	global_load_lds_dwordx4 v[206:207], off
	v_lshl_add_u64 v[206:207], s[72:73], 0, v[146:147]
	s_add_i32 m0, s50, 0xe000
	s_nop 0
	global_load_lds_dwordx4 v[206:207], off
	s_waitcnt vmcnt(8)
	s_waitcnt lgkmcnt(0)
	s_barrier
	v_mfma_f32_16x16x32_bf16 v[126:129], v[130:133], v[174:177], v[126:129]
	v_mfma_f32_16x16x32_bf16 v[122:125], v[138:141], v[174:177], v[122:125]
	v_mfma_f32_16x16x32_bf16 v[118:121], v[130:133], v[182:185], v[118:121]
	v_mfma_f32_16x16x32_bf16 v[114:117], v[138:141], v[182:185], v[114:117]
	v_mfma_f32_16x16x32_bf16 v[102:105], v[130:133], v[190:193], v[102:105]
	v_mfma_f32_16x16x32_bf16 v[90:93], v[138:141], v[190:193], v[90:93]
	v_mfma_f32_16x16x32_bf16 v[82:85], v[130:133], v[198:201], v[82:85]
	v_mfma_f32_16x16x32_bf16 v[74:77], v[138:141], v[198:201], v[74:77]
	v_mfma_f32_16x16x32_bf16 v[126:129], v[134:137], v[178:181], v[126:129]
	v_mfma_f32_16x16x32_bf16 v[122:125], v[142:145], v[178:181], v[122:125]
	v_mfma_f32_16x16x32_bf16 v[118:121], v[134:137], v[186:189], v[118:121]
	v_mfma_f32_16x16x32_bf16 v[114:117], v[142:145], v[186:189], v[114:117]
	v_mfma_f32_16x16x32_bf16 v[102:105], v[134:137], v[194:197], v[102:105]
	v_mfma_f32_16x16x32_bf16 v[90:93], v[142:145], v[194:197], v[90:93]
	v_mfma_f32_16x16x32_bf16 v[82:85], v[134:137], v[202:205], v[82:85]
	v_mfma_f32_16x16x32_bf16 v[74:77], v[142:145], v[202:205], v[74:77]
	v_mfma_f32_16x16x32_bf16 v[110:113], v[152:155], v[174:177], v[110:113]
	v_mfma_f32_16x16x32_bf16 v[106:109], v[166:169], v[174:177], v[106:109]
	v_mfma_f32_16x16x32_bf16 v[98:101], v[152:155], v[182:185], v[98:101]
	v_mfma_f32_16x16x32_bf16 v[94:97], v[166:169], v[182:185], v[94:97]
	v_mfma_f32_16x16x32_bf16 v[86:89], v[152:155], v[190:193], v[86:89]
	v_mfma_f32_16x16x32_bf16 v[78:81], v[166:169], v[190:193], v[78:81]
	v_mfma_f32_16x16x32_bf16 v[70:73], v[152:155], v[198:201], v[70:73]
	v_mfma_f32_16x16x32_bf16 v[66:69], v[166:169], v[198:201], v[66:69]
	v_mfma_f32_16x16x32_bf16 v[110:113], v[162:165], v[178:181], v[110:113]
	v_mfma_f32_16x16x32_bf16 v[106:109], v[170:173], v[178:181], v[106:109]
	v_mfma_f32_16x16x32_bf16 v[98:101], v[162:165], v[186:189], v[98:101]
	v_mfma_f32_16x16x32_bf16 v[94:97], v[170:173], v[186:189], v[94:97]
	v_mfma_f32_16x16x32_bf16 v[86:89], v[162:165], v[194:197], v[86:89]
	v_mfma_f32_16x16x32_bf16 v[78:81], v[170:173], v[194:197], v[78:81]
	v_mfma_f32_16x16x32_bf16 v[70:73], v[162:165], v[202:205], v[70:73]
	v_mfma_f32_16x16x32_bf16 v[66:69], v[170:173], v[202:205], v[66:69]
	s_barrier
	s_add_i32 s72, s62, s48
	v_lshl_add_u64 v[206:207], s[34:35], 0, v[148:149]
	s_mov_b32 m0, s72
	ds_read_b128 v[174:177], v160 offset:16384
	ds_read_b128 v[178:181], v160 offset:17408
	ds_read_b128 v[182:185], v160 offset:18432
	ds_read_b128 v[186:189], v160 offset:19456
	ds_read_b128 v[190:193], v160 offset:20480
	ds_read_b128 v[194:197], v160 offset:21504
	ds_read_b128 v[198:201], v160 offset:22528
	ds_read_b128 v[202:205], v160 offset:23552
	global_load_lds_dwordx4 v[206:207], off
	s_add_i32 m0, s72, 0x2000
	s_add_u32 s72, s34, 0x40000
	v_lshl_add_u64 v[208:209], s[34:35], 0, v[146:147]
	s_addc_u32 s73, s35, 0
	s_add_i32 s74, s63, s48
	global_load_lds_dwordx4 v[208:209], off
	v_lshl_add_u64 v[210:211], s[72:73], 0, v[148:149]
	s_mov_b32 m0, s74
	v_lshl_add_u64 v[212:213], s[36:37], 0, v[146:147]
	global_load_lds_dwordx4 v[210:211], off
	v_lshl_add_u64 v[210:211], s[72:73], 0, v[146:147]
	s_add_i32 m0, s74, 0x2000
	s_nop 0
	global_load_lds_dwordx4 v[210:211], off
	v_lshl_add_u64 v[210:211], s[36:37], 0, v[148:149]
	s_mov_b32 m0, s50
	s_nop 0
	global_load_lds_dwordx4 v[210:211], off
	s_mov_b32 m0, s51
	s_nop 0
	global_load_lds_dwordx4 v[212:213], off
	s_waitcnt vmcnt(8)
	s_waitcnt lgkmcnt(0)
	s_barrier
; #define PG8_STAGE(bufoff, gbase, voff) do { _Pragma("unroll") for (int _i = 0; _i < 2; ++_i) \
;         __builtin_amdgcn_global_load_lds((const unsigned*)((const char*)(gbase) + (voff)[_i]), (PG8_LAS unsigned*)(lds + (bufoff) + ldsw + _i * 8192), 16, 0, 0); } while (0)
; #define PG8_LDA(dst, b, h) do { _Pragma("unroll") for (int m = 0; m < 4; ++m) _Pragma("unroll") for (int k = 0; k < 2; ++k) dst[m][k] = *(const PG8_LAS bf16x8*)(lds + PG8_SA(b, h) + aoff + m * 2048 + k * 1024); } while (0)
; #define PG8_LDB(dst, b, h) do { _Pragma("unroll") for (int n = 0; n < 2; ++n) _Pragma("unroll") for (int k = 0; k < 2; ++k) dst[n][k] = *(const PG8_LAS bf16x8*)(lds + PG8_SB(b, h) + boff + n * 2048 + k * 1024); } while (0)
; #define PG8_MMA(ai, bj, At, Bt) do { __builtin_amdgcn_s_setprio(1); _Pragma("unroll") for (int m = 0; m < 4; ++m) _Pragma("unroll") for (int n = 0; n < 2; ++n) _Pragma("unroll") for (int k = 0; k < 2; ++k) \
;         acc[ai][bj][m][n] = __builtin_amdgcn_mfma_f32_16x16x32_bf16(Bt[n][k], At[m][k], acc[ai][bj][m][n], 0, 0, 0); __builtin_amdgcn_s_setprio(0); } while (0)
; #define PG8_WAIT_V(n) asm volatile("s_waitcnt vmcnt(" #n ")" ::: "memory")
; #define PG8_WAIT_L(n) asm volatile("s_waitcnt lgkmcnt(" #n ")" ::: "memory")
; #define PG8_BAR __builtin_amdgcn_s_barrier()
; #define PG8_SCHED __builtin_amdgcn_sched_barrier(0)
; template <class Epi, class Sched, bool ALIGN_EPI = false, bool SP2 = false>
; __device__ __forceinline__ void gemm_phase(PG8_LAS unsigned char* lds, const Gemm g, const Sched& S, const Epi& E) {
;     ...
;             PG8_WAIT_V(8); PG8_WAIT_L(0); PG8_BAR; PG8_MMA(1, 0, At, B0); PG8_MMA(1, 1, At, B1); PG8_BAR; PG8_SCHED;
;             PG8_LDB(B0, 1, 0); PG8_LDB(B1, 1, 1); PG8_SCHED; PG8_LDA(At, 1, 0); PG8_STAGE(PG8_SA(0, 1), a2 + hstepA, voffA);
;             PG8_WAIT_V(8); PG8_WAIT_L(0); PG8_BAR; PG8_MMA(0, 0, At, B0); PG8_MMA(0, 1, At, B1); PG8_BAR; PG8_SCHED;
	v_mfma_f32_16x16x32_bf16 v[62:65], v[130:133], v[174:177], v[62:65]
	v_mfma_f32_16x16x32_bf16 v[58:61], v[138:141], v[174:177], v[58:61]
	v_mfma_f32_16x16x32_bf16 v[54:57], v[130:133], v[182:185], v[54:57]
	v_mfma_f32_16x16x32_bf16 v[50:53], v[138:141], v[182:185], v[50:53]
	v_mfma_f32_16x16x32_bf16 v[46:49], v[130:133], v[190:193], v[46:49]
	v_mfma_f32_16x16x32_bf16 v[38:41], v[138:141], v[190:193], v[38:41]
	v_mfma_f32_16x16x32_bf16 v[18:21], v[130:133], v[198:201], v[18:21]
	v_mfma_f32_16x16x32_bf16 v[10:13], v[138:141], v[198:201], v[10:13]
	v_mfma_f32_16x16x32_bf16 v[62:65], v[134:137], v[178:181], v[62:65]
	v_mfma_f32_16x16x32_bf16 v[58:61], v[142:145], v[178:181], v[58:61]
	v_mfma_f32_16x16x32_bf16 v[54:57], v[134:137], v[186:189], v[54:57]
	v_mfma_f32_16x16x32_bf16 v[50:53], v[142:145], v[186:189], v[50:53]
	v_mfma_f32_16x16x32_bf16 v[46:49], v[134:137], v[194:197], v[46:49]
	v_mfma_f32_16x16x32_bf16 v[38:41], v[142:145], v[194:197], v[38:41]
	v_mfma_f32_16x16x32_bf16 v[18:21], v[134:137], v[202:205], v[18:21]
	v_mfma_f32_16x16x32_bf16 v[10:13], v[142:145], v[202:205], v[10:13]
	v_mfma_f32_16x16x32_bf16 v[42:45], v[152:155], v[174:177], v[42:45]
	v_mfma_f32_16x16x32_bf16 v[34:37], v[166:169], v[174:177], v[34:37]
	v_mfma_f32_16x16x32_bf16 v[30:33], v[152:155], v[182:185], v[30:33]
	v_mfma_f32_16x16x32_bf16 v[26:29], v[166:169], v[182:185], v[26:29]
	v_mfma_f32_16x16x32_bf16 v[22:25], v[152:155], v[190:193], v[22:25]
	v_mfma_f32_16x16x32_bf16 v[14:17], v[166:169], v[190:193], v[14:17]
	v_mfma_f32_16x16x32_bf16 v[6:9], v[152:155], v[198:201], v[6:9]
	v_mfma_f32_16x16x32_bf16 v[2:5], v[166:169], v[198:201], v[2:5]
	v_mfma_f32_16x16x32_bf16 v[42:45], v[162:165], v[178:181], v[42:45]
	v_mfma_f32_16x16x32_bf16 v[34:37], v[170:173], v[178:181], v[34:37]
	v_mfma_f32_16x16x32_bf16 v[30:33], v[162:165], v[186:189], v[30:33]
	v_mfma_f32_16x16x32_bf16 v[26:29], v[170:173], v[186:189], v[26:29]
	v_mfma_f32_16x16x32_bf16 v[22:25], v[162:165], v[194:197], v[22:25]
	v_mfma_f32_16x16x32_bf16 v[14:17], v[170:173], v[194:197], v[14:17]
	v_mfma_f32_16x16x32_bf16 v[6:9], v[162:165], v[202:205], v[6:9]
	v_mfma_f32_16x16x32_bf16 v[2:5], v[170:173], v[202:205], v[2:5]
	s_barrier
	s_add_i32 s72, 0, 0x18000
	s_add_i32 s73, 0, 0x1c000
	v_add_u32_e32 v142, s72, v1
	v_add_u32_e32 v170, s73, v1
	ds_read_b128 v[130:133], v142
	ds_read_b128 v[134:137], v142 offset:1024
	ds_read_b128 v[138:141], v142 offset:2048
	ds_read_b128 v[142:145], v142 offset:3072
	ds_read_b128 v[152:155], v170
	ds_read_b128 v[162:165], v170 offset:1024
	ds_read_b128 v[166:169], v170 offset:2048
	ds_read_b128 v[170:173], v170 offset:3072
	s_add_u32 s36, s36, 0x40000
	s_addc_u32 s37, s37, 0
	s_mov_b32 m0, s52
	v_lshl_add_u64 v[214:215], s[36:37], 0, v[148:149]
	ds_read_b128 v[174:177], v160 offset:32768
	ds_read_b128 v[178:181], v160 offset:33792
	ds_read_b128 v[182:185], v160 offset:34816
	ds_read_b128 v[186:189], v160 offset:35840
	ds_read_b128 v[190:193], v160 offset:36864
	ds_read_b128 v[194:197], v160 offset:37888
	ds_read_b128 v[198:201], v160 offset:38912
	ds_read_b128 v[202:205], v160 offset:39936
	global_load_lds_dwordx4 v[214:215], off
	v_lshl_add_u64 v[214:215], s[36:37], 0, v[146:147]
	s_mov_b32 m0, s53
	s_nop 0
	global_load_lds_dwordx4 v[214:215], off
	s_waitcnt vmcnt(8)
	s_waitcnt lgkmcnt(0)
	s_barrier
	v_mfma_f32_16x16x32_bf16 v[126:129], v[130:133], v[174:177], v[126:129]
	v_mfma_f32_16x16x32_bf16 v[122:125], v[138:141], v[174:177], v[122:125]
	v_mfma_f32_16x16x32_bf16 v[118:121], v[130:133], v[182:185], v[118:121]
	v_mfma_f32_16x16x32_bf16 v[114:117], v[138:141], v[182:185], v[114:117]
	v_mfma_f32_16x16x32_bf16 v[102:105], v[130:133], v[190:193], v[102:105]
	v_mfma_f32_16x16x32_bf16 v[90:93], v[138:141], v[190:193], v[90:93]
	v_mfma_f32_16x16x32_bf16 v[82:85], v[130:133], v[198:201], v[82:85]
	v_mfma_f32_16x16x32_bf16 v[74:77], v[138:141], v[198:201], v[74:77]
	v_mfma_f32_16x16x32_bf16 v[126:129], v[134:137], v[178:181], v[126:129]
	v_mfma_f32_16x16x32_bf16 v[122:125], v[142:145], v[178:181], v[122:125]
	v_mfma_f32_16x16x32_bf16 v[118:121], v[134:137], v[186:189], v[118:121]
	v_mfma_f32_16x16x32_bf16 v[114:117], v[142:145], v[186:189], v[114:117]
	v_mfma_f32_16x16x32_bf16 v[102:105], v[134:137], v[194:197], v[102:105]
	v_mfma_f32_16x16x32_bf16 v[90:93], v[142:145], v[194:197], v[90:93]
	v_mfma_f32_16x16x32_bf16 v[82:85], v[134:137], v[202:205], v[82:85]
	v_mfma_f32_16x16x32_bf16 v[74:77], v[142:145], v[202:205], v[74:77]
	v_mfma_f32_16x16x32_bf16 v[110:113], v[152:155], v[174:177], v[110:113]
	v_mfma_f32_16x16x32_bf16 v[106:109], v[166:169], v[174:177], v[106:109]
	v_mfma_f32_16x16x32_bf16 v[98:101], v[152:155], v[182:185], v[98:101]
	v_mfma_f32_16x16x32_bf16 v[94:97], v[166:169], v[182:185], v[94:97]
	v_mfma_f32_16x16x32_bf16 v[86:89], v[152:155], v[190:193], v[86:89]
	v_mfma_f32_16x16x32_bf16 v[78:81], v[166:169], v[190:193], v[78:81]
	v_mfma_f32_16x16x32_bf16 v[70:73], v[152:155], v[198:201], v[70:73]
	v_mfma_f32_16x16x32_bf16 v[66:69], v[166:169], v[198:201], v[66:69]
	v_mfma_f32_16x16x32_bf16 v[110:113], v[162:165], v[178:181], v[110:113]
	v_mfma_f32_16x16x32_bf16 v[106:109], v[170:173], v[178:181], v[106:109]
	v_mfma_f32_16x16x32_bf16 v[98:101], v[162:165], v[186:189], v[98:101]
	v_mfma_f32_16x16x32_bf16 v[94:97], v[170:173], v[186:189], v[94:97]
	v_mfma_f32_16x16x32_bf16 v[86:89], v[162:165], v[194:197], v[86:89]
	v_mfma_f32_16x16x32_bf16 v[78:81], v[170:173], v[194:197], v[78:81]
	v_mfma_f32_16x16x32_bf16 v[70:73], v[162:165], v[202:205], v[70:73]
	v_mfma_f32_16x16x32_bf16 v[66:69], v[170:173], v[202:205], v[66:69]
	s_barrier
; #define PG8_STAGE(bufoff, gbase, voff) do { _Pragma("unroll") for (int _i = 0; _i < 2; ++_i) \
;         __builtin_amdgcn_global_load_lds((const unsigned*)((const char*)(gbase) + (voff)[_i]), (PG8_LAS unsigned*)(lds + (bufoff) + ldsw + _i * 8192), 16, 0, 0); } while (0)
; #define PG8_LDA(dst, b, h) do { _Pragma("unroll") for (int m = 0; m < 4; ++m) _Pragma("unroll") for (int k = 0; k < 2; ++k) dst[m][k] = *(const PG8_LAS bf16x8*)(lds + PG8_SA(b, h) + aoff + m * 2048 + k * 1024); } while (0)
; #define PG8_MMA(ai, bj, At, Bt) do { __builtin_amdgcn_s_setprio(1); _Pragma("unroll") for (int m = 0; m < 4; ++m) _Pragma("unroll") for (int n = 0; n < 2; ++n) _Pragma("unroll") for (int k = 0; k < 2; ++k) \
;         acc[ai][bj][m][n] = __builtin_amdgcn_mfma_f32_16x16x32_bf16(Bt[n][k], At[m][k], acc[ai][bj][m][n], 0, 0, 0); __builtin_amdgcn_s_setprio(0); } while (0)
; #define PG8_WAIT_V(n) asm volatile("s_waitcnt vmcnt(" #n ")" ::: "memory")
; #define PG8_WAIT_L(n) asm volatile("s_waitcnt lgkmcnt(" #n ")" ::: "memory")
; #define PG8_BAR __builtin_amdgcn_s_barrier()
; #define PG8_SCHED __builtin_amdgcn_sched_barrier(0)
; template <class Epi, class Sched, bool ALIGN_EPI = false, bool SP2 = false>
; __device__ __forceinline__ void gemm_phase(PG8_LAS unsigned char* lds, const Gemm g, const Sched& S, const Epi& E) {
;     ...
;         for (int t = 0; t < nt; t += 2) {
;     ...
;             PG8_LDA(At, 1, 1); PG8_STAGE(PG8_SB(1, 0), b3, voffB); PG8_STAGE(PG8_SB(1, 1), b3 + hstepB, voffB); PG8_STAGE(PG8_SA(1, 0), a3, voffA);
;             PG8_WAIT_V(8); PG8_WAIT_L(0); PG8_BAR; PG8_MMA(1, 0, At, B0); PG8_MMA(1, 1, At, B1); PG8_BAR; PG8_SCHED;
	s_add_i32 s36, s72, s48
	v_lshl_add_u64 v[206:207], v[206:207], 0, s[4:5]
	s_mov_b32 m0, s36
	ds_read_b128 v[174:177], v160 offset:49152
	ds_read_b128 v[178:181], v160 offset:50176
	ds_read_b128 v[182:185], v160 offset:51200
	ds_read_b128 v[186:189], v160 offset:52224
	ds_read_b128 v[190:193], v160 offset:53248
	ds_read_b128 v[194:197], v160 offset:54272
	ds_read_b128 v[198:201], v160 offset:55296
	ds_read_b128 v[202:205], v160 offset:56320
	global_load_lds_dwordx4 v[206:207], off
	s_add_i32 m0, s36, 0x2000
	s_add_u32 s34, s34, 0x40080
	v_lshl_add_u64 v[206:207], v[208:209], 0, s[4:5]
	s_addc_u32 s35, s35, 0
	s_add_i32 s36, s73, s48
	global_load_lds_dwordx4 v[206:207], off
	v_lshl_add_u64 v[206:207], s[34:35], 0, v[148:149]
	s_mov_b32 m0, s36
	s_nop 0
	global_load_lds_dwordx4 v[206:207], off
	v_lshl_add_u64 v[206:207], s[34:35], 0, v[146:147]
	s_add_i32 m0, s36, 0x2000
	s_nop 0
	global_load_lds_dwordx4 v[206:207], off
	v_lshl_add_u64 v[206:207], v[210:211], 0, s[4:5]
	s_mov_b32 m0, s59
	s_nop 0
	global_load_lds_dwordx4 v[206:207], off
	v_lshl_add_u64 v[206:207], v[212:213], 0, s[4:5]
	s_mov_b32 m0, s60
	s_nop 0
	global_load_lds_dwordx4 v[206:207], off
	s_waitcnt vmcnt(8)
	s_waitcnt lgkmcnt(0)
	s_barrier
	v_mfma_f32_16x16x32_bf16 v[62:65], v[130:133], v[174:177], v[62:65]
	v_mfma_f32_16x16x32_bf16 v[58:61], v[138:141], v[174:177], v[58:61]
	v_mfma_f32_16x16x32_bf16 v[54:57], v[130:133], v[182:185], v[54:57]
	v_mfma_f32_16x16x32_bf16 v[50:53], v[138:141], v[182:185], v[50:53]
	v_mfma_f32_16x16x32_bf16 v[46:49], v[130:133], v[190:193], v[46:49]
	v_mfma_f32_16x16x32_bf16 v[38:41], v[138:141], v[190:193], v[38:41]
	v_mfma_f32_16x16x32_bf16 v[18:21], v[130:133], v[198:201], v[18:21]
	v_mfma_f32_16x16x32_bf16 v[10:13], v[138:141], v[198:201], v[10:13]
	v_mfma_f32_16x16x32_bf16 v[62:65], v[134:137], v[178:181], v[62:65]
	v_mfma_f32_16x16x32_bf16 v[58:61], v[142:145], v[178:181], v[58:61]
	v_mfma_f32_16x16x32_bf16 v[54:57], v[134:137], v[186:189], v[54:57]
	v_mfma_f32_16x16x32_bf16 v[50:53], v[142:145], v[186:189], v[50:53]
	v_mfma_f32_16x16x32_bf16 v[46:49], v[134:137], v[194:197], v[46:49]
	v_mfma_f32_16x16x32_bf16 v[38:41], v[142:145], v[194:197], v[38:41]
	v_mfma_f32_16x16x32_bf16 v[18:21], v[134:137], v[202:205], v[18:21]
	v_mfma_f32_16x16x32_bf16 v[10:13], v[142:145], v[202:205], v[10:13]
	v_mfma_f32_16x16x32_bf16 v[42:45], v[152:155], v[174:177], v[42:45]
	v_mfma_f32_16x16x32_bf16 v[34:37], v[166:169], v[174:177], v[34:37]
	v_mfma_f32_16x16x32_bf16 v[30:33], v[152:155], v[182:185], v[30:33]
	v_mfma_f32_16x16x32_bf16 v[26:29], v[166:169], v[182:185], v[26:29]
	v_mfma_f32_16x16x32_bf16 v[22:25], v[152:155], v[190:193], v[22:25]
	v_mfma_f32_16x16x32_bf16 v[14:17], v[166:169], v[190:193], v[14:17]
	v_mfma_f32_16x16x32_bf16 v[6:9], v[152:155], v[198:201], v[6:9]
	v_mfma_f32_16x16x32_bf16 v[2:5], v[166:169], v[198:201], v[2:5]
	v_mfma_f32_16x16x32_bf16 v[42:45], v[162:165], v[178:181], v[42:45]
	v_mfma_f32_16x16x32_bf16 v[34:37], v[170:173], v[178:181], v[34:37]
	v_mfma_f32_16x16x32_bf16 v[30:33], v[162:165], v[186:189], v[30:33]
	v_mfma_f32_16x16x32_bf16 v[26:29], v[170:173], v[186:189], v[26:29]
	v_mfma_f32_16x16x32_bf16 v[22:25], v[162:165], v[194:197], v[22:25]
	v_mfma_f32_16x16x32_bf16 v[14:17], v[170:173], v[194:197], v[14:17]
	v_mfma_f32_16x16x32_bf16 v[6:9], v[162:165], v[202:205], v[6:9]
	v_mfma_f32_16x16x32_bf16 v[2:5], v[170:173], v[202:205], v[2:5]
	s_barrier
	s_movk_i32 s72, 0x100
	s_and_b64 vcc, exec, s[30:31]
	s_mov_b64 s[34:35], -1
	s_mov_b64 s[30:31], 0
	s_cbranch_vccnz .LBB0_1364
	s_andn2_b64 vcc, exec, s[8:9]
	s_cbranch_vccnz .LBB0_1367
	s_barrier

; #define PG8_STAGE(bufoff, gbase, voff) do { _Pragma("unroll") for (int _i = 0; _i < 2; ++_i) \
;         __builtin_amdgcn_global_load_lds((const unsigned*)((const char*)(gbase) + (voff)[_i]), (PG8_LAS unsigned*)(lds + (bufoff) + ldsw + _i * 8192), 16, 0, 0); } while (0)
; #define PG8_LDA(dst, b, h) do { _Pragma("unroll") for (int m = 0; m < 4; ++m) _Pragma("unroll") for (int k = 0; k < 2; ++k) dst[m][k] = *(const PG8_LAS bf16x8*)(lds + PG8_SA(b, h) + aoff + m * 2048 + k * 1024); } while (0)
; #define PG8_LDB(dst, b, h) do { _Pragma("unroll") for (int n = 0; n < 2; ++n) _Pragma("unroll") for (int k = 0; k < 2; ++k) dst[n][k] = *(const PG8_LAS bf16x8*)(lds + PG8_SB(b, h) + boff + n * 2048 + k * 1024); } while (0)
; #define PG8_MMA(ai, bj, At, Bt) do { __builtin_amdgcn_s_setprio(1); _Pragma("unroll") for (int m = 0; m < 4; ++m) _Pragma("unroll") for (int n = 0; n < 2; ++n) _Pragma("unroll") for (int k = 0; k < 2; ++k) \
;         acc[ai][bj][m][n] = __builtin_amdgcn_mfma_f32_16x16x32_bf16(Bt[n][k], At[m][k], acc[ai][bj][m][n], 0, 0, 0); __builtin_amdgcn_s_setprio(0); } while (0)
; #define PG8_WAIT_V(n) asm volatile("s_waitcnt vmcnt(" #n ")" ::: "memory")
; #define PG8_WAIT_L(n) asm volatile("s_waitcnt lgkmcnt(" #n ")" ::: "memory")
; template <class Epi, class Sched, bool ALIGN_EPI = false, bool SP2 = false>
; __device__ __forceinline__ void gemm_phase(PG8_LAS unsigned char* lds, const Gemm g, const Sched& S, const Epi& E) {
;     ...
;             const bool last = (t == nt - 2);
;             const char* a1 = cA + (size_t)(t + 1) * kstep;
;             const char* a2 = last ? nA : cA + (size_t)(t + 2) * kstep; const char* b2 = last ? nB : cB + (size_t)(t + 2) * kstep;
;             const char* a3 = a2 + kstep; const char* b3 = b2 + kstep;
;             if (last && has_next) S.a_ready(nxt);
;             if constexpr (SP2) {
;             PG8_LDB(B0, 0, 0); PG8_LDB(B1, 0, 1); PG8_SCHED; PG8_LDA(At, 0, 0); PG8_STAGE(PG8_SA(1, 1), a1 + hstepA, voffA);
;             PG8_WAIT_V(8); PG8_WAIT_L(0); PG8_BAR; PG8_MMA(0, 0, At, B0); PG8_MMA(0, 1, At, B1); PG8_BAR; PG8_SCHED;
;             PG8_LDA(At, 0, 1); PG8_STAGE(PG8_SB(0, 0), b2, voffB); PG8_STAGE(PG8_SB(0, 1), b2 + hstepB, voffB); PG8_STAGE(PG8_SA(0, 0), a2, voffA);
;             PG8_WAIT_V(8); PG8_WAIT_L(0); PG8_BAR; PG8_MMA(1, 0, At, B0); PG8_MMA(1, 1, At, B1); PG8_BAR; PG8_SCHED;
.LBB0_1384:
	s_add_u32 s70, s28, s69
	ds_read_b128 v[130:133], v158
	ds_read_b128 v[134:137], v158 offset:1024
	ds_read_b128 v[138:141], v158 offset:2048
	ds_read_b128 v[142:145], v158 offset:3072
	ds_read_b128 v[152:155], v159
	ds_read_b128 v[162:165], v159 offset:1024
	ds_read_b128 v[166:169], v159 offset:2048
	ds_read_b128 v[170:173], v159 offset:3072
	s_addc_u32 s71, s29, 0
	s_add_u32 s72, s70, 0x100
	s_addc_u32 s73, s71, 0
	s_and_b64 s[36:37], s[34:35], exec
	s_cselect_b32 s37, s17, s73
	s_cselect_b32 s36, s67, s72
	s_add_u32 s69, s26, s69
	s_addc_u32 s72, s27, 0
	s_add_u32 s69, s69, 0x100
	s_addc_u32 s72, s72, 0
	s_and_b64 s[34:35], s[34:35], exec
	s_cselect_b32 s35, s15, s72
	s_cselect_b32 s34, s68, s69
	s_add_u32 s70, s70, 0x40080
	s_addc_u32 s71, s71, 0
	v_lshl_add_u64 v[206:207], s[70:71], 0, v[148:149]
	s_add_i32 m0, s47, 0xc000
	ds_read_b128 v[174:177], v160
	ds_read_b128 v[178:181], v160 offset:1024
	ds_read_b128 v[182:185], v160 offset:2048
	ds_read_b128 v[186:189], v160 offset:3072
	ds_read_b128 v[190:193], v160 offset:4096
	ds_read_b128 v[194:197], v160 offset:5120
	ds_read_b128 v[198:201], v160 offset:6144
	ds_read_b128 v[202:205], v160 offset:7168
	global_load_lds_dwordx4 v[206:207], off
	v_lshl_add_u64 v[206:207], s[70:71], 0, v[146:147]
	s_add_i32 m0, s47, 0xe000
	s_nop 0
	global_load_lds_dwordx4 v[206:207], off
	s_waitcnt vmcnt(8)
	s_waitcnt lgkmcnt(0)
	s_barrier
	v_mfma_f32_16x16x32_bf16 v[126:129], v[130:133], v[174:177], v[126:129]
	v_mfma_f32_16x16x32_bf16 v[122:125], v[138:141], v[174:177], v[122:125]
	v_mfma_f32_16x16x32_bf16 v[118:121], v[130:133], v[182:185], v[118:121]
	v_mfma_f32_16x16x32_bf16 v[114:117], v[138:141], v[182:185], v[114:117]
	v_mfma_f32_16x16x32_bf16 v[102:105], v[130:133], v[190:193], v[102:105]
	v_mfma_f32_16x16x32_bf16 v[90:93], v[138:141], v[190:193], v[90:93]
	v_mfma_f32_16x16x32_bf16 v[82:85], v[130:133], v[198:201], v[82:85]
	v_mfma_f32_16x16x32_bf16 v[74:77], v[138:141], v[198:201], v[74:77]
	v_mfma_f32_16x16x32_bf16 v[126:129], v[134:137], v[178:181], v[126:129]
	v_mfma_f32_16x16x32_bf16 v[122:125], v[142:145], v[178:181], v[122:125]
	v_mfma_f32_16x16x32_bf16 v[118:121], v[134:137], v[186:189], v[118:121]
	v_mfma_f32_16x16x32_bf16 v[114:117], v[142:145], v[186:189], v[114:117]
	v_mfma_f32_16x16x32_bf16 v[102:105], v[134:137], v[194:197], v[102:105]
	v_mfma_f32_16x16x32_bf16 v[90:93], v[142:145], v[194:197], v[90:93]
	v_mfma_f32_16x16x32_bf16 v[82:85], v[134:137], v[202:205], v[82:85]
	v_mfma_f32_16x16x32_bf16 v[74:77], v[142:145], v[202:205], v[74:77]
	v_mfma_f32_16x16x32_bf16 v[110:113], v[152:155], v[174:177], v[110:113]
	v_mfma_f32_16x16x32_bf16 v[106:109], v[166:169], v[174:177], v[106:109]
	v_mfma_f32_16x16x32_bf16 v[98:101], v[152:155], v[182:185], v[98:101]
	v_mfma_f32_16x16x32_bf16 v[94:97], v[166:169], v[182:185], v[94:97]
	v_mfma_f32_16x16x32_bf16 v[86:89], v[152:155], v[190:193], v[86:89]
	v_mfma_f32_16x16x32_bf16 v[78:81], v[166:169], v[190:193], v[78:81]
	v_mfma_f32_16x16x32_bf16 v[70:73], v[152:155], v[198:201], v[70:73]
	v_mfma_f32_16x16x32_bf16 v[66:69], v[166:169], v[198:201], v[66:69]
	v_mfma_f32_16x16x32_bf16 v[110:113], v[162:165], v[178:181], v[110:113]
	v_mfma_f32_16x16x32_bf16 v[106:109], v[170:173], v[178:181], v[106:109]
	v_mfma_f32_16x16x32_bf16 v[98:101], v[162:165], v[186:189], v[98:101]
	v_mfma_f32_16x16x32_bf16 v[94:97], v[170:173], v[186:189], v[94:97]
	v_mfma_f32_16x16x32_bf16 v[86:89], v[162:165], v[194:197], v[86:89]
	v_mfma_f32_16x16x32_bf16 v[78:81], v[170:173], v[194:197], v[78:81]
	v_mfma_f32_16x16x32_bf16 v[70:73], v[162:165], v[202:205], v[70:73]
	v_mfma_f32_16x16x32_bf16 v[66:69], v[170:173], v[202:205], v[66:69]
	s_barrier
	s_add_i32 s69, s59, s44
	v_lshl_add_u64 v[206:207], s[34:35], 0, v[148:149]
	s_mov_b32 m0, s69
	ds_read_b128 v[174:177], v160 offset:16384
	ds_read_b128 v[178:181], v160 offset:17408
	ds_read_b128 v[182:185], v160 offset:18432
	ds_read_b128 v[186:189], v160 offset:19456
	ds_read_b128 v[190:193], v160 offset:20480
	ds_read_b128 v[194:197], v160 offset:21504
	ds_read_b128 v[198:201], v160 offset:22528
	ds_read_b128 v[202:205], v160 offset:23552
	global_load_lds_dwordx4 v[206:207], off
	s_add_i32 m0, s69, 0x2000
	s_add_u32 s70, s34, 0x40000
	v_lshl_add_u64 v[208:209], s[34:35], 0, v[146:147]
	s_addc_u32 s71, s35, 0
	s_add_i32 s69, s60, s44
	global_load_lds_dwordx4 v[208:209], off
	v_lshl_add_u64 v[210:211], s[70:71], 0, v[148:149]
	s_mov_b32 m0, s69
	v_lshl_add_u64 v[212:213], s[36:37], 0, v[146:147]
	global_load_lds_dwordx4 v[210:211], off
	v_lshl_add_u64 v[210:211], s[70:71], 0, v[146:147]
	s_add_i32 m0, s69, 0x2000
	s_nop 0
	global_load_lds_dwordx4 v[210:211], off
	v_lshl_add_u64 v[210:211], s[36:37], 0, v[148:149]
	s_mov_b32 m0, s47
	s_nop 0
	global_load_lds_dwordx4 v[210:211], off
	s_mov_b32 m0, s48
	s_nop 0
	global_load_lds_dwordx4 v[212:213], off
	s_waitcnt vmcnt(8)
	s_waitcnt lgkmcnt(0)
	s_barrier
; #define PG8_STAGE(bufoff, gbase, voff) do { _Pragma("unroll") for (int _i = 0; _i < 2; ++_i) \
;         __builtin_amdgcn_global_load_lds((const unsigned*)((const char*)(gbase) + (voff)[_i]), (PG8_LAS unsigned*)(lds + (bufoff) + ldsw + _i * 8192), 16, 0, 0); } while (0)
; #define PG8_LDA(dst, b, h) do { _Pragma("unroll") for (int m = 0; m < 4; ++m) _Pragma("unroll") for (int k = 0; k < 2; ++k) dst[m][k] = *(const PG8_LAS bf16x8*)(lds + PG8_SA(b, h) + aoff + m * 2048 + k * 1024); } while (0)
; #define PG8_LDB(dst, b, h) do { _Pragma("unroll") for (int n = 0; n < 2; ++n) _Pragma("unroll") for (int k = 0; k < 2; ++k) dst[n][k] = *(const PG8_LAS bf16x8*)(lds + PG8_SB(b, h) + boff + n * 2048 + k * 1024); } while (0)
; #define PG8_MMA(ai, bj, At, Bt) do { __builtin_amdgcn_s_setprio(1); _Pragma("unroll") for (int m = 0; m < 4; ++m) _Pragma("unroll") for (int n = 0; n < 2; ++n) _Pragma("unroll") for (int k = 0; k < 2; ++k) \
;         acc[ai][bj][m][n] = __builtin_amdgcn_mfma_f32_16x16x32_bf16(Bt[n][k], At[m][k], acc[ai][bj][m][n], 0, 0, 0); __builtin_amdgcn_s_setprio(0); } while (0)
; #define PG8_WAIT_V(n) asm volatile("s_waitcnt vmcnt(" #n ")" ::: "memory")
; #define PG8_WAIT_L(n) asm volatile("s_waitcnt lgkmcnt(" #n ")" ::: "memory")
; #define PG8_BAR __builtin_amdgcn_s_barrier()
; #define PG8_SCHED __builtin_amdgcn_sched_barrier(0)
; template <class Epi, class Sched, bool ALIGN_EPI = false, bool SP2 = false>
; __device__ __forceinline__ void gemm_phase(PG8_LAS unsigned char* lds, const Gemm g, const Sched& S, const Epi& E) {
;     ...
;             PG8_WAIT_V(8); PG8_WAIT_L(0); PG8_BAR; PG8_MMA(1, 0, At, B0); PG8_MMA(1, 1, At, B1); PG8_BAR; PG8_SCHED;
;             PG8_LDB(B0, 1, 0); PG8_LDB(B1, 1, 1); PG8_SCHED; PG8_LDA(At, 1, 0); PG8_STAGE(PG8_SA(0, 1), a2 + hstepA, voffA);
;             PG8_WAIT_V(8); PG8_WAIT_L(0); PG8_BAR; PG8_MMA(0, 0, At, B0); PG8_MMA(0, 1, At, B1); PG8_BAR; PG8_SCHED;
	v_mfma_f32_16x16x32_bf16 v[62:65], v[130:133], v[174:177], v[62:65]
	v_mfma_f32_16x16x32_bf16 v[58:61], v[138:141], v[174:177], v[58:61]
	v_mfma_f32_16x16x32_bf16 v[54:57], v[130:133], v[182:185], v[54:57]
	v_mfma_f32_16x16x32_bf16 v[50:53], v[138:141], v[182:185], v[50:53]
	v_mfma_f32_16x16x32_bf16 v[46:49], v[130:133], v[190:193], v[46:49]
	v_mfma_f32_16x16x32_bf16 v[38:41], v[138:141], v[190:193], v[38:41]
	v_mfma_f32_16x16x32_bf16 v[18:21], v[130:133], v[198:201], v[18:21]
	v_mfma_f32_16x16x32_bf16 v[10:13], v[138:141], v[198:201], v[10:13]
	v_mfma_f32_16x16x32_bf16 v[62:65], v[134:137], v[178:181], v[62:65]
	v_mfma_f32_16x16x32_bf16 v[58:61], v[142:145], v[178:181], v[58:61]
	v_mfma_f32_16x16x32_bf16 v[54:57], v[134:137], v[186:189], v[54:57]
	v_mfma_f32_16x16x32_bf16 v[50:53], v[142:145], v[186:189], v[50:53]
	v_mfma_f32_16x16x32_bf16 v[46:49], v[134:137], v[194:197], v[46:49]
	v_mfma_f32_16x16x32_bf16 v[38:41], v[142:145], v[194:197], v[38:41]
	v_mfma_f32_16x16x32_bf16 v[18:21], v[134:137], v[202:205], v[18:21]
	v_mfma_f32_16x16x32_bf16 v[10:13], v[142:145], v[202:205], v[10:13]
	v_mfma_f32_16x16x32_bf16 v[42:45], v[152:155], v[174:177], v[42:45]
	v_mfma_f32_16x16x32_bf16 v[34:37], v[166:169], v[174:177], v[34:37]
	v_mfma_f32_16x16x32_bf16 v[30:33], v[152:155], v[182:185], v[30:33]
	v_mfma_f32_16x16x32_bf16 v[26:29], v[166:169], v[182:185], v[26:29]
	v_mfma_f32_16x16x32_bf16 v[22:25], v[152:155], v[190:193], v[22:25]
	v_mfma_f32_16x16x32_bf16 v[14:17], v[166:169], v[190:193], v[14:17]
	v_mfma_f32_16x16x32_bf16 v[6:9], v[152:155], v[198:201], v[6:9]
	v_mfma_f32_16x16x32_bf16 v[2:5], v[166:169], v[198:201], v[2:5]
	v_mfma_f32_16x16x32_bf16 v[42:45], v[162:165], v[178:181], v[42:45]
	v_mfma_f32_16x16x32_bf16 v[34:37], v[170:173], v[178:181], v[34:37]
	v_mfma_f32_16x16x32_bf16 v[30:33], v[162:165], v[186:189], v[30:33]
	v_mfma_f32_16x16x32_bf16 v[26:29], v[170:173], v[186:189], v[26:29]
	v_mfma_f32_16x16x32_bf16 v[22:25], v[162:165], v[194:197], v[22:25]
	v_mfma_f32_16x16x32_bf16 v[14:17], v[170:173], v[194:197], v[14:17]
	v_mfma_f32_16x16x32_bf16 v[6:9], v[162:165], v[202:205], v[6:9]
	v_mfma_f32_16x16x32_bf16 v[2:5], v[170:173], v[202:205], v[2:5]
	s_barrier
	s_add_i32 s69, 0, 0x18000
	s_add_i32 s70, 0, 0x1c000
	v_add_u32_e32 v142, s69, v1
	v_add_u32_e32 v170, s70, v1
	ds_read_b128 v[130:133], v142
	ds_read_b128 v[134:137], v142 offset:1024
	ds_read_b128 v[138:141], v142 offset:2048
	ds_read_b128 v[142:145], v142 offset:3072
	ds_read_b128 v[152:155], v170
	ds_read_b128 v[162:165], v170 offset:1024
	ds_read_b128 v[166:169], v170 offset:2048
	ds_read_b128 v[170:173], v170 offset:3072
	s_add_u32 s36, s36, 0x40000
	s_addc_u32 s37, s37, 0
	s_mov_b32 m0, s49
	v_lshl_add_u64 v[214:215], s[36:37], 0, v[148:149]
	ds_read_b128 v[174:177], v160 offset:32768
	ds_read_b128 v[178:181], v160 offset:33792
	ds_read_b128 v[182:185], v160 offset:34816
	ds_read_b128 v[186:189], v160 offset:35840
	ds_read_b128 v[190:193], v160 offset:36864
	ds_read_b128 v[194:197], v160 offset:37888
	ds_read_b128 v[198:201], v160 offset:38912
	ds_read_b128 v[202:205], v160 offset:39936
	global_load_lds_dwordx4 v[214:215], off
	v_lshl_add_u64 v[214:215], s[36:37], 0, v[146:147]
	s_mov_b32 m0, s50
	s_nop 0
	global_load_lds_dwordx4 v[214:215], off
	s_waitcnt vmcnt(8)
	s_waitcnt lgkmcnt(0)
	s_barrier
	v_mfma_f32_16x16x32_bf16 v[126:129], v[130:133], v[174:177], v[126:129]
	v_mfma_f32_16x16x32_bf16 v[122:125], v[138:141], v[174:177], v[122:125]
	v_mfma_f32_16x16x32_bf16 v[118:121], v[130:133], v[182:185], v[118:121]
	v_mfma_f32_16x16x32_bf16 v[114:117], v[138:141], v[182:185], v[114:117]
	v_mfma_f32_16x16x32_bf16 v[102:105], v[130:133], v[190:193], v[102:105]
	v_mfma_f32_16x16x32_bf16 v[90:93], v[138:141], v[190:193], v[90:93]
	v_mfma_f32_16x16x32_bf16 v[82:85], v[130:133], v[198:201], v[82:85]
	v_mfma_f32_16x16x32_bf16 v[74:77], v[138:141], v[198:201], v[74:77]
	v_mfma_f32_16x16x32_bf16 v[126:129], v[134:137], v[178:181], v[126:129]
	v_mfma_f32_16x16x32_bf16 v[122:125], v[142:145], v[178:181], v[122:125]
	v_mfma_f32_16x16x32_bf16 v[118:121], v[134:137], v[186:189], v[118:121]
	v_mfma_f32_16x16x32_bf16 v[114:117], v[142:145], v[186:189], v[114:117]
	v_mfma_f32_16x16x32_bf16 v[102:105], v[134:137], v[194:197], v[102:105]
	v_mfma_f32_16x16x32_bf16 v[90:93], v[142:145], v[194:197], v[90:93]
	v_mfma_f32_16x16x32_bf16 v[82:85], v[134:137], v[202:205], v[82:85]
	v_mfma_f32_16x16x32_bf16 v[74:77], v[142:145], v[202:205], v[74:77]
	v_mfma_f32_16x16x32_bf16 v[110:113], v[152:155], v[174:177], v[110:113]
	v_mfma_f32_16x16x32_bf16 v[106:109], v[166:169], v[174:177], v[106:109]
	v_mfma_f32_16x16x32_bf16 v[98:101], v[152:155], v[182:185], v[98:101]
	v_mfma_f32_16x16x32_bf16 v[94:97], v[166:169], v[182:185], v[94:97]
	v_mfma_f32_16x16x32_bf16 v[86:89], v[152:155], v[190:193], v[86:89]
	v_mfma_f32_16x16x32_bf16 v[78:81], v[166:169], v[190:193], v[78:81]
	v_mfma_f32_16x16x32_bf16 v[70:73], v[152:155], v[198:201], v[70:73]
	v_mfma_f32_16x16x32_bf16 v[66:69], v[166:169], v[198:201], v[66:69]
	v_mfma_f32_16x16x32_bf16 v[110:113], v[162:165], v[178:181], v[110:113]
	v_mfma_f32_16x16x32_bf16 v[106:109], v[170:173], v[178:181], v[106:109]
	v_mfma_f32_16x16x32_bf16 v[98:101], v[162:165], v[186:189], v[98:101]
	v_mfma_f32_16x16x32_bf16 v[94:97], v[170:173], v[186:189], v[94:97]
	v_mfma_f32_16x16x32_bf16 v[86:89], v[162:165], v[194:197], v[86:89]
	v_mfma_f32_16x16x32_bf16 v[78:81], v[170:173], v[194:197], v[78:81]
	v_mfma_f32_16x16x32_bf16 v[70:73], v[162:165], v[202:205], v[70:73]
	v_mfma_f32_16x16x32_bf16 v[66:69], v[170:173], v[202:205], v[66:69]
	s_barrier
; #define PG8_STAGE(bufoff, gbase, voff) do { _Pragma("unroll") for (int _i = 0; _i < 2; ++_i) \
;         __builtin_amdgcn_global_load_lds((const unsigned*)((const char*)(gbase) + (voff)[_i]), (PG8_LAS unsigned*)(lds + (bufoff) + ldsw + _i * 8192), 16, 0, 0); } while (0)
; #define PG8_LDA(dst, b, h) do { _Pragma("unroll") for (int m = 0; m < 4; ++m) _Pragma("unroll") for (int k = 0; k < 2; ++k) dst[m][k] = *(const PG8_LAS bf16x8*)(lds + PG8_SA(b, h) + aoff + m * 2048 + k * 1024); } while (0)
; #define PG8_MMA(ai, bj, At, Bt) do { __builtin_amdgcn_s_setprio(1); _Pragma("unroll") for (int m = 0; m < 4; ++m) _Pragma("unroll") for (int n = 0; n < 2; ++n) _Pragma("unroll") for (int k = 0; k < 2; ++k) \
;         acc[ai][bj][m][n] = __builtin_amdgcn_mfma_f32_16x16x32_bf16(Bt[n][k], At[m][k], acc[ai][bj][m][n], 0, 0, 0); __builtin_amdgcn_s_setprio(0); } while (0)
; #define PG8_WAIT_V(n) asm volatile("s_waitcnt vmcnt(" #n ")" ::: "memory")
; #define PG8_WAIT_L(n) asm volatile("s_waitcnt lgkmcnt(" #n ")" ::: "memory")
; #define PG8_BAR __builtin_amdgcn_s_barrier()
; #define PG8_SCHED __builtin_amdgcn_sched_barrier(0)
; template <class Epi, class Sched, bool ALIGN_EPI = false, bool SP2 = false>
; __device__ __forceinline__ void gemm_phase(PG8_LAS unsigned char* lds, const Gemm g, const Sched& S, const Epi& E) {
;     ...
;         for (int t = 0; t < nt; t += 2) {
;     ...
;             PG8_LDA(At, 1, 1); PG8_STAGE(PG8_SB(1, 0), b3, voffB); PG8_STAGE(PG8_SB(1, 1), b3 + hstepB, voffB); PG8_STAGE(PG8_SA(1, 0), a3, voffA);
;             PG8_WAIT_V(8); PG8_WAIT_L(0); PG8_BAR; PG8_MMA(1, 0, At, B0); PG8_MMA(1, 1, At, B1); PG8_BAR; PG8_SCHED;
	s_add_i32 s36, s69, s44
	v_lshl_add_u64 v[206:207], v[206:207], 0, s[4:5]
	s_mov_b32 m0, s36
	ds_read_b128 v[174:177], v160 offset:49152
	ds_read_b128 v[178:181], v160 offset:50176
	ds_read_b128 v[182:185], v160 offset:51200
	ds_read_b128 v[186:189], v160 offset:52224
	ds_read_b128 v[190:193], v160 offset:53248
	ds_read_b128 v[194:197], v160 offset:54272
	ds_read_b128 v[198:201], v160 offset:55296
	ds_read_b128 v[202:205], v160 offset:56320
	global_load_lds_dwordx4 v[206:207], off
	s_add_i32 m0, s36, 0x2000
	s_add_u32 s34, s34, 0x40080
	v_lshl_add_u64 v[206:207], v[208:209], 0, s[4:5]
	s_addc_u32 s35, s35, 0
	s_add_i32 s36, s70, s44
	global_load_lds_dwordx4 v[206:207], off
	v_lshl_add_u64 v[206:207], s[34:35], 0, v[148:149]
	s_mov_b32 m0, s36
	s_nop 0
	global_load_lds_dwordx4 v[206:207], off
	v_lshl_add_u64 v[206:207], s[34:35], 0, v[146:147]
	s_add_i32 m0, s36, 0x2000
	s_nop 0
	global_load_lds_dwordx4 v[206:207], off
	v_lshl_add_u64 v[206:207], v[210:211], 0, s[4:5]
	s_mov_b32 m0, s57
	s_nop 0
	global_load_lds_dwordx4 v[206:207], off
	v_lshl_add_u64 v[206:207], v[212:213], 0, s[4:5]
	s_mov_b32 m0, s58
	s_nop 0
	global_load_lds_dwordx4 v[206:207], off
	s_waitcnt vmcnt(8)
	s_waitcnt lgkmcnt(0)
	s_barrier
	v_mfma_f32_16x16x32_bf16 v[62:65], v[130:133], v[174:177], v[62:65]
	v_mfma_f32_16x16x32_bf16 v[58:61], v[138:141], v[174:177], v[58:61]
	v_mfma_f32_16x16x32_bf16 v[54:57], v[130:133], v[182:185], v[54:57]
	v_mfma_f32_16x16x32_bf16 v[50:53], v[138:141], v[182:185], v[50:53]
	v_mfma_f32_16x16x32_bf16 v[46:49], v[130:133], v[190:193], v[46:49]
	v_mfma_f32_16x16x32_bf16 v[38:41], v[138:141], v[190:193], v[38:41]
	v_mfma_f32_16x16x32_bf16 v[18:21], v[130:133], v[198:201], v[18:21]
	v_mfma_f32_16x16x32_bf16 v[10:13], v[138:141], v[198:201], v[10:13]
	v_mfma_f32_16x16x32_bf16 v[62:65], v[134:137], v[178:181], v[62:65]
	v_mfma_f32_16x16x32_bf16 v[58:61], v[142:145], v[178:181], v[58:61]
	v_mfma_f32_16x16x32_bf16 v[54:57], v[134:137], v[186:189], v[54:57]
	v_mfma_f32_16x16x32_bf16 v[50:53], v[142:145], v[186:189], v[50:53]
	v_mfma_f32_16x16x32_bf16 v[46:49], v[134:137], v[194:197], v[46:49]
	v_mfma_f32_16x16x32_bf16 v[38:41], v[142:145], v[194:197], v[38:41]
	v_mfma_f32_16x16x32_bf16 v[18:21], v[134:137], v[202:205], v[18:21]
	v_mfma_f32_16x16x32_bf16 v[10:13], v[142:145], v[202:205], v[10:13]
	v_mfma_f32_16x16x32_bf16 v[42:45], v[152:155], v[174:177], v[42:45]
	v_mfma_f32_16x16x32_bf16 v[34:37], v[166:169], v[174:177], v[34:37]
	v_mfma_f32_16x16x32_bf16 v[30:33], v[152:155], v[182:185], v[30:33]
	v_mfma_f32_16x16x32_bf16 v[26:29], v[166:169], v[182:185], v[26:29]
	v_mfma_f32_16x16x32_bf16 v[22:25], v[152:155], v[190:193], v[22:25]
	v_mfma_f32_16x16x32_bf16 v[14:17], v[166:169], v[190:193], v[14:17]
	v_mfma_f32_16x16x32_bf16 v[6:9], v[152:155], v[198:201], v[6:9]
	v_mfma_f32_16x16x32_bf16 v[2:5], v[166:169], v[198:201], v[2:5]
	v_mfma_f32_16x16x32_bf16 v[42:45], v[162:165], v[178:181], v[42:45]
	v_mfma_f32_16x16x32_bf16 v[34:37], v[170:173], v[178:181], v[34:37]
	v_mfma_f32_16x16x32_bf16 v[30:33], v[162:165], v[186:189], v[30:33]
	v_mfma_f32_16x16x32_bf16 v[26:29], v[170:173], v[186:189], v[26:29]
	v_mfma_f32_16x16x32_bf16 v[22:25], v[162:165], v[194:197], v[22:25]
	v_mfma_f32_16x16x32_bf16 v[14:17], v[170:173], v[194:197], v[14:17]
	v_mfma_f32_16x16x32_bf16 v[6:9], v[162:165], v[202:205], v[6:9]
	v_mfma_f32_16x16x32_bf16 v[2:5], v[170:173], v[202:205], v[2:5]
	s_barrier
	s_movk_i32 s69, 0x100
	s_and_b64 vcc, exec, s[30:31]
	s_mov_b64 s[34:35], -1
	s_mov_b64 s[30:31], 0
	s_cbranch_vccnz .LBB0_1384
	s_andn2_b64 vcc, exec, s[8:9]
	s_cbranch_vccnz .LBB0_1387
	s_barrier

; #define PG8_STAGE(bufoff, gbase, voff) do { _Pragma("unroll") for (int _i = 0; _i < 2; ++_i) \
;         __builtin_amdgcn_global_load_lds((const unsigned*)((const char*)(gbase) + (voff)[_i]), (PG8_LAS unsigned*)(lds + (bufoff) + ldsw + _i * 8192), 16, 0, 0); } while (0)
; #define PG8_LDA(dst, b, h) do { _Pragma("unroll") for (int m = 0; m < 4; ++m) _Pragma("unroll") for (int k = 0; k < 2; ++k) dst[m][k] = *(const PG8_LAS bf16x8*)(lds + PG8_SA(b, h) + aoff + m * 2048 + k * 1024); } while (0)
; #define PG8_LDB(dst, b, h) do { _Pragma("unroll") for (int n = 0; n < 2; ++n) _Pragma("unroll") for (int k = 0; k < 2; ++k) dst[n][k] = *(const PG8_LAS bf16x8*)(lds + PG8_SB(b, h) + boff + n * 2048 + k * 1024); } while (0)
; #define PG8_MMA(ai, bj, At, Bt) do { __builtin_amdgcn_s_setprio(1); _Pragma("unroll") for (int m = 0; m < 4; ++m) _Pragma("unroll") for (int n = 0; n < 2; ++n) _Pragma("unroll") for (int k = 0; k < 2; ++k) \
;         acc[ai][bj][m][n] = __builtin_amdgcn_mfma_f32_16x16x32_bf16(Bt[n][k], At[m][k], acc[ai][bj][m][n], 0, 0, 0); __builtin_amdgcn_s_setprio(0); } while (0)
; #define PG8_WAIT_V(n) asm volatile("s_waitcnt vmcnt(" #n ")" ::: "memory")
; #define PG8_WAIT_L(n) asm volatile("s_waitcnt lgkmcnt(" #n ")" ::: "memory")
; template <class Epi, class Sched, bool ALIGN_EPI = false, bool SP2 = false>
; __device__ __forceinline__ void gemm_phase(PG8_LAS unsigned char* lds, const Gemm g, const Sched& S, const Epi& E) {
;     ...
;             const bool last = (t == nt - 2);
;             const char* a1 = cA + (size_t)(t + 1) * kstep;
;             const char* a2 = last ? nA : cA + (size_t)(t + 2) * kstep; const char* b2 = last ? nB : cB + (size_t)(t + 2) * kstep;
;             const char* a3 = a2 + kstep; const char* b3 = b2 + kstep;
;             if (last && has_next) S.a_ready(nxt);
;             if constexpr (SP2) {
;             PG8_LDB(B0, 0, 0); PG8_LDB(B1, 0, 1); PG8_SCHED; PG8_LDA(At, 0, 0); PG8_STAGE(PG8_SA(1, 1), a1 + hstepA, voffA);
;             PG8_WAIT_V(8); PG8_WAIT_L(0); PG8_BAR; PG8_MMA(0, 0, At, B0); PG8_MMA(0, 1, At, B1); PG8_BAR; PG8_SCHED;
;             PG8_LDA(At, 0, 1); PG8_STAGE(PG8_SB(0, 0), b2, voffB); PG8_STAGE(PG8_SB(0, 1), b2 + hstepB, voffB); PG8_STAGE(PG8_SA(0, 0), a2, voffA);
;             PG8_WAIT_V(8); PG8_WAIT_L(0); PG8_BAR; PG8_MMA(1, 0, At, B0); PG8_MMA(1, 1, At, B1); PG8_BAR; PG8_SCHED;
.LBB0_1921:
	ds_read_b128 v[130:133], v162
	ds_read_b128 v[134:137], v162 offset:1024
	ds_read_b128 v[138:141], v162 offset:2048
	ds_read_b128 v[142:145], v162 offset:3072
	ds_read_b128 v[156:159], v163
	ds_read_b128 v[166:169], v163 offset:1024
	ds_read_b128 v[170:173], v163 offset:2048
	ds_read_b128 v[174:177], v163 offset:3072
	s_add_u32 s22, s20, 0x100
	s_addc_u32 s23, s21, 0
	s_cmp_eq_u32 s67, 4
	s_cselect_b32 s27, s19, s23
	s_cselect_b32 s26, s18, s22
	s_cselect_b32 s25, s1, s66
	s_cselect_b32 s24, s0, s65
	v_lshl_add_u64 v[210:211], s[20:21], 0, v[154:155]
	s_add_i32 m0, s41, 0xc000
	ds_read_b128 v[178:181], v164
	ds_read_b128 v[182:185], v164 offset:1024
	ds_read_b128 v[186:189], v164 offset:2048
	ds_read_b128 v[190:193], v164 offset:3072
	ds_read_b128 v[194:197], v164 offset:4096
	ds_read_b128 v[198:201], v164 offset:5120
	ds_read_b128 v[202:205], v164 offset:6144
	ds_read_b128 v[206:209], v164 offset:7168
	global_load_lds_dwordx4 v[210:211], off
	v_lshl_add_u64 v[210:211], s[20:21], 0, v[152:153]
	s_add_i32 m0, s41, 0xe000
	s_nop 0
	global_load_lds_dwordx4 v[210:211], off
	s_waitcnt vmcnt(8)
	s_waitcnt lgkmcnt(0)
	s_barrier
	v_mfma_f32_16x16x32_bf16 v[126:129], v[130:133], v[178:181], v[126:129]
	v_mfma_f32_16x16x32_bf16 v[122:125], v[138:141], v[178:181], v[122:125]
	v_mfma_f32_16x16x32_bf16 v[118:121], v[130:133], v[186:189], v[118:121]
	v_mfma_f32_16x16x32_bf16 v[114:117], v[138:141], v[186:189], v[114:117]
	v_mfma_f32_16x16x32_bf16 v[102:105], v[130:133], v[194:197], v[102:105]
	v_mfma_f32_16x16x32_bf16 v[90:93], v[138:141], v[194:197], v[90:93]
	v_mfma_f32_16x16x32_bf16 v[82:85], v[130:133], v[202:205], v[82:85]
	v_mfma_f32_16x16x32_bf16 v[74:77], v[138:141], v[202:205], v[74:77]
	v_mfma_f32_16x16x32_bf16 v[126:129], v[134:137], v[182:185], v[126:129]
	v_mfma_f32_16x16x32_bf16 v[122:125], v[142:145], v[182:185], v[122:125]
	v_mfma_f32_16x16x32_bf16 v[118:121], v[134:137], v[190:193], v[118:121]
	v_mfma_f32_16x16x32_bf16 v[114:117], v[142:145], v[190:193], v[114:117]
	v_mfma_f32_16x16x32_bf16 v[102:105], v[134:137], v[198:201], v[102:105]
	v_mfma_f32_16x16x32_bf16 v[90:93], v[142:145], v[198:201], v[90:93]
	v_mfma_f32_16x16x32_bf16 v[82:85], v[134:137], v[206:209], v[82:85]
	v_mfma_f32_16x16x32_bf16 v[74:77], v[142:145], v[206:209], v[74:77]
	v_mfma_f32_16x16x32_bf16 v[110:113], v[156:159], v[178:181], v[110:113]
	v_mfma_f32_16x16x32_bf16 v[106:109], v[170:173], v[178:181], v[106:109]
	v_mfma_f32_16x16x32_bf16 v[98:101], v[156:159], v[186:189], v[98:101]
	v_mfma_f32_16x16x32_bf16 v[94:97], v[170:173], v[186:189], v[94:97]
	v_mfma_f32_16x16x32_bf16 v[86:89], v[156:159], v[194:197], v[86:89]
	v_mfma_f32_16x16x32_bf16 v[78:81], v[170:173], v[194:197], v[78:81]
	v_mfma_f32_16x16x32_bf16 v[70:73], v[156:159], v[202:205], v[70:73]
	v_mfma_f32_16x16x32_bf16 v[66:69], v[170:173], v[202:205], v[66:69]
	v_mfma_f32_16x16x32_bf16 v[110:113], v[166:169], v[182:185], v[110:113]
	v_mfma_f32_16x16x32_bf16 v[106:109], v[174:177], v[182:185], v[106:109]
	v_mfma_f32_16x16x32_bf16 v[98:101], v[166:169], v[190:193], v[98:101]
	v_mfma_f32_16x16x32_bf16 v[94:97], v[174:177], v[190:193], v[94:97]
	v_mfma_f32_16x16x32_bf16 v[86:89], v[166:169], v[198:201], v[86:89]
	v_mfma_f32_16x16x32_bf16 v[78:81], v[174:177], v[198:201], v[78:81]
	v_mfma_f32_16x16x32_bf16 v[70:73], v[166:169], v[206:209], v[70:73]
	v_mfma_f32_16x16x32_bf16 v[66:69], v[174:177], v[206:209], v[66:69]
	s_barrier
	s_add_i32 s20, s53, s39
	v_lshl_add_u64 v[210:211], s[24:25], 0, v[148:149]
	s_mov_b32 m0, s20
	ds_read_b128 v[178:181], v164 offset:16384
	ds_read_b128 v[182:185], v164 offset:17408
	ds_read_b128 v[186:189], v164 offset:18432
	ds_read_b128 v[190:193], v164 offset:19456
	ds_read_b128 v[194:197], v164 offset:20480
	ds_read_b128 v[198:201], v164 offset:21504
	ds_read_b128 v[202:205], v164 offset:22528
	ds_read_b128 v[206:209], v164 offset:23552
	global_load_lds_dwordx4 v[210:211], off
	s_add_i32 m0, s20, 0x2000
	s_add_u32 s20, s24, 0xb0000
	v_lshl_add_u64 v[212:213], s[24:25], 0, v[146:147]
	s_addc_u32 s21, s25, 0
	s_add_i32 s68, s54, s39
	global_load_lds_dwordx4 v[212:213], off
	v_lshl_add_u64 v[214:215], s[20:21], 0, v[148:149]
	s_mov_b32 m0, s68
	v_lshl_add_u64 v[216:217], s[26:27], 0, v[146:147]
	global_load_lds_dwordx4 v[214:215], off
	v_lshl_add_u64 v[214:215], s[20:21], 0, v[146:147]
	s_add_i32 m0, s68, 0x2000
	s_nop 0
	global_load_lds_dwordx4 v[214:215], off
	v_lshl_add_u64 v[214:215], s[26:27], 0, v[148:149]
	s_mov_b32 m0, s41
	s_nop 0
	global_load_lds_dwordx4 v[214:215], off
	s_mov_b32 m0, s42
	s_nop 0
	global_load_lds_dwordx4 v[216:217], off
	s_waitcnt vmcnt(8)
	s_waitcnt lgkmcnt(0)
	s_barrier
; #define PG8_STAGE(bufoff, gbase, voff) do { _Pragma("unroll") for (int _i = 0; _i < 2; ++_i) \
;         __builtin_amdgcn_global_load_lds((const unsigned*)((const char*)(gbase) + (voff)[_i]), (PG8_LAS unsigned*)(lds + (bufoff) + ldsw + _i * 8192), 16, 0, 0); } while (0)
; #define PG8_LDA(dst, b, h) do { _Pragma("unroll") for (int m = 0; m < 4; ++m) _Pragma("unroll") for (int k = 0; k < 2; ++k) dst[m][k] = *(const PG8_LAS bf16x8*)(lds + PG8_SA(b, h) + aoff + m * 2048 + k * 1024); } while (0)
; #define PG8_LDB(dst, b, h) do { _Pragma("unroll") for (int n = 0; n < 2; ++n) _Pragma("unroll") for (int k = 0; k < 2; ++k) dst[n][k] = *(const PG8_LAS bf16x8*)(lds + PG8_SB(b, h) + boff + n * 2048 + k * 1024); } while (0)
; #define PG8_MMA(ai, bj, At, Bt) do { __builtin_amdgcn_s_setprio(1); _Pragma("unroll") for (int m = 0; m < 4; ++m) _Pragma("unroll") for (int n = 0; n < 2; ++n) _Pragma("unroll") for (int k = 0; k < 2; ++k) \
;         acc[ai][bj][m][n] = __builtin_amdgcn_mfma_f32_16x16x32_bf16(Bt[n][k], At[m][k], acc[ai][bj][m][n], 0, 0, 0); __builtin_amdgcn_s_setprio(0); } while (0)
; #define PG8_WAIT_V(n) asm volatile("s_waitcnt vmcnt(" #n ")" ::: "memory")
; #define PG8_WAIT_L(n) asm volatile("s_waitcnt lgkmcnt(" #n ")" ::: "memory")
; #define PG8_BAR __builtin_amdgcn_s_barrier()
; #define PG8_SCHED __builtin_amdgcn_sched_barrier(0)
; template <class Epi, class Sched, bool ALIGN_EPI = false, bool SP2 = false>
; __device__ __forceinline__ void gemm_phase(PG8_LAS unsigned char* lds, const Gemm g, const Sched& S, const Epi& E) {
;     ...
;             PG8_WAIT_V(8); PG8_WAIT_L(0); PG8_BAR; PG8_MMA(1, 0, At, B0); PG8_MMA(1, 1, At, B1); PG8_BAR; PG8_SCHED;
;             PG8_LDB(B0, 1, 0); PG8_LDB(B1, 1, 1); PG8_SCHED; PG8_LDA(At, 1, 0); PG8_STAGE(PG8_SA(0, 1), a2 + hstepA, voffA);
;             PG8_WAIT_V(8); PG8_WAIT_L(0); PG8_BAR; PG8_MMA(0, 0, At, B0); PG8_MMA(0, 1, At, B1); PG8_BAR; PG8_SCHED;
	v_mfma_f32_16x16x32_bf16 v[62:65], v[130:133], v[178:181], v[62:65]
	v_mfma_f32_16x16x32_bf16 v[58:61], v[138:141], v[178:181], v[58:61]
	v_mfma_f32_16x16x32_bf16 v[54:57], v[130:133], v[186:189], v[54:57]
	v_mfma_f32_16x16x32_bf16 v[50:53], v[138:141], v[186:189], v[50:53]
	v_mfma_f32_16x16x32_bf16 v[46:49], v[130:133], v[194:197], v[46:49]
	v_mfma_f32_16x16x32_bf16 v[38:41], v[138:141], v[194:197], v[38:41]
	v_mfma_f32_16x16x32_bf16 v[18:21], v[130:133], v[202:205], v[18:21]
	v_mfma_f32_16x16x32_bf16 v[10:13], v[138:141], v[202:205], v[10:13]
	v_mfma_f32_16x16x32_bf16 v[62:65], v[134:137], v[182:185], v[62:65]
	v_mfma_f32_16x16x32_bf16 v[58:61], v[142:145], v[182:185], v[58:61]
	v_mfma_f32_16x16x32_bf16 v[54:57], v[134:137], v[190:193], v[54:57]
	v_mfma_f32_16x16x32_bf16 v[50:53], v[142:145], v[190:193], v[50:53]
	v_mfma_f32_16x16x32_bf16 v[46:49], v[134:137], v[198:201], v[46:49]
	v_mfma_f32_16x16x32_bf16 v[38:41], v[142:145], v[198:201], v[38:41]
	v_mfma_f32_16x16x32_bf16 v[18:21], v[134:137], v[206:209], v[18:21]
	v_mfma_f32_16x16x32_bf16 v[10:13], v[142:145], v[206:209], v[10:13]
	v_mfma_f32_16x16x32_bf16 v[42:45], v[156:159], v[178:181], v[42:45]
	v_mfma_f32_16x16x32_bf16 v[34:37], v[170:173], v[178:181], v[34:37]
	v_mfma_f32_16x16x32_bf16 v[30:33], v[156:159], v[186:189], v[30:33]
	v_mfma_f32_16x16x32_bf16 v[26:29], v[170:173], v[186:189], v[26:29]
	v_mfma_f32_16x16x32_bf16 v[22:25], v[156:159], v[194:197], v[22:25]
	v_mfma_f32_16x16x32_bf16 v[14:17], v[170:173], v[194:197], v[14:17]
	v_mfma_f32_16x16x32_bf16 v[6:9], v[156:159], v[202:205], v[6:9]
	v_mfma_f32_16x16x32_bf16 v[2:5], v[170:173], v[202:205], v[2:5]
	v_mfma_f32_16x16x32_bf16 v[42:45], v[166:169], v[182:185], v[42:45]
	v_mfma_f32_16x16x32_bf16 v[34:37], v[174:177], v[182:185], v[34:37]
	v_mfma_f32_16x16x32_bf16 v[30:33], v[166:169], v[190:193], v[30:33]
	v_mfma_f32_16x16x32_bf16 v[26:29], v[174:177], v[190:193], v[26:29]
	v_mfma_f32_16x16x32_bf16 v[22:25], v[166:169], v[198:201], v[22:25]
	v_mfma_f32_16x16x32_bf16 v[14:17], v[174:177], v[198:201], v[14:17]
	v_mfma_f32_16x16x32_bf16 v[6:9], v[166:169], v[206:209], v[6:9]
	v_mfma_f32_16x16x32_bf16 v[2:5], v[174:177], v[206:209], v[2:5]
	s_barrier
	s_add_i32 s68, 0, 0x18000
	s_add_i32 s69, 0, 0x1c000
	v_add_u32_e32 v142, s68, v1
	v_add_u32_e32 v174, s69, v1
	ds_read_b128 v[130:133], v142
	ds_read_b128 v[134:137], v142 offset:1024
	ds_read_b128 v[138:141], v142 offset:2048
	ds_read_b128 v[142:145], v142 offset:3072
	ds_read_b128 v[156:159], v174
	ds_read_b128 v[166:169], v174 offset:1024
	ds_read_b128 v[170:173], v174 offset:2048
	ds_read_b128 v[174:177], v174 offset:3072
	s_add_u32 s20, s26, 0xb0000
	s_addc_u32 s21, s27, 0
	s_mov_b32 m0, s43
	v_lshl_add_u64 v[218:219], s[20:21], 0, v[148:149]
	ds_read_b128 v[178:181], v164 offset:32768
	ds_read_b128 v[182:185], v164 offset:33792
	ds_read_b128 v[186:189], v164 offset:34816
	ds_read_b128 v[190:193], v164 offset:35840
	ds_read_b128 v[194:197], v164 offset:36864
	ds_read_b128 v[198:201], v164 offset:37888
	ds_read_b128 v[202:205], v164 offset:38912
	ds_read_b128 v[206:209], v164 offset:39936
	global_load_lds_dwordx4 v[218:219], off
	v_lshl_add_u64 v[218:219], s[20:21], 0, v[146:147]
	s_mov_b32 m0, s44
	s_nop 0
	global_load_lds_dwordx4 v[218:219], off
	s_waitcnt vmcnt(8)
	s_waitcnt lgkmcnt(0)
	s_barrier
	v_mfma_f32_16x16x32_bf16 v[126:129], v[130:133], v[178:181], v[126:129]
	v_mfma_f32_16x16x32_bf16 v[122:125], v[138:141], v[178:181], v[122:125]
	v_mfma_f32_16x16x32_bf16 v[118:121], v[130:133], v[186:189], v[118:121]
	v_mfma_f32_16x16x32_bf16 v[114:117], v[138:141], v[186:189], v[114:117]
	v_mfma_f32_16x16x32_bf16 v[102:105], v[130:133], v[194:197], v[102:105]
	v_mfma_f32_16x16x32_bf16 v[90:93], v[138:141], v[194:197], v[90:93]
	v_mfma_f32_16x16x32_bf16 v[82:85], v[130:133], v[202:205], v[82:85]
	v_mfma_f32_16x16x32_bf16 v[74:77], v[138:141], v[202:205], v[74:77]
	v_mfma_f32_16x16x32_bf16 v[126:129], v[134:137], v[182:185], v[126:129]
	v_mfma_f32_16x16x32_bf16 v[122:125], v[142:145], v[182:185], v[122:125]
	v_mfma_f32_16x16x32_bf16 v[118:121], v[134:137], v[190:193], v[118:121]
	v_mfma_f32_16x16x32_bf16 v[114:117], v[142:145], v[190:193], v[114:117]
	v_mfma_f32_16x16x32_bf16 v[102:105], v[134:137], v[198:201], v[102:105]
	v_mfma_f32_16x16x32_bf16 v[90:93], v[142:145], v[198:201], v[90:93]
	v_mfma_f32_16x16x32_bf16 v[82:85], v[134:137], v[206:209], v[82:85]
	v_mfma_f32_16x16x32_bf16 v[74:77], v[142:145], v[206:209], v[74:77]
	v_mfma_f32_16x16x32_bf16 v[110:113], v[156:159], v[178:181], v[110:113]
	v_mfma_f32_16x16x32_bf16 v[106:109], v[170:173], v[178:181], v[106:109]
	v_mfma_f32_16x16x32_bf16 v[98:101], v[156:159], v[186:189], v[98:101]
	v_mfma_f32_16x16x32_bf16 v[94:97], v[170:173], v[186:189], v[94:97]
	v_mfma_f32_16x16x32_bf16 v[86:89], v[156:159], v[194:197], v[86:89]
	v_mfma_f32_16x16x32_bf16 v[78:81], v[170:173], v[194:197], v[78:81]
	v_mfma_f32_16x16x32_bf16 v[70:73], v[156:159], v[202:205], v[70:73]
	v_mfma_f32_16x16x32_bf16 v[66:69], v[170:173], v[202:205], v[66:69]
	v_mfma_f32_16x16x32_bf16 v[110:113], v[166:169], v[182:185], v[110:113]
	v_mfma_f32_16x16x32_bf16 v[106:109], v[174:177], v[182:185], v[106:109]
	v_mfma_f32_16x16x32_bf16 v[98:101], v[166:169], v[190:193], v[98:101]
	v_mfma_f32_16x16x32_bf16 v[94:97], v[174:177], v[190:193], v[94:97]
	v_mfma_f32_16x16x32_bf16 v[86:89], v[166:169], v[198:201], v[86:89]
	v_mfma_f32_16x16x32_bf16 v[78:81], v[174:177], v[198:201], v[78:81]
	v_mfma_f32_16x16x32_bf16 v[70:73], v[166:169], v[206:209], v[70:73]
	v_mfma_f32_16x16x32_bf16 v[66:69], v[174:177], v[206:209], v[66:69]
	s_barrier
; #define PG8_STAGE(bufoff, gbase, voff) do { _Pragma("unroll") for (int _i = 0; _i < 2; ++_i) \
;         __builtin_amdgcn_global_load_lds((const unsigned*)((const char*)(gbase) + (voff)[_i]), (PG8_LAS unsigned*)(lds + (bufoff) + ldsw + _i * 8192), 16, 0, 0); } while (0)
; #define PG8_LDA(dst, b, h) do { _Pragma("unroll") for (int m = 0; m < 4; ++m) _Pragma("unroll") for (int k = 0; k < 2; ++k) dst[m][k] = *(const PG8_LAS bf16x8*)(lds + PG8_SA(b, h) + aoff + m * 2048 + k * 1024); } while (0)
; #define PG8_MMA(ai, bj, At, Bt) do { __builtin_amdgcn_s_setprio(1); _Pragma("unroll") for (int m = 0; m < 4; ++m) _Pragma("unroll") for (int n = 0; n < 2; ++n) _Pragma("unroll") for (int k = 0; k < 2; ++k) \
;         acc[ai][bj][m][n] = __builtin_amdgcn_mfma_f32_16x16x32_bf16(Bt[n][k], At[m][k], acc[ai][bj][m][n], 0, 0, 0); __builtin_amdgcn_s_setprio(0); } while (0)
; #define PG8_WAIT_V(n) asm volatile("s_waitcnt vmcnt(" #n ")" ::: "memory")
; #define PG8_WAIT_L(n) asm volatile("s_waitcnt lgkmcnt(" #n ")" ::: "memory")
; #define PG8_BAR __builtin_amdgcn_s_barrier()
; #define PG8_SCHED __builtin_amdgcn_sched_barrier(0)
; template <class Epi, class Sched, bool ALIGN_EPI = false, bool SP2 = false>
; __device__ __forceinline__ void gemm_phase(PG8_LAS unsigned char* lds, const Gemm g, const Sched& S, const Epi& E) {
;     ...
;         for (int t = 0; t < nt; t += 2) {
;     ...
;             PG8_LDA(At, 1, 1); PG8_STAGE(PG8_SB(1, 0), b3, voffB); PG8_STAGE(PG8_SB(1, 1), b3 + hstepB, voffB); PG8_STAGE(PG8_SA(1, 0), a3, voffA);
;             PG8_WAIT_V(8); PG8_WAIT_L(0); PG8_BAR; PG8_MMA(1, 0, At, B0); PG8_MMA(1, 1, At, B1); PG8_BAR; PG8_SCHED;
	s_add_i32 s20, s68, s39
	v_lshl_add_u64 v[210:211], v[210:211], 0, s[8:9]
	s_mov_b32 m0, s20
	ds_read_b128 v[178:181], v164 offset:49152
	ds_read_b128 v[182:185], v164 offset:50176
	ds_read_b128 v[186:189], v164 offset:51200
	ds_read_b128 v[190:193], v164 offset:52224
	ds_read_b128 v[194:197], v164 offset:53248
	ds_read_b128 v[198:201], v164 offset:54272
	ds_read_b128 v[202:205], v164 offset:55296
	ds_read_b128 v[206:209], v164 offset:56320
	global_load_lds_dwordx4 v[210:211], off
	s_add_i32 m0, s20, 0x2000
	s_add_u32 s20, s24, 0xb0080
	v_lshl_add_u64 v[210:211], v[212:213], 0, s[8:9]
	s_addc_u32 s21, s25, 0
	s_add_i32 s24, s69, s39
	global_load_lds_dwordx4 v[210:211], off
	v_lshl_add_u64 v[210:211], s[20:21], 0, v[148:149]
	s_mov_b32 m0, s24
	s_nop 0
	global_load_lds_dwordx4 v[210:211], off
	v_lshl_add_u64 v[210:211], s[20:21], 0, v[146:147]
	s_add_i32 m0, s24, 0x2000
	s_nop 0
	global_load_lds_dwordx4 v[210:211], off
	v_lshl_add_u64 v[210:211], v[214:215], 0, s[8:9]
	s_mov_b32 m0, s51
	s_nop 0
	global_load_lds_dwordx4 v[210:211], off
	v_lshl_add_u64 v[210:211], v[216:217], 0, s[8:9]
	s_mov_b32 m0, s52
	s_nop 0
	global_load_lds_dwordx4 v[210:211], off
	s_waitcnt vmcnt(8)
	s_waitcnt lgkmcnt(0)
	s_barrier
	v_mfma_f32_16x16x32_bf16 v[62:65], v[130:133], v[178:181], v[62:65]
	v_mfma_f32_16x16x32_bf16 v[58:61], v[138:141], v[178:181], v[58:61]
	v_mfma_f32_16x16x32_bf16 v[54:57], v[130:133], v[186:189], v[54:57]
	v_mfma_f32_16x16x32_bf16 v[50:53], v[138:141], v[186:189], v[50:53]
	v_mfma_f32_16x16x32_bf16 v[46:49], v[130:133], v[194:197], v[46:49]
	v_mfma_f32_16x16x32_bf16 v[38:41], v[138:141], v[194:197], v[38:41]
	v_mfma_f32_16x16x32_bf16 v[18:21], v[130:133], v[202:205], v[18:21]
	v_mfma_f32_16x16x32_bf16 v[10:13], v[138:141], v[202:205], v[10:13]
	v_mfma_f32_16x16x32_bf16 v[62:65], v[134:137], v[182:185], v[62:65]
	v_mfma_f32_16x16x32_bf16 v[58:61], v[142:145], v[182:185], v[58:61]
	v_mfma_f32_16x16x32_bf16 v[54:57], v[134:137], v[190:193], v[54:57]
	v_mfma_f32_16x16x32_bf16 v[50:53], v[142:145], v[190:193], v[50:53]
	v_mfma_f32_16x16x32_bf16 v[46:49], v[134:137], v[198:201], v[46:49]
	v_mfma_f32_16x16x32_bf16 v[38:41], v[142:145], v[198:201], v[38:41]
	v_mfma_f32_16x16x32_bf16 v[18:21], v[134:137], v[206:209], v[18:21]
	v_mfma_f32_16x16x32_bf16 v[10:13], v[142:145], v[206:209], v[10:13]
	v_mfma_f32_16x16x32_bf16 v[42:45], v[156:159], v[178:181], v[42:45]
	v_mfma_f32_16x16x32_bf16 v[34:37], v[170:173], v[178:181], v[34:37]
	v_mfma_f32_16x16x32_bf16 v[30:33], v[156:159], v[186:189], v[30:33]
	v_mfma_f32_16x16x32_bf16 v[26:29], v[170:173], v[186:189], v[26:29]
	v_mfma_f32_16x16x32_bf16 v[22:25], v[156:159], v[194:197], v[22:25]
	v_mfma_f32_16x16x32_bf16 v[14:17], v[170:173], v[194:197], v[14:17]
	v_mfma_f32_16x16x32_bf16 v[6:9], v[156:159], v[202:205], v[6:9]
	v_mfma_f32_16x16x32_bf16 v[2:5], v[170:173], v[202:205], v[2:5]
	v_mfma_f32_16x16x32_bf16 v[42:45], v[166:169], v[182:185], v[42:45]
	v_mfma_f32_16x16x32_bf16 v[34:37], v[174:177], v[182:185], v[34:37]
	v_mfma_f32_16x16x32_bf16 v[30:33], v[166:169], v[190:193], v[30:33]
	v_mfma_f32_16x16x32_bf16 v[26:29], v[174:177], v[190:193], v[26:29]
	v_mfma_f32_16x16x32_bf16 v[22:25], v[166:169], v[198:201], v[22:25]
	v_mfma_f32_16x16x32_bf16 v[14:17], v[174:177], v[198:201], v[14:17]
	v_mfma_f32_16x16x32_bf16 v[6:9], v[166:169], v[206:209], v[6:9]
	v_mfma_f32_16x16x32_bf16 v[2:5], v[174:177], v[206:209], v[2:5]
	s_barrier
	s_add_i32 s67, s67, 2
	s_add_u32 s65, s65, 0x100
	s_addc_u32 s66, s66, 0
	s_cmp_lt_u32 s67, 6
	s_mov_b64 s[20:21], s[22:23]
	s_cbranch_scc1 .LBB0_1921
	s_andn2_b64 vcc, exec, s[10:11]
	s_cbranch_vccnz .LBB0_1924
	s_barrier

; #define PG8_STAGE(bufoff, gbase, voff) do { _Pragma("unroll") for (int _i = 0; _i < 2; ++_i) \
;         __builtin_amdgcn_global_load_lds((const unsigned*)((const char*)(gbase) + (voff)[_i]), (PG8_LAS unsigned*)(lds + (bufoff) + ldsw + _i * 8192), 16, 0, 0); } while (0)
; #define PG8_LDA(dst, b, h) do { _Pragma("unroll") for (int m = 0; m < 4; ++m) _Pragma("unroll") for (int k = 0; k < 2; ++k) dst[m][k] = *(const PG8_LAS bf16x8*)(lds + PG8_SA(b, h) + aoff + m * 2048 + k * 1024); } while (0)
; #define PG8_LDB(dst, b, h) do { _Pragma("unroll") for (int n = 0; n < 2; ++n) _Pragma("unroll") for (int k = 0; k < 2; ++k) dst[n][k] = *(const PG8_LAS bf16x8*)(lds + PG8_SB(b, h) + boff + n * 2048 + k * 1024); } while (0)
; #define PG8_MMA(ai, bj, At, Bt) do { __builtin_amdgcn_s_setprio(1); _Pragma("unroll") for (int m = 0; m < 4; ++m) _Pragma("unroll") for (int n = 0; n < 2; ++n) _Pragma("unroll") for (int k = 0; k < 2; ++k) \
;         acc[ai][bj][m][n] = __builtin_amdgcn_mfma_f32_16x16x32_bf16(Bt[n][k], At[m][k], acc[ai][bj][m][n], 0, 0, 0); __builtin_amdgcn_s_setprio(0); } while (0)
; #define PG8_WAIT_V(n) asm volatile("s_waitcnt vmcnt(" #n ")" ::: "memory")
; #define PG8_WAIT_L(n) asm volatile("s_waitcnt lgkmcnt(" #n ")" ::: "memory")
; template <class Epi, class Sched, bool ALIGN_EPI = false, bool SP2 = false>
; __device__ __forceinline__ void gemm_phase(PG8_LAS unsigned char* lds, const Gemm g, const Sched& S, const Epi& E) {
;     ...
;             const bool last = (t == nt - 2);
;             const char* a1 = cA + (size_t)(t + 1) * kstep;
;             const char* a2 = last ? nA : cA + (size_t)(t + 2) * kstep; const char* b2 = last ? nB : cB + (size_t)(t + 2) * kstep;
;             const char* a3 = a2 + kstep; const char* b3 = b2 + kstep;
;             if (last && has_next) S.a_ready(nxt);
;             if constexpr (SP2) {
;             PG8_LDB(B0, 0, 0); PG8_LDB(B1, 0, 1); PG8_SCHED; PG8_LDA(At, 0, 0); PG8_STAGE(PG8_SA(1, 1), a1 + hstepA, voffA);
;             PG8_WAIT_V(8); PG8_WAIT_L(0); PG8_BAR; PG8_MMA(0, 0, At, B0); PG8_MMA(0, 1, At, B1); PG8_BAR; PG8_SCHED;
;             PG8_LDA(At, 0, 1); PG8_STAGE(PG8_SB(0, 0), b2, voffB); PG8_STAGE(PG8_SB(0, 1), b2 + hstepB, voffB); PG8_STAGE(PG8_SA(0, 0), a2, voffA);
;             PG8_WAIT_V(8); PG8_WAIT_L(0); PG8_BAR; PG8_MMA(1, 0, At, B0); PG8_MMA(1, 1, At, B1); PG8_BAR; PG8_SCHED;
.LBB0_1945:
	ds_read_b128 v[130:133], v162
	ds_read_b128 v[134:137], v162 offset:1024
	ds_read_b128 v[138:141], v162 offset:2048
	ds_read_b128 v[142:145], v162 offset:3072
	ds_read_b128 v[156:159], v163
	ds_read_b128 v[166:169], v163 offset:1024
	ds_read_b128 v[170:173], v163 offset:2048
	ds_read_b128 v[174:177], v163 offset:3072
	s_add_u32 s22, s20, 0x100
	s_addc_u32 s23, s21, 0
	s_cmp_eq_u32 s68, 4
	s_cselect_b32 s27, s19, s23
	s_cselect_b32 s26, s18, s22
	s_cselect_b32 s25, s1, s67
	s_cselect_b32 s24, s0, s66
	v_lshl_add_u64 v[210:211], s[20:21], 0, v[154:155]
	s_add_i32 m0, s42, 0xc000
	ds_read_b128 v[178:181], v164
	ds_read_b128 v[182:185], v164 offset:1024
	ds_read_b128 v[186:189], v164 offset:2048
	ds_read_b128 v[190:193], v164 offset:3072
	ds_read_b128 v[194:197], v164 offset:4096
	ds_read_b128 v[198:201], v164 offset:5120
	ds_read_b128 v[202:205], v164 offset:6144
	ds_read_b128 v[206:209], v164 offset:7168
	global_load_lds_dwordx4 v[210:211], off
	v_lshl_add_u64 v[210:211], s[20:21], 0, v[152:153]
	s_add_i32 m0, s42, 0xe000
	s_nop 0
	global_load_lds_dwordx4 v[210:211], off
	s_waitcnt vmcnt(8)
	s_waitcnt lgkmcnt(0)
	s_barrier
	v_mfma_f32_16x16x32_bf16 v[126:129], v[130:133], v[178:181], v[126:129]
	v_mfma_f32_16x16x32_bf16 v[122:125], v[138:141], v[178:181], v[122:125]
	v_mfma_f32_16x16x32_bf16 v[118:121], v[130:133], v[186:189], v[118:121]
	v_mfma_f32_16x16x32_bf16 v[114:117], v[138:141], v[186:189], v[114:117]
	v_mfma_f32_16x16x32_bf16 v[102:105], v[130:133], v[194:197], v[102:105]
	v_mfma_f32_16x16x32_bf16 v[90:93], v[138:141], v[194:197], v[90:93]
	v_mfma_f32_16x16x32_bf16 v[82:85], v[130:133], v[202:205], v[82:85]
	v_mfma_f32_16x16x32_bf16 v[74:77], v[138:141], v[202:205], v[74:77]
	v_mfma_f32_16x16x32_bf16 v[126:129], v[134:137], v[182:185], v[126:129]
	v_mfma_f32_16x16x32_bf16 v[122:125], v[142:145], v[182:185], v[122:125]
	v_mfma_f32_16x16x32_bf16 v[118:121], v[134:137], v[190:193], v[118:121]
	v_mfma_f32_16x16x32_bf16 v[114:117], v[142:145], v[190:193], v[114:117]
	v_mfma_f32_16x16x32_bf16 v[102:105], v[134:137], v[198:201], v[102:105]
	v_mfma_f32_16x16x32_bf16 v[90:93], v[142:145], v[198:201], v[90:93]
	v_mfma_f32_16x16x32_bf16 v[82:85], v[134:137], v[206:209], v[82:85]
	v_mfma_f32_16x16x32_bf16 v[74:77], v[142:145], v[206:209], v[74:77]
	v_mfma_f32_16x16x32_bf16 v[110:113], v[156:159], v[178:181], v[110:113]
	v_mfma_f32_16x16x32_bf16 v[106:109], v[170:173], v[178:181], v[106:109]
	v_mfma_f32_16x16x32_bf16 v[98:101], v[156:159], v[186:189], v[98:101]
	v_mfma_f32_16x16x32_bf16 v[94:97], v[170:173], v[186:189], v[94:97]
	v_mfma_f32_16x16x32_bf16 v[86:89], v[156:159], v[194:197], v[86:89]
	v_mfma_f32_16x16x32_bf16 v[78:81], v[170:173], v[194:197], v[78:81]
	v_mfma_f32_16x16x32_bf16 v[70:73], v[156:159], v[202:205], v[70:73]
	v_mfma_f32_16x16x32_bf16 v[66:69], v[170:173], v[202:205], v[66:69]
	v_mfma_f32_16x16x32_bf16 v[110:113], v[166:169], v[182:185], v[110:113]
	v_mfma_f32_16x16x32_bf16 v[106:109], v[174:177], v[182:185], v[106:109]
	v_mfma_f32_16x16x32_bf16 v[98:101], v[166:169], v[190:193], v[98:101]
	v_mfma_f32_16x16x32_bf16 v[94:97], v[174:177], v[190:193], v[94:97]
	v_mfma_f32_16x16x32_bf16 v[86:89], v[166:169], v[198:201], v[86:89]
	v_mfma_f32_16x16x32_bf16 v[78:81], v[174:177], v[198:201], v[78:81]
	v_mfma_f32_16x16x32_bf16 v[70:73], v[166:169], v[206:209], v[70:73]
	v_mfma_f32_16x16x32_bf16 v[66:69], v[174:177], v[206:209], v[66:69]
	s_barrier
	s_add_i32 s20, s54, s40
	v_lshl_add_u64 v[210:211], s[24:25], 0, v[148:149]
	s_mov_b32 m0, s20
	ds_read_b128 v[178:181], v164 offset:16384
	ds_read_b128 v[182:185], v164 offset:17408
	ds_read_b128 v[186:189], v164 offset:18432
	ds_read_b128 v[190:193], v164 offset:19456
	ds_read_b128 v[194:197], v164 offset:20480
	ds_read_b128 v[198:201], v164 offset:21504
	ds_read_b128 v[202:205], v164 offset:22528
	ds_read_b128 v[206:209], v164 offset:23552
	global_load_lds_dwordx4 v[210:211], off
	s_add_i32 m0, s20, 0x2000
	s_add_u32 s20, s24, 0xb0000
	v_lshl_add_u64 v[212:213], s[24:25], 0, v[146:147]
	s_addc_u32 s21, s25, 0
	s_add_i32 s69, s55, s40
	global_load_lds_dwordx4 v[212:213], off
	v_lshl_add_u64 v[214:215], s[20:21], 0, v[148:149]
	s_mov_b32 m0, s69
	v_lshl_add_u64 v[216:217], s[26:27], 0, v[146:147]
	global_load_lds_dwordx4 v[214:215], off
	v_lshl_add_u64 v[214:215], s[20:21], 0, v[146:147]
	s_add_i32 m0, s69, 0x2000
	s_nop 0
	global_load_lds_dwordx4 v[214:215], off
	v_lshl_add_u64 v[214:215], s[26:27], 0, v[148:149]
	s_mov_b32 m0, s42
	s_nop 0
	global_load_lds_dwordx4 v[214:215], off
	s_mov_b32 m0, s43
	s_nop 0
	global_load_lds_dwordx4 v[216:217], off
	s_waitcnt vmcnt(8)
	s_waitcnt lgkmcnt(0)
	s_barrier
; #define PG8_STAGE(bufoff, gbase, voff) do { _Pragma("unroll") for (int _i = 0; _i < 2; ++_i) \
;         __builtin_amdgcn_global_load_lds((const unsigned*)((const char*)(gbase) + (voff)[_i]), (PG8_LAS unsigned*)(lds + (bufoff) + ldsw + _i * 8192), 16, 0, 0); } while (0)
; #define PG8_LDA(dst, b, h) do { _Pragma("unroll") for (int m = 0; m < 4; ++m) _Pragma("unroll") for (int k = 0; k < 2; ++k) dst[m][k] = *(const PG8_LAS bf16x8*)(lds + PG8_SA(b, h) + aoff + m * 2048 + k * 1024); } while (0)
; #define PG8_LDB(dst, b, h) do { _Pragma("unroll") for (int n = 0; n < 2; ++n) _Pragma("unroll") for (int k = 0; k < 2; ++k) dst[n][k] = *(const PG8_LAS bf16x8*)(lds + PG8_SB(b, h) + boff + n * 2048 + k * 1024); } while (0)
; #define PG8_MMA(ai, bj, At, Bt) do { __builtin_amdgcn_s_setprio(1); _Pragma("unroll") for (int m = 0; m < 4; ++m) _Pragma("unroll") for (int n = 0; n < 2; ++n) _Pragma("unroll") for (int k = 0; k < 2; ++k) \
;         acc[ai][bj][m][n] = __builtin_amdgcn_mfma_f32_16x16x32_bf16(Bt[n][k], At[m][k], acc[ai][bj][m][n], 0, 0, 0); __builtin_amdgcn_s_setprio(0); } while (0)
; #define PG8_WAIT_V(n) asm volatile("s_waitcnt vmcnt(" #n ")" ::: "memory")
; #define PG8_WAIT_L(n) asm volatile("s_waitcnt lgkmcnt(" #n ")" ::: "memory")
; #define PG8_BAR __builtin_amdgcn_s_barrier()
; #define PG8_SCHED __builtin_amdgcn_sched_barrier(0)
; template <class Epi, class Sched, bool ALIGN_EPI = false, bool SP2 = false>
; __device__ __forceinline__ void gemm_phase(PG8_LAS unsigned char* lds, const Gemm g, const Sched& S, const Epi& E) {
;     ...
;             PG8_WAIT_V(8); PG8_WAIT_L(0); PG8_BAR; PG8_MMA(1, 0, At, B0); PG8_MMA(1, 1, At, B1); PG8_BAR; PG8_SCHED;
;             PG8_LDB(B0, 1, 0); PG8_LDB(B1, 1, 1); PG8_SCHED; PG8_LDA(At, 1, 0); PG8_STAGE(PG8_SA(0, 1), a2 + hstepA, voffA);
;             PG8_WAIT_V(8); PG8_WAIT_L(0); PG8_BAR; PG8_MMA(0, 0, At, B0); PG8_MMA(0, 1, At, B1); PG8_BAR; PG8_SCHED;
	v_mfma_f32_16x16x32_bf16 v[62:65], v[130:133], v[178:181], v[62:65]
	v_mfma_f32_16x16x32_bf16 v[58:61], v[138:141], v[178:181], v[58:61]
	v_mfma_f32_16x16x32_bf16 v[54:57], v[130:133], v[186:189], v[54:57]
	v_mfma_f32_16x16x32_bf16 v[50:53], v[138:141], v[186:189], v[50:53]
	v_mfma_f32_16x16x32_bf16 v[46:49], v[130:133], v[194:197], v[46:49]
	v_mfma_f32_16x16x32_bf16 v[38:41], v[138:141], v[194:197], v[38:41]
	v_mfma_f32_16x16x32_bf16 v[18:21], v[130:133], v[202:205], v[18:21]
	v_mfma_f32_16x16x32_bf16 v[10:13], v[138:141], v[202:205], v[10:13]
	v_mfma_f32_16x16x32_bf16 v[62:65], v[134:137], v[182:185], v[62:65]
	v_mfma_f32_16x16x32_bf16 v[58:61], v[142:145], v[182:185], v[58:61]
	v_mfma_f32_16x16x32_bf16 v[54:57], v[134:137], v[190:193], v[54:57]
	v_mfma_f32_16x16x32_bf16 v[50:53], v[142:145], v[190:193], v[50:53]
	v_mfma_f32_16x16x32_bf16 v[46:49], v[134:137], v[198:201], v[46:49]
	v_mfma_f32_16x16x32_bf16 v[38:41], v[142:145], v[198:201], v[38:41]
	v_mfma_f32_16x16x32_bf16 v[18:21], v[134:137], v[206:209], v[18:21]
	v_mfma_f32_16x16x32_bf16 v[10:13], v[142:145], v[206:209], v[10:13]
	v_mfma_f32_16x16x32_bf16 v[42:45], v[156:159], v[178:181], v[42:45]
	v_mfma_f32_16x16x32_bf16 v[34:37], v[170:173], v[178:181], v[34:37]
	v_mfma_f32_16x16x32_bf16 v[30:33], v[156:159], v[186:189], v[30:33]
	v_mfma_f32_16x16x32_bf16 v[26:29], v[170:173], v[186:189], v[26:29]
	v_mfma_f32_16x16x32_bf16 v[22:25], v[156:159], v[194:197], v[22:25]
	v_mfma_f32_16x16x32_bf16 v[14:17], v[170:173], v[194:197], v[14:17]
	v_mfma_f32_16x16x32_bf16 v[6:9], v[156:159], v[202:205], v[6:9]
	v_mfma_f32_16x16x32_bf16 v[2:5], v[170:173], v[202:205], v[2:5]
	v_mfma_f32_16x16x32_bf16 v[42:45], v[166:169], v[182:185], v[42:45]
	v_mfma_f32_16x16x32_bf16 v[34:37], v[174:177], v[182:185], v[34:37]
	v_mfma_f32_16x16x32_bf16 v[30:33], v[166:169], v[190:193], v[30:33]
	v_mfma_f32_16x16x32_bf16 v[26:29], v[174:177], v[190:193], v[26:29]
	v_mfma_f32_16x16x32_bf16 v[22:25], v[166:169], v[198:201], v[22:25]
	v_mfma_f32_16x16x32_bf16 v[14:17], v[174:177], v[198:201], v[14:17]
	v_mfma_f32_16x16x32_bf16 v[6:9], v[166:169], v[206:209], v[6:9]
	v_mfma_f32_16x16x32_bf16 v[2:5], v[174:177], v[206:209], v[2:5]
	s_barrier
	s_add_i32 s69, 0, 0x18000
	s_add_i32 s70, 0, 0x1c000
	v_add_u32_e32 v142, s69, v1
	v_add_u32_e32 v174, s70, v1
	ds_read_b128 v[130:133], v142
	ds_read_b128 v[134:137], v142 offset:1024
	ds_read_b128 v[138:141], v142 offset:2048
	ds_read_b128 v[142:145], v142 offset:3072
	ds_read_b128 v[156:159], v174
	ds_read_b128 v[166:169], v174 offset:1024
	ds_read_b128 v[170:173], v174 offset:2048
	ds_read_b128 v[174:177], v174 offset:3072
	s_add_u32 s20, s26, 0xb0000
	s_addc_u32 s21, s27, 0
	s_mov_b32 m0, s44
	v_lshl_add_u64 v[218:219], s[20:21], 0, v[148:149]
	ds_read_b128 v[178:181], v164 offset:32768
	ds_read_b128 v[182:185], v164 offset:33792
	ds_read_b128 v[186:189], v164 offset:34816
	ds_read_b128 v[190:193], v164 offset:35840
	ds_read_b128 v[194:197], v164 offset:36864
	ds_read_b128 v[198:201], v164 offset:37888
	ds_read_b128 v[202:205], v164 offset:38912
	ds_read_b128 v[206:209], v164 offset:39936
	global_load_lds_dwordx4 v[218:219], off
	v_lshl_add_u64 v[218:219], s[20:21], 0, v[146:147]
	s_mov_b32 m0, s45
	s_nop 0
	global_load_lds_dwordx4 v[218:219], off
	s_waitcnt vmcnt(8)
	s_waitcnt lgkmcnt(0)
	s_barrier
	v_mfma_f32_16x16x32_bf16 v[126:129], v[130:133], v[178:181], v[126:129]
	v_mfma_f32_16x16x32_bf16 v[122:125], v[138:141], v[178:181], v[122:125]
	v_mfma_f32_16x16x32_bf16 v[118:121], v[130:133], v[186:189], v[118:121]
	v_mfma_f32_16x16x32_bf16 v[114:117], v[138:141], v[186:189], v[114:117]
	v_mfma_f32_16x16x32_bf16 v[102:105], v[130:133], v[194:197], v[102:105]
	v_mfma_f32_16x16x32_bf16 v[90:93], v[138:141], v[194:197], v[90:93]
	v_mfma_f32_16x16x32_bf16 v[82:85], v[130:133], v[202:205], v[82:85]
	v_mfma_f32_16x16x32_bf16 v[74:77], v[138:141], v[202:205], v[74:77]
	v_mfma_f32_16x16x32_bf16 v[126:129], v[134:137], v[182:185], v[126:129]
	v_mfma_f32_16x16x32_bf16 v[122:125], v[142:145], v[182:185], v[122:125]
	v_mfma_f32_16x16x32_bf16 v[118:121], v[134:137], v[190:193], v[118:121]
	v_mfma_f32_16x16x32_bf16 v[114:117], v[142:145], v[190:193], v[114:117]
	v_mfma_f32_16x16x32_bf16 v[102:105], v[134:137], v[198:201], v[102:105]
	v_mfma_f32_16x16x32_bf16 v[90:93], v[142:145], v[198:201], v[90:93]
	v_mfma_f32_16x16x32_bf16 v[82:85], v[134:137], v[206:209], v[82:85]
	v_mfma_f32_16x16x32_bf16 v[74:77], v[142:145], v[206:209], v[74:77]
	v_mfma_f32_16x16x32_bf16 v[110:113], v[156:159], v[178:181], v[110:113]
	v_mfma_f32_16x16x32_bf16 v[106:109], v[170:173], v[178:181], v[106:109]
	v_mfma_f32_16x16x32_bf16 v[98:101], v[156:159], v[186:189], v[98:101]
	v_mfma_f32_16x16x32_bf16 v[94:97], v[170:173], v[186:189], v[94:97]
	v_mfma_f32_16x16x32_bf16 v[86:89], v[156:159], v[194:197], v[86:89]
	v_mfma_f32_16x16x32_bf16 v[78:81], v[170:173], v[194:197], v[78:81]
	v_mfma_f32_16x16x32_bf16 v[70:73], v[156:159], v[202:205], v[70:73]
	v_mfma_f32_16x16x32_bf16 v[66:69], v[170:173], v[202:205], v[66:69]
	v_mfma_f32_16x16x32_bf16 v[110:113], v[166:169], v[182:185], v[110:113]
	v_mfma_f32_16x16x32_bf16 v[106:109], v[174:177], v[182:185], v[106:109]
	v_mfma_f32_16x16x32_bf16 v[98:101], v[166:169], v[190:193], v[98:101]
	v_mfma_f32_16x16x32_bf16 v[94:97], v[174:177], v[190:193], v[94:97]
	v_mfma_f32_16x16x32_bf16 v[86:89], v[166:169], v[198:201], v[86:89]
	v_mfma_f32_16x16x32_bf16 v[78:81], v[174:177], v[198:201], v[78:81]
	v_mfma_f32_16x16x32_bf16 v[70:73], v[166:169], v[206:209], v[70:73]
	v_mfma_f32_16x16x32_bf16 v[66:69], v[174:177], v[206:209], v[66:69]
	s_barrier
; #define PG8_STAGE(bufoff, gbase, voff) do { _Pragma("unroll") for (int _i = 0; _i < 2; ++_i) \
;         __builtin_amdgcn_global_load_lds((const unsigned*)((const char*)(gbase) + (voff)[_i]), (PG8_LAS unsigned*)(lds + (bufoff) + ldsw + _i * 8192), 16, 0, 0); } while (0)
; #define PG8_LDA(dst, b, h) do { _Pragma("unroll") for (int m = 0; m < 4; ++m) _Pragma("unroll") for (int k = 0; k < 2; ++k) dst[m][k] = *(const PG8_LAS bf16x8*)(lds + PG8_SA(b, h) + aoff + m * 2048 + k * 1024); } while (0)
; #define PG8_MMA(ai, bj, At, Bt) do { __builtin_amdgcn_s_setprio(1); _Pragma("unroll") for (int m = 0; m < 4; ++m) _Pragma("unroll") for (int n = 0; n < 2; ++n) _Pragma("unroll") for (int k = 0; k < 2; ++k) \
;         acc[ai][bj][m][n] = __builtin_amdgcn_mfma_f32_16x16x32_bf16(Bt[n][k], At[m][k], acc[ai][bj][m][n], 0, 0, 0); __builtin_amdgcn_s_setprio(0); } while (0)
; #define PG8_WAIT_V(n) asm volatile("s_waitcnt vmcnt(" #n ")" ::: "memory")
; #define PG8_WAIT_L(n) asm volatile("s_waitcnt lgkmcnt(" #n ")" ::: "memory")
; #define PG8_BAR __builtin_amdgcn_s_barrier()
; #define PG8_SCHED __builtin_amdgcn_sched_barrier(0)
; template <class Epi, class Sched, bool ALIGN_EPI = false, bool SP2 = false>
; __device__ __forceinline__ void gemm_phase(PG8_LAS unsigned char* lds, const Gemm g, const Sched& S, const Epi& E) {
;     ...
;         for (int t = 0; t < nt; t += 2) {
;     ...
;             PG8_LDA(At, 1, 1); PG8_STAGE(PG8_SB(1, 0), b3, voffB); PG8_STAGE(PG8_SB(1, 1), b3 + hstepB, voffB); PG8_STAGE(PG8_SA(1, 0), a3, voffA);
;             PG8_WAIT_V(8); PG8_WAIT_L(0); PG8_BAR; PG8_MMA(1, 0, At, B0); PG8_MMA(1, 1, At, B1); PG8_BAR; PG8_SCHED;
	s_add_i32 s20, s69, s40
	v_lshl_add_u64 v[210:211], v[210:211], 0, s[8:9]
	s_mov_b32 m0, s20
	ds_read_b128 v[178:181], v164 offset:49152
	ds_read_b128 v[182:185], v164 offset:50176
	ds_read_b128 v[186:189], v164 offset:51200
	ds_read_b128 v[190:193], v164 offset:52224
	ds_read_b128 v[194:197], v164 offset:53248
	ds_read_b128 v[198:201], v164 offset:54272
	ds_read_b128 v[202:205], v164 offset:55296
	ds_read_b128 v[206:209], v164 offset:56320
	global_load_lds_dwordx4 v[210:211], off
	s_add_i32 m0, s20, 0x2000
	s_add_u32 s20, s24, 0xb0080
	v_lshl_add_u64 v[210:211], v[212:213], 0, s[8:9]
	s_addc_u32 s21, s25, 0
	s_add_i32 s24, s70, s40
	global_load_lds_dwordx4 v[210:211], off
	v_lshl_add_u64 v[210:211], s[20:21], 0, v[148:149]
	s_mov_b32 m0, s24
	s_nop 0
	global_load_lds_dwordx4 v[210:211], off
	v_lshl_add_u64 v[210:211], s[20:21], 0, v[146:147]
	s_add_i32 m0, s24, 0x2000
	s_nop 0
	global_load_lds_dwordx4 v[210:211], off
	v_lshl_add_u64 v[210:211], v[214:215], 0, s[8:9]
	s_mov_b32 m0, s51
	s_nop 0
	global_load_lds_dwordx4 v[210:211], off
	v_lshl_add_u64 v[210:211], v[216:217], 0, s[8:9]
	s_mov_b32 m0, s52
	s_nop 0
	global_load_lds_dwordx4 v[210:211], off
	s_waitcnt vmcnt(8)
	s_waitcnt lgkmcnt(0)
	s_barrier
	v_mfma_f32_16x16x32_bf16 v[62:65], v[130:133], v[178:181], v[62:65]
	v_mfma_f32_16x16x32_bf16 v[58:61], v[138:141], v[178:181], v[58:61]
	v_mfma_f32_16x16x32_bf16 v[54:57], v[130:133], v[186:189], v[54:57]
	v_mfma_f32_16x16x32_bf16 v[50:53], v[138:141], v[186:189], v[50:53]
	v_mfma_f32_16x16x32_bf16 v[46:49], v[130:133], v[194:197], v[46:49]
	v_mfma_f32_16x16x32_bf16 v[38:41], v[138:141], v[194:197], v[38:41]
	v_mfma_f32_16x16x32_bf16 v[18:21], v[130:133], v[202:205], v[18:21]
	v_mfma_f32_16x16x32_bf16 v[10:13], v[138:141], v[202:205], v[10:13]
	v_mfma_f32_16x16x32_bf16 v[62:65], v[134:137], v[182:185], v[62:65]
	v_mfma_f32_16x16x32_bf16 v[58:61], v[142:145], v[182:185], v[58:61]
	v_mfma_f32_16x16x32_bf16 v[54:57], v[134:137], v[190:193], v[54:57]
	v_mfma_f32_16x16x32_bf16 v[50:53], v[142:145], v[190:193], v[50:53]
	v_mfma_f32_16x16x32_bf16 v[46:49], v[134:137], v[198:201], v[46:49]
	v_mfma_f32_16x16x32_bf16 v[38:41], v[142:145], v[198:201], v[38:41]
	v_mfma_f32_16x16x32_bf16 v[18:21], v[134:137], v[206:209], v[18:21]
	v_mfma_f32_16x16x32_bf16 v[10:13], v[142:145], v[206:209], v[10:13]
	v_mfma_f32_16x16x32_bf16 v[42:45], v[156:159], v[178:181], v[42:45]
	v_mfma_f32_16x16x32_bf16 v[34:37], v[170:173], v[178:181], v[34:37]
	v_mfma_f32_16x16x32_bf16 v[30:33], v[156:159], v[186:189], v[30:33]
	v_mfma_f32_16x16x32_bf16 v[26:29], v[170:173], v[186:189], v[26:29]
	v_mfma_f32_16x16x32_bf16 v[22:25], v[156:159], v[194:197], v[22:25]
	v_mfma_f32_16x16x32_bf16 v[14:17], v[170:173], v[194:197], v[14:17]
	v_mfma_f32_16x16x32_bf16 v[6:9], v[156:159], v[202:205], v[6:9]
	v_mfma_f32_16x16x32_bf16 v[2:5], v[170:173], v[202:205], v[2:5]
	v_mfma_f32_16x16x32_bf16 v[42:45], v[166:169], v[182:185], v[42:45]
	v_mfma_f32_16x16x32_bf16 v[34:37], v[174:177], v[182:185], v[34:37]
	v_mfma_f32_16x16x32_bf16 v[30:33], v[166:169], v[190:193], v[30:33]
	v_mfma_f32_16x16x32_bf16 v[26:29], v[174:177], v[190:193], v[26:29]
	v_mfma_f32_16x16x32_bf16 v[22:25], v[166:169], v[198:201], v[22:25]
	v_mfma_f32_16x16x32_bf16 v[14:17], v[174:177], v[198:201], v[14:17]
	v_mfma_f32_16x16x32_bf16 v[6:9], v[166:169], v[206:209], v[6:9]
	v_mfma_f32_16x16x32_bf16 v[2:5], v[174:177], v[206:209], v[2:5]
	s_barrier
	s_add_i32 s68, s68, 2
	s_add_u32 s66, s66, 0x100
	s_addc_u32 s67, s67, 0
	s_cmp_lt_u32 s68, 6
	s_mov_b64 s[20:21], s[22:23]
	s_cbranch_scc1 .LBB0_1945
	s_andn2_b64 vcc, exec, s[10:11]
	s_cbranch_vccnz .LBB0_1948
	s_barrier

; #define PG8_STAGE(bufoff, gbase, voff) do { _Pragma("unroll") for (int _i = 0; _i < 2; ++_i) \
;         __builtin_amdgcn_global_load_lds((const unsigned*)((const char*)(gbase) + (voff)[_i]), (PG8_LAS unsigned*)(lds + (bufoff) + ldsw + _i * 8192), 16, 0, 0); } while (0)
; #define PG8_LDA(dst, b, h) do { _Pragma("unroll") for (int m = 0; m < 4; ++m) _Pragma("unroll") for (int k = 0; k < 2; ++k) dst[m][k] = *(const PG8_LAS bf16x8*)(lds + PG8_SA(b, h) + aoff + m * 2048 + k * 1024); } while (0)
; #define PG8_LDB(dst, b, h) do { _Pragma("unroll") for (int n = 0; n < 2; ++n) _Pragma("unroll") for (int k = 0; k < 2; ++k) dst[n][k] = *(const PG8_LAS bf16x8*)(lds + PG8_SB(b, h) + boff + n * 2048 + k * 1024); } while (0)
; #define PG8_MMA(ai, bj, At, Bt) do { __builtin_amdgcn_s_setprio(1); _Pragma("unroll") for (int m = 0; m < 4; ++m) _Pragma("unroll") for (int n = 0; n < 2; ++n) _Pragma("unroll") for (int k = 0; k < 2; ++k) \
;         acc[ai][bj][m][n] = __builtin_amdgcn_mfma_f32_16x16x32_bf16(Bt[n][k], At[m][k], acc[ai][bj][m][n], 0, 0, 0); __builtin_amdgcn_s_setprio(0); } while (0)
; #define PG8_WAIT_V(n) asm volatile("s_waitcnt vmcnt(" #n ")" ::: "memory")
; #define PG8_WAIT_L(n) asm volatile("s_waitcnt lgkmcnt(" #n ")" ::: "memory")
; template <class Epi, class Sched, bool ALIGN_EPI = false, bool SP2 = false>
; __device__ __forceinline__ void gemm_phase(PG8_LAS unsigned char* lds, const Gemm g, const Sched& S, const Epi& E) {
;     ...
;             const bool last = (t == nt - 2);
;             const char* a1 = cA + (size_t)(t + 1) * kstep;
;             const char* a2 = last ? nA : cA + (size_t)(t + 2) * kstep; const char* b2 = last ? nB : cB + (size_t)(t + 2) * kstep;
;             const char* a3 = a2 + kstep; const char* b3 = b2 + kstep;
;             if (last && has_next) S.a_ready(nxt);
;             if constexpr (SP2) {
;             PG8_LDB(B0, 0, 0); PG8_LDB(B1, 0, 1); PG8_SCHED; PG8_LDA(At, 0, 0); PG8_STAGE(PG8_SA(1, 1), a1 + hstepA, voffA);
;             PG8_WAIT_V(8); PG8_WAIT_L(0); PG8_BAR; PG8_MMA(0, 0, At, B0); PG8_MMA(0, 1, At, B1); PG8_BAR; PG8_SCHED;
;             PG8_LDA(At, 0, 1); PG8_STAGE(PG8_SB(0, 0), b2, voffB); PG8_STAGE(PG8_SB(0, 1), b2 + hstepB, voffB); PG8_STAGE(PG8_SA(0, 0), a2, voffA);
;             PG8_WAIT_V(8); PG8_WAIT_L(0); PG8_BAR; PG8_MMA(1, 0, At, B0); PG8_MMA(1, 1, At, B1); PG8_BAR; PG8_SCHED;
.LBB0_2017:
	s_add_u32 s66, s22, s65
	ds_read_b128 v[130:133], v158
	ds_read_b128 v[134:137], v158 offset:1024
	ds_read_b128 v[138:141], v158 offset:2048
	ds_read_b128 v[142:145], v158 offset:3072
	ds_read_b128 v[152:155], v159
	ds_read_b128 v[162:165], v159 offset:1024
	ds_read_b128 v[166:169], v159 offset:2048
	ds_read_b128 v[170:173], v159 offset:3072
	s_addc_u32 s67, s23, 0
	s_add_u32 s68, s66, 0x100
	s_addc_u32 s69, s67, 0
	s_and_b64 s[28:29], s[26:27], exec
	s_cselect_b32 s29, s19, s69
	s_cselect_b32 s28, s18, s68
	s_add_u32 s65, s20, s65
	s_addc_u32 s68, s21, 0
	s_add_u32 s65, s65, 0x100
	s_addc_u32 s68, s68, 0
	s_and_b64 s[26:27], s[26:27], exec
	s_cselect_b32 s27, s1, s68
	s_cselect_b32 s26, s0, s65
	s_add_u32 s66, s66, 0xb0080
	s_addc_u32 s67, s67, 0
	v_lshl_add_u64 v[206:207], s[66:67], 0, v[148:149]
	s_add_i32 m0, s41, 0xc000
	ds_read_b128 v[174:177], v160
	ds_read_b128 v[178:181], v160 offset:1024
	ds_read_b128 v[182:185], v160 offset:2048
	ds_read_b128 v[186:189], v160 offset:3072
	ds_read_b128 v[190:193], v160 offset:4096
	ds_read_b128 v[194:197], v160 offset:5120
	ds_read_b128 v[198:201], v160 offset:6144
	ds_read_b128 v[202:205], v160 offset:7168
	global_load_lds_dwordx4 v[206:207], off
	v_lshl_add_u64 v[206:207], s[66:67], 0, v[146:147]
	s_add_i32 m0, s41, 0xe000
	s_nop 0
	global_load_lds_dwordx4 v[206:207], off
	s_waitcnt vmcnt(8)
	s_waitcnt lgkmcnt(0)
	s_barrier
	v_mfma_f32_16x16x32_bf16 v[126:129], v[130:133], v[174:177], v[126:129]
	v_mfma_f32_16x16x32_bf16 v[122:125], v[138:141], v[174:177], v[122:125]
	v_mfma_f32_16x16x32_bf16 v[118:121], v[130:133], v[182:185], v[118:121]
	v_mfma_f32_16x16x32_bf16 v[114:117], v[138:141], v[182:185], v[114:117]
	v_mfma_f32_16x16x32_bf16 v[102:105], v[130:133], v[190:193], v[102:105]
	v_mfma_f32_16x16x32_bf16 v[90:93], v[138:141], v[190:193], v[90:93]
	v_mfma_f32_16x16x32_bf16 v[82:85], v[130:133], v[198:201], v[82:85]
	v_mfma_f32_16x16x32_bf16 v[74:77], v[138:141], v[198:201], v[74:77]
	v_mfma_f32_16x16x32_bf16 v[126:129], v[134:137], v[178:181], v[126:129]
	v_mfma_f32_16x16x32_bf16 v[122:125], v[142:145], v[178:181], v[122:125]
	v_mfma_f32_16x16x32_bf16 v[118:121], v[134:137], v[186:189], v[118:121]
	v_mfma_f32_16x16x32_bf16 v[114:117], v[142:145], v[186:189], v[114:117]
	v_mfma_f32_16x16x32_bf16 v[102:105], v[134:137], v[194:197], v[102:105]
	v_mfma_f32_16x16x32_bf16 v[90:93], v[142:145], v[194:197], v[90:93]
	v_mfma_f32_16x16x32_bf16 v[82:85], v[134:137], v[202:205], v[82:85]
	v_mfma_f32_16x16x32_bf16 v[74:77], v[142:145], v[202:205], v[74:77]
	v_mfma_f32_16x16x32_bf16 v[110:113], v[152:155], v[174:177], v[110:113]
	v_mfma_f32_16x16x32_bf16 v[106:109], v[166:169], v[174:177], v[106:109]
	v_mfma_f32_16x16x32_bf16 v[98:101], v[152:155], v[182:185], v[98:101]
	v_mfma_f32_16x16x32_bf16 v[94:97], v[166:169], v[182:185], v[94:97]
	v_mfma_f32_16x16x32_bf16 v[86:89], v[152:155], v[190:193], v[86:89]
	v_mfma_f32_16x16x32_bf16 v[78:81], v[166:169], v[190:193], v[78:81]
	v_mfma_f32_16x16x32_bf16 v[70:73], v[152:155], v[198:201], v[70:73]
	v_mfma_f32_16x16x32_bf16 v[66:69], v[166:169], v[198:201], v[66:69]
	v_mfma_f32_16x16x32_bf16 v[110:113], v[162:165], v[178:181], v[110:113]
	v_mfma_f32_16x16x32_bf16 v[106:109], v[170:173], v[178:181], v[106:109]
	v_mfma_f32_16x16x32_bf16 v[98:101], v[162:165], v[186:189], v[98:101]
	v_mfma_f32_16x16x32_bf16 v[94:97], v[170:173], v[186:189], v[94:97]
	v_mfma_f32_16x16x32_bf16 v[86:89], v[162:165], v[194:197], v[86:89]
	v_mfma_f32_16x16x32_bf16 v[78:81], v[170:173], v[194:197], v[78:81]
	v_mfma_f32_16x16x32_bf16 v[70:73], v[162:165], v[202:205], v[70:73]
	v_mfma_f32_16x16x32_bf16 v[66:69], v[170:173], v[202:205], v[66:69]
	s_barrier
	s_add_i32 s65, s53, s39
	v_lshl_add_u64 v[206:207], s[26:27], 0, v[148:149]
	s_mov_b32 m0, s65
	ds_read_b128 v[174:177], v160 offset:16384
	ds_read_b128 v[178:181], v160 offset:17408
	ds_read_b128 v[182:185], v160 offset:18432
	ds_read_b128 v[186:189], v160 offset:19456
	ds_read_b128 v[190:193], v160 offset:20480
	ds_read_b128 v[194:197], v160 offset:21504
	ds_read_b128 v[198:201], v160 offset:22528
	ds_read_b128 v[202:205], v160 offset:23552
	global_load_lds_dwordx4 v[206:207], off
	s_add_i32 m0, s65, 0x2000
	s_add_u32 s66, s26, 0xb0000
	v_lshl_add_u64 v[208:209], s[26:27], 0, v[146:147]
	s_addc_u32 s67, s27, 0
	s_add_i32 s65, s54, s39
	global_load_lds_dwordx4 v[208:209], off
	v_lshl_add_u64 v[210:211], s[66:67], 0, v[148:149]
	s_mov_b32 m0, s65
	v_lshl_add_u64 v[212:213], s[28:29], 0, v[146:147]
	global_load_lds_dwordx4 v[210:211], off
	v_lshl_add_u64 v[210:211], s[66:67], 0, v[146:147]
	s_add_i32 m0, s65, 0x2000
	s_nop 0
	global_load_lds_dwordx4 v[210:211], off
	v_lshl_add_u64 v[210:211], s[28:29], 0, v[148:149]
	s_mov_b32 m0, s41
	s_nop 0
	global_load_lds_dwordx4 v[210:211], off
	s_mov_b32 m0, s42
	s_nop 0
	global_load_lds_dwordx4 v[212:213], off
	s_waitcnt vmcnt(8)
	s_waitcnt lgkmcnt(0)
	s_barrier
; #define PG8_STAGE(bufoff, gbase, voff) do { _Pragma("unroll") for (int _i = 0; _i < 2; ++_i) \
;         __builtin_amdgcn_global_load_lds((const unsigned*)((const char*)(gbase) + (voff)[_i]), (PG8_LAS unsigned*)(lds + (bufoff) + ldsw + _i * 8192), 16, 0, 0); } while (0)
; #define PG8_LDA(dst, b, h) do { _Pragma("unroll") for (int m = 0; m < 4; ++m) _Pragma("unroll") for (int k = 0; k < 2; ++k) dst[m][k] = *(const PG8_LAS bf16x8*)(lds + PG8_SA(b, h) + aoff + m * 2048 + k * 1024); } while (0)
; #define PG8_LDB(dst, b, h) do { _Pragma("unroll") for (int n = 0; n < 2; ++n) _Pragma("unroll") for (int k = 0; k < 2; ++k) dst[n][k] = *(const PG8_LAS bf16x8*)(lds + PG8_SB(b, h) + boff + n * 2048 + k * 1024); } while (0)
; #define PG8_MMA(ai, bj, At, Bt) do { __builtin_amdgcn_s_setprio(1); _Pragma("unroll") for (int m = 0; m < 4; ++m) _Pragma("unroll") for (int n = 0; n < 2; ++n) _Pragma("unroll") for (int k = 0; k < 2; ++k) \
;         acc[ai][bj][m][n] = __builtin_amdgcn_mfma_f32_16x16x32_bf16(Bt[n][k], At[m][k], acc[ai][bj][m][n], 0, 0, 0); __builtin_amdgcn_s_setprio(0); } while (0)
; #define PG8_WAIT_V(n) asm volatile("s_waitcnt vmcnt(" #n ")" ::: "memory")
; #define PG8_WAIT_L(n) asm volatile("s_waitcnt lgkmcnt(" #n ")" ::: "memory")
; #define PG8_BAR __builtin_amdgcn_s_barrier()
; #define PG8_SCHED __builtin_amdgcn_sched_barrier(0)
; template <class Epi, class Sched, bool ALIGN_EPI = false, bool SP2 = false>
; __device__ __forceinline__ void gemm_phase(PG8_LAS unsigned char* lds, const Gemm g, const Sched& S, const Epi& E) {
;     ...
;             PG8_WAIT_V(8); PG8_WAIT_L(0); PG8_BAR; PG8_MMA(1, 0, At, B0); PG8_MMA(1, 1, At, B1); PG8_BAR; PG8_SCHED;
;             PG8_LDB(B0, 1, 0); PG8_LDB(B1, 1, 1); PG8_SCHED; PG8_LDA(At, 1, 0); PG8_STAGE(PG8_SA(0, 1), a2 + hstepA, voffA);
;             PG8_WAIT_V(8); PG8_WAIT_L(0); PG8_BAR; PG8_MMA(0, 0, At, B0); PG8_MMA(0, 1, At, B1); PG8_BAR; PG8_SCHED;
	v_mfma_f32_16x16x32_bf16 v[62:65], v[130:133], v[174:177], v[62:65]
	v_mfma_f32_16x16x32_bf16 v[58:61], v[138:141], v[174:177], v[58:61]
	v_mfma_f32_16x16x32_bf16 v[54:57], v[130:133], v[182:185], v[54:57]
	v_mfma_f32_16x16x32_bf16 v[50:53], v[138:141], v[182:185], v[50:53]
	v_mfma_f32_16x16x32_bf16 v[46:49], v[130:133], v[190:193], v[46:49]
	v_mfma_f32_16x16x32_bf16 v[38:41], v[138:141], v[190:193], v[38:41]
	v_mfma_f32_16x16x32_bf16 v[18:21], v[130:133], v[198:201], v[18:21]
	v_mfma_f32_16x16x32_bf16 v[10:13], v[138:141], v[198:201], v[10:13]
	v_mfma_f32_16x16x32_bf16 v[62:65], v[134:137], v[178:181], v[62:65]
	v_mfma_f32_16x16x32_bf16 v[58:61], v[142:145], v[178:181], v[58:61]
	v_mfma_f32_16x16x32_bf16 v[54:57], v[134:137], v[186:189], v[54:57]
	v_mfma_f32_16x16x32_bf16 v[50:53], v[142:145], v[186:189], v[50:53]
	v_mfma_f32_16x16x32_bf16 v[46:49], v[134:137], v[194:197], v[46:49]
	v_mfma_f32_16x16x32_bf16 v[38:41], v[142:145], v[194:197], v[38:41]
	v_mfma_f32_16x16x32_bf16 v[18:21], v[134:137], v[202:205], v[18:21]
	v_mfma_f32_16x16x32_bf16 v[10:13], v[142:145], v[202:205], v[10:13]
	v_mfma_f32_16x16x32_bf16 v[42:45], v[152:155], v[174:177], v[42:45]
	v_mfma_f32_16x16x32_bf16 v[34:37], v[166:169], v[174:177], v[34:37]
	v_mfma_f32_16x16x32_bf16 v[30:33], v[152:155], v[182:185], v[30:33]
	v_mfma_f32_16x16x32_bf16 v[26:29], v[166:169], v[182:185], v[26:29]
	v_mfma_f32_16x16x32_bf16 v[22:25], v[152:155], v[190:193], v[22:25]
	v_mfma_f32_16x16x32_bf16 v[14:17], v[166:169], v[190:193], v[14:17]
	v_mfma_f32_16x16x32_bf16 v[6:9], v[152:155], v[198:201], v[6:9]
	v_mfma_f32_16x16x32_bf16 v[2:5], v[166:169], v[198:201], v[2:5]
	v_mfma_f32_16x16x32_bf16 v[42:45], v[162:165], v[178:181], v[42:45]
	v_mfma_f32_16x16x32_bf16 v[34:37], v[170:173], v[178:181], v[34:37]
	v_mfma_f32_16x16x32_bf16 v[30:33], v[162:165], v[186:189], v[30:33]
	v_mfma_f32_16x16x32_bf16 v[26:29], v[170:173], v[186:189], v[26:29]
	v_mfma_f32_16x16x32_bf16 v[22:25], v[162:165], v[194:197], v[22:25]
	v_mfma_f32_16x16x32_bf16 v[14:17], v[170:173], v[194:197], v[14:17]
	v_mfma_f32_16x16x32_bf16 v[6:9], v[162:165], v[202:205], v[6:9]
	v_mfma_f32_16x16x32_bf16 v[2:5], v[170:173], v[202:205], v[2:5]
	s_barrier
	s_add_i32 s65, 0, 0x18000
	s_add_i32 s66, 0, 0x1c000
	v_add_u32_e32 v142, s65, v1
	v_add_u32_e32 v170, s66, v1
	ds_read_b128 v[130:133], v142
	ds_read_b128 v[134:137], v142 offset:1024
	ds_read_b128 v[138:141], v142 offset:2048
	ds_read_b128 v[142:145], v142 offset:3072
	ds_read_b128 v[152:155], v170
	ds_read_b128 v[162:165], v170 offset:1024
	ds_read_b128 v[166:169], v170 offset:2048
	ds_read_b128 v[170:173], v170 offset:3072
	s_add_u32 s28, s28, 0xb0000
	s_addc_u32 s29, s29, 0
	s_mov_b32 m0, s43
	v_lshl_add_u64 v[214:215], s[28:29], 0, v[148:149]
	ds_read_b128 v[174:177], v160 offset:32768
	ds_read_b128 v[178:181], v160 offset:33792
	ds_read_b128 v[182:185], v160 offset:34816
	ds_read_b128 v[186:189], v160 offset:35840
	ds_read_b128 v[190:193], v160 offset:36864
	ds_read_b128 v[194:197], v160 offset:37888
	ds_read_b128 v[198:201], v160 offset:38912
	ds_read_b128 v[202:205], v160 offset:39936
	global_load_lds_dwordx4 v[214:215], off
	v_lshl_add_u64 v[214:215], s[28:29], 0, v[146:147]
	s_mov_b32 m0, s44
	s_nop 0
	global_load_lds_dwordx4 v[214:215], off
	s_waitcnt vmcnt(8)
	s_waitcnt lgkmcnt(0)
	s_barrier
	v_mfma_f32_16x16x32_bf16 v[126:129], v[130:133], v[174:177], v[126:129]
	v_mfma_f32_16x16x32_bf16 v[122:125], v[138:141], v[174:177], v[122:125]
	v_mfma_f32_16x16x32_bf16 v[118:121], v[130:133], v[182:185], v[118:121]
	v_mfma_f32_16x16x32_bf16 v[114:117], v[138:141], v[182:185], v[114:117]
	v_mfma_f32_16x16x32_bf16 v[102:105], v[130:133], v[190:193], v[102:105]
	v_mfma_f32_16x16x32_bf16 v[90:93], v[138:141], v[190:193], v[90:93]
	v_mfma_f32_16x16x32_bf16 v[82:85], v[130:133], v[198:201], v[82:85]
	v_mfma_f32_16x16x32_bf16 v[74:77], v[138:141], v[198:201], v[74:77]
	v_mfma_f32_16x16x32_bf16 v[126:129], v[134:137], v[178:181], v[126:129]
	v_mfma_f32_16x16x32_bf16 v[122:125], v[142:145], v[178:181], v[122:125]
	v_mfma_f32_16x16x32_bf16 v[118:121], v[134:137], v[186:189], v[118:121]
	v_mfma_f32_16x16x32_bf16 v[114:117], v[142:145], v[186:189], v[114:117]
	v_mfma_f32_16x16x32_bf16 v[102:105], v[134:137], v[194:197], v[102:105]
	v_mfma_f32_16x16x32_bf16 v[90:93], v[142:145], v[194:197], v[90:93]
	v_mfma_f32_16x16x32_bf16 v[82:85], v[134:137], v[202:205], v[82:85]
	v_mfma_f32_16x16x32_bf16 v[74:77], v[142:145], v[202:205], v[74:77]
	v_mfma_f32_16x16x32_bf16 v[110:113], v[152:155], v[174:177], v[110:113]
	v_mfma_f32_16x16x32_bf16 v[106:109], v[166:169], v[174:177], v[106:109]
	v_mfma_f32_16x16x32_bf16 v[98:101], v[152:155], v[182:185], v[98:101]
	v_mfma_f32_16x16x32_bf16 v[94:97], v[166:169], v[182:185], v[94:97]
	v_mfma_f32_16x16x32_bf16 v[86:89], v[152:155], v[190:193], v[86:89]
	v_mfma_f32_16x16x32_bf16 v[78:81], v[166:169], v[190:193], v[78:81]
	v_mfma_f32_16x16x32_bf16 v[70:73], v[152:155], v[198:201], v[70:73]
	v_mfma_f32_16x16x32_bf16 v[66:69], v[166:169], v[198:201], v[66:69]
	v_mfma_f32_16x16x32_bf16 v[110:113], v[162:165], v[178:181], v[110:113]
	v_mfma_f32_16x16x32_bf16 v[106:109], v[170:173], v[178:181], v[106:109]
	v_mfma_f32_16x16x32_bf16 v[98:101], v[162:165], v[186:189], v[98:101]
	v_mfma_f32_16x16x32_bf16 v[94:97], v[170:173], v[186:189], v[94:97]
	v_mfma_f32_16x16x32_bf16 v[86:89], v[162:165], v[194:197], v[86:89]
	v_mfma_f32_16x16x32_bf16 v[78:81], v[170:173], v[194:197], v[78:81]
	v_mfma_f32_16x16x32_bf16 v[70:73], v[162:165], v[202:205], v[70:73]
	v_mfma_f32_16x16x32_bf16 v[66:69], v[170:173], v[202:205], v[66:69]
	s_barrier
; #define PG8_STAGE(bufoff, gbase, voff) do { _Pragma("unroll") for (int _i = 0; _i < 2; ++_i) \
;         __builtin_amdgcn_global_load_lds((const unsigned*)((const char*)(gbase) + (voff)[_i]), (PG8_LAS unsigned*)(lds + (bufoff) + ldsw + _i * 8192), 16, 0, 0); } while (0)
; #define PG8_LDA(dst, b, h) do { _Pragma("unroll") for (int m = 0; m < 4; ++m) _Pragma("unroll") for (int k = 0; k < 2; ++k) dst[m][k] = *(const PG8_LAS bf16x8*)(lds + PG8_SA(b, h) + aoff + m * 2048 + k * 1024); } while (0)
; #define PG8_MMA(ai, bj, At, Bt) do { __builtin_amdgcn_s_setprio(1); _Pragma("unroll") for (int m = 0; m < 4; ++m) _Pragma("unroll") for (int n = 0; n < 2; ++n) _Pragma("unroll") for (int k = 0; k < 2; ++k) \
;         acc[ai][bj][m][n] = __builtin_amdgcn_mfma_f32_16x16x32_bf16(Bt[n][k], At[m][k], acc[ai][bj][m][n], 0, 0, 0); __builtin_amdgcn_s_setprio(0); } while (0)
; #define PG8_WAIT_V(n) asm volatile("s_waitcnt vmcnt(" #n ")" ::: "memory")
; #define PG8_WAIT_L(n) asm volatile("s_waitcnt lgkmcnt(" #n ")" ::: "memory")
; #define PG8_BAR __builtin_amdgcn_s_barrier()
; #define PG8_SCHED __builtin_amdgcn_sched_barrier(0)
; template <class Epi, class Sched, bool ALIGN_EPI = false, bool SP2 = false>
; __device__ __forceinline__ void gemm_phase(PG8_LAS unsigned char* lds, const Gemm g, const Sched& S, const Epi& E) {
;     ...
;         for (int t = 0; t < nt; t += 2) {
;     ...
;             PG8_LDA(At, 1, 1); PG8_STAGE(PG8_SB(1, 0), b3, voffB); PG8_STAGE(PG8_SB(1, 1), b3 + hstepB, voffB); PG8_STAGE(PG8_SA(1, 0), a3, voffA);
;             PG8_WAIT_V(8); PG8_WAIT_L(0); PG8_BAR; PG8_MMA(1, 0, At, B0); PG8_MMA(1, 1, At, B1); PG8_BAR; PG8_SCHED;
	s_add_i32 s28, s65, s39
	v_lshl_add_u64 v[206:207], v[206:207], 0, s[8:9]
	s_mov_b32 m0, s28
	ds_read_b128 v[174:177], v160 offset:49152
	ds_read_b128 v[178:181], v160 offset:50176
	ds_read_b128 v[182:185], v160 offset:51200
	ds_read_b128 v[186:189], v160 offset:52224
	ds_read_b128 v[190:193], v160 offset:53248
	ds_read_b128 v[194:197], v160 offset:54272
	ds_read_b128 v[198:201], v160 offset:55296
	ds_read_b128 v[202:205], v160 offset:56320
	global_load_lds_dwordx4 v[206:207], off
	s_add_i32 m0, s28, 0x2000
	s_add_u32 s26, s26, 0xb0080
	v_lshl_add_u64 v[206:207], v[208:209], 0, s[8:9]
	s_addc_u32 s27, s27, 0
	s_add_i32 s28, s66, s39
	global_load_lds_dwordx4 v[206:207], off
	v_lshl_add_u64 v[206:207], s[26:27], 0, v[148:149]
	s_mov_b32 m0, s28
	s_nop 0
	global_load_lds_dwordx4 v[206:207], off
	v_lshl_add_u64 v[206:207], s[26:27], 0, v[146:147]
	s_add_i32 m0, s28, 0x2000
	s_nop 0
	global_load_lds_dwordx4 v[206:207], off
	v_lshl_add_u64 v[206:207], v[210:211], 0, s[8:9]
	s_mov_b32 m0, s51
	s_nop 0
	global_load_lds_dwordx4 v[206:207], off
	v_lshl_add_u64 v[206:207], v[212:213], 0, s[8:9]
	s_mov_b32 m0, s52
	s_nop 0
	global_load_lds_dwordx4 v[206:207], off
	s_waitcnt vmcnt(8)
	s_waitcnt lgkmcnt(0)
	s_barrier
	v_mfma_f32_16x16x32_bf16 v[62:65], v[130:133], v[174:177], v[62:65]
	v_mfma_f32_16x16x32_bf16 v[58:61], v[138:141], v[174:177], v[58:61]
	v_mfma_f32_16x16x32_bf16 v[54:57], v[130:133], v[182:185], v[54:57]
	v_mfma_f32_16x16x32_bf16 v[50:53], v[138:141], v[182:185], v[50:53]
	v_mfma_f32_16x16x32_bf16 v[46:49], v[130:133], v[190:193], v[46:49]
	v_mfma_f32_16x16x32_bf16 v[38:41], v[138:141], v[190:193], v[38:41]
	v_mfma_f32_16x16x32_bf16 v[18:21], v[130:133], v[198:201], v[18:21]
	v_mfma_f32_16x16x32_bf16 v[10:13], v[138:141], v[198:201], v[10:13]
	v_mfma_f32_16x16x32_bf16 v[62:65], v[134:137], v[178:181], v[62:65]
	v_mfma_f32_16x16x32_bf16 v[58:61], v[142:145], v[178:181], v[58:61]
	v_mfma_f32_16x16x32_bf16 v[54:57], v[134:137], v[186:189], v[54:57]
	v_mfma_f32_16x16x32_bf16 v[50:53], v[142:145], v[186:189], v[50:53]
	v_mfma_f32_16x16x32_bf16 v[46:49], v[134:137], v[194:197], v[46:49]
	v_mfma_f32_16x16x32_bf16 v[38:41], v[142:145], v[194:197], v[38:41]
	v_mfma_f32_16x16x32_bf16 v[18:21], v[134:137], v[202:205], v[18:21]
	v_mfma_f32_16x16x32_bf16 v[10:13], v[142:145], v[202:205], v[10:13]
	v_mfma_f32_16x16x32_bf16 v[42:45], v[152:155], v[174:177], v[42:45]
	v_mfma_f32_16x16x32_bf16 v[34:37], v[166:169], v[174:177], v[34:37]
	v_mfma_f32_16x16x32_bf16 v[30:33], v[152:155], v[182:185], v[30:33]
	v_mfma_f32_16x16x32_bf16 v[26:29], v[166:169], v[182:185], v[26:29]
	v_mfma_f32_16x16x32_bf16 v[22:25], v[152:155], v[190:193], v[22:25]
	v_mfma_f32_16x16x32_bf16 v[14:17], v[166:169], v[190:193], v[14:17]
	v_mfma_f32_16x16x32_bf16 v[6:9], v[152:155], v[198:201], v[6:9]
	v_mfma_f32_16x16x32_bf16 v[2:5], v[166:169], v[198:201], v[2:5]
	v_mfma_f32_16x16x32_bf16 v[42:45], v[162:165], v[178:181], v[42:45]
	v_mfma_f32_16x16x32_bf16 v[34:37], v[170:173], v[178:181], v[34:37]
	v_mfma_f32_16x16x32_bf16 v[30:33], v[162:165], v[186:189], v[30:33]
	v_mfma_f32_16x16x32_bf16 v[26:29], v[170:173], v[186:189], v[26:29]
	v_mfma_f32_16x16x32_bf16 v[22:25], v[162:165], v[194:197], v[22:25]
	v_mfma_f32_16x16x32_bf16 v[14:17], v[170:173], v[194:197], v[14:17]
	v_mfma_f32_16x16x32_bf16 v[6:9], v[162:165], v[202:205], v[6:9]
	v_mfma_f32_16x16x32_bf16 v[2:5], v[170:173], v[202:205], v[2:5]
	s_barrier
	s_movk_i32 s65, 0x100
	s_and_b64 vcc, exec, s[24:25]
	s_mov_b64 s[26:27], -1
	s_mov_b64 s[24:25], 0
	s_cbranch_vccnz .LBB0_2017
	s_andn2_b64 vcc, exec, s[10:11]
	s_cbranch_vccnz .LBB0_2020
	s_barrier
